# norm phases 2,5,10,13: all 8 row loads issued up front, counted vmcnt waits
# speedup vs baseline: 1.0016x; 1.0016x over previous
.LBB0_250:
	v_lshrrev_b32_e32 v16, 8, v110
	v_mul_hi_i32_i24_e32 v17, 0x9000, v16
	v_mul_i32_i24_e32 v16, 0x9000, v16
	v_lshlrev_b32_e32 v86, 3, v110
	v_lshl_add_u64 v[16:17], s[96:97], 0, v[16:17]
	v_ashrrev_i32_e32 v87, 31, v86
	v_readlane_b32 s36, v254, 11
	v_lshl_add_u64 v[20:21], v[16:17], 0, s[30:31]
	v_lshlrev_b64 v[32:33], 12, v[86:87]
	v_readlane_b32 s37, v254, 12
	v_lshl_add_u64 v[18:19], v[20:21], 0, v[66:67]
	v_lshl_add_u64 v[22:23], v[20:21], 0, v[68:69]
	v_lshl_add_u64 v[32:33], s[36:37], 0, v[32:33]
	v_lshl_add_u64 v[28:29], v[16:17], 0, v[66:67]
	global_load_dwordx4 v[88:91], v[18:19], off
	s_nop 0
	global_load_dwordx4 v[16:19], v[28:29], off
	global_load_dwordx4 v[92:95], v[22:23], off
	v_lshl_add_u64 v[22:23], v[20:21], 0, v[70:71]
	v_lshl_add_u64 v[20:21], v[20:21], 0, v[72:73]
	v_lshl_add_u64 v[32:33], v[32:33], 0, v[82:83]
	global_load_dwordx4 v[96:99], v[22:23], off
	global_load_dwordx4 v[100:103], v[20:21], off
	s_nop 0
	global_load_dwordx4 v[20:23], v[28:29], off offset:1024
	global_load_dwordx4 v[24:27], v[28:29], off offset:2048
	s_nop 0
	global_load_dwordx4 v[28:31], v[28:29], off offset:3072
	s_nop 0
	v_ashrrev_i32_e32 v81, 31, v80
	v_readlane_b32 s48, v254, 23
	v_readlane_b32 s49, v254, 24
	v_readlane_b32 s50, v254, 25
	v_readlane_b32 s51, v254, 26
	v_lshlrev_b64 v[84:85], 12, v[80:81]
	v_lshlrev_b64 v[86:87], 11, v[86:87]
	v_lshl_add_u64 v[84:85], v[78:79], 0, v[84:85]
	v_lshl_add_u64 v[86:87], v[76:77], 0, v[86:87]
	v_readlane_b32 s38, v254, 13
	v_readlane_b32 s39, v254, 14
	v_readlane_b32 s40, v254, 15
	v_readlane_b32 s41, v254, 16
	v_readlane_b32 s42, v254, 17
	v_readlane_b32 s43, v254, 18
	v_readlane_b32 s44, v254, 19
	v_readlane_b32 s45, v254, 20
	v_readlane_b32 s46, v254, 21
	v_readlane_b32 s47, v254, 22
	global_load_dwordx4 v[60:63], v[32:33], off
	global_load_dwordx4 v[56:59], v[32:33], off offset:1024
	global_load_dwordx4 v[44:47], v[32:33], off offset:2048
	global_load_dwordx4 v[36:39], v[32:33], off offset:3072
	s_mov_b64 s[6:7], 0x1000
	v_lshl_add_u64 v[112:113], v[84:85], 0, s[6:7]
	global_load_dwordx4 v[32:35], v[112:113], off
	global_load_dwordx4 v[40:43], v[112:113], off offset:1024
	global_load_dwordx4 v[48:51], v[112:113], off offset:2048
	global_load_dwordx4 v[52:55], v[112:113], off offset:3072
	s_mov_b64 s[6:7], 0x2000
	v_lshl_add_u64 v[114:115], v[84:85], 0, s[6:7]
	global_load_dwordx4 v[176:179], v[114:115], off
	global_load_dwordx4 v[180:183], v[114:115], off offset:1024
	global_load_dwordx4 v[184:187], v[114:115], off offset:2048
	global_load_dwordx4 v[188:191], v[114:115], off offset:3072
	s_mov_b64 s[6:7], 0x3000
	v_lshl_add_u64 v[112:113], v[84:85], 0, s[6:7]
	global_load_dwordx4 v[192:195], v[112:113], off
	global_load_dwordx4 v[196:199], v[112:113], off offset:1024
	global_load_dwordx4 v[200:203], v[112:113], off offset:2048
	global_load_dwordx4 v[204:207], v[112:113], off offset:3072
	s_mov_b64 s[6:7], 0x4000
	v_lshl_add_u64 v[114:115], v[84:85], 0, s[6:7]
	global_load_dwordx4 v[208:211], v[114:115], off
	global_load_dwordx4 v[212:215], v[114:115], off offset:1024
	global_load_dwordx4 v[216:219], v[114:115], off offset:2048
	global_load_dwordx4 v[220:223], v[114:115], off offset:3072
	s_mov_b64 s[6:7], 0x5000
	v_lshl_add_u64 v[112:113], v[84:85], 0, s[6:7]
	global_load_dwordx4 v[224:227], v[112:113], off
	global_load_dwordx4 v[228:231], v[112:113], off offset:1024
	global_load_dwordx4 v[232:235], v[112:113], off offset:2048
	global_load_dwordx4 v[236:239], v[112:113], off offset:3072
	s_mov_b64 s[6:7], 0x6000
	v_lshl_add_u64 v[114:115], v[84:85], 0, s[6:7]
	global_load_dwordx4 v[240:243], v[114:115], off
	global_load_dwordx4 v[244:247], v[114:115], off offset:1024
	global_load_dwordx4 v[248:251], v[114:115], off offset:2048
	global_load_dwordx4 v[124:127], v[114:115], off offset:3072
	s_mov_b64 s[6:7], 0x7000
	v_lshl_add_u64 v[112:113], v[84:85], 0, s[6:7]
	global_load_dwordx4 v[128:131], v[112:113], off
	global_load_dwordx4 v[132:135], v[112:113], off offset:1024
	global_load_dwordx4 v[136:139], v[112:113], off offset:2048
	global_load_dwordx4 v[140:143], v[112:113], off offset:3072
	s_waitcnt vmcnt(32)
	v_pk_add_f32 v[90:91], v[90:91], 1.0 op_sel_hi:[1,0]
	v_pk_add_f32 v[112:113], v[88:89], 1.0 op_sel_hi:[1,0]
	v_pk_add_f32 v[94:95], v[94:95], 1.0 op_sel_hi:[1,0]
	v_pk_add_f32 v[114:115], v[92:93], 1.0 op_sel_hi:[1,0]
	v_pk_add_f32 v[98:99], v[98:99], 1.0 op_sel_hi:[1,0]
	v_pk_add_f32 v[116:117], v[96:97], 1.0 op_sel_hi:[1,0]
	v_pk_add_f32 v[102:103], v[102:103], 1.0 op_sel_hi:[1,0]
	v_pk_add_f32 v[118:119], v[100:101], 1.0 op_sel_hi:[1,0]
	v_pk_mul_f32 v[88:89], v[2:3], v[90:91]
	v_pk_mul_f32 v[90:91], v[0:1], v[112:113]
	v_pk_mul_f32 v[92:93], v[6:7], v[94:95]
	v_pk_mul_f32 v[94:95], v[4:5], v[114:115]
	v_pk_mul_f32 v[96:97], v[10:11], v[98:99]
	v_pk_mul_f32 v[98:99], v[8:9], v[116:117]
	v_pk_mul_f32 v[100:101], v[14:15], v[102:103]
	v_pk_mul_f32 v[102:103], v[12:13], v[118:119]
	s_waitcnt vmcnt(31)
	v_pk_mul_f32 v[116:117], v[62:63], v[62:63]
	v_pk_mul_f32 v[118:119], v[60:61], v[60:61]
	s_waitcnt vmcnt(30)
	v_pk_mul_f32 v[112:113], v[58:59], v[58:59]
	v_pk_mul_f32 v[114:115], v[56:57], v[56:57]
	v_pk_mov_b32 v[120:121], v[118:119], v[116:117] op_sel:[1,0]
	v_mov_b32_e32 v119, v117
	v_pk_add_f32 v[116:117], v[120:121], v[118:119]
	v_pk_mov_b32 v[118:119], v[114:115], v[112:113] op_sel:[1,0]
	v_mov_b32_e32 v115, v113
	v_pk_add_f32 v[112:113], v[118:119], v[114:115]
	v_pk_add_f32 v[116:117], v[116:117], v[116:117] op_sel_hi:[0,1]
	v_pk_add_f32 v[112:113], v[112:113], v[112:113] op_sel_hi:[0,1]
	s_waitcnt vmcnt(29)
	v_mul_f32_e32 v112, v44, v44
	v_pk_fma_f32 v[114:115], v[44:45], v[44:45], v[112:113] op_sel_hi:[1,1,0]
	v_mul_f32_e32 v112, v46, v46
	v_pk_fma_f32 v[118:119], v[46:47], v[46:47], v[112:113] op_sel_hi:[1,1,0]
	s_waitcnt vmcnt(28)
	v_mul_f32_e32 v114, v36, v36
	v_mul_f32_e32 v118, v37, v37
	v_mul_f32_e32 v116, v38, v38
	v_mul_f32_e32 v112, v39, v39
	v_pk_add_f32 v[114:115], v[114:115], v[118:119]
	v_pk_add_f32 v[112:113], v[116:117], v[112:113]
	v_pk_add_f32 v[112:113], v[114:115], v[112:113]
	v_add_f32_e32 v81, v112, v113
	ds_bpermute_b32 v111, v65, v81
	s_waitcnt lgkmcnt(0)
	v_add_f32_e32 v81, v81, v111
	ds_bpermute_b32 v111, v104, v81
	s_waitcnt lgkmcnt(0)
	v_add_f32_e32 v81, v81, v111
	ds_bpermute_b32 v111, v105, v81
	s_waitcnt lgkmcnt(0)
	v_add_f32_e32 v81, v81, v111
	ds_bpermute_b32 v111, v106, v81
	s_waitcnt lgkmcnt(0)
	v_add_f32_e32 v81, v81, v111
	ds_bpermute_b32 v111, v107, v81
	s_waitcnt lgkmcnt(0)
	v_add_f32_e32 v81, v81, v111
	ds_bpermute_b32 v111, v108, v81
	s_waitcnt lgkmcnt(0)
	v_add_f32_e32 v81, v81, v111
	v_fmamk_f32 v81, v81, 0x3a800000, v75
	v_mul_f32_e32 v111, 0x4f800000, v81
	v_cmp_gt_f32_e32 vcc, s8, v81
	s_nop 1
	v_cndmask_b32_e32 v81, v81, v111, vcc
	v_sqrt_f32_e32 v111, v81
	s_nop 0
	v_add_u32_e32 v112, -1, v111
	v_add_u32_e32 v113, 1, v111
	v_fma_f32 v114, -v112, v111, v81
	v_fma_f32 v115, -v113, v111, v81
	v_cmp_ge_f32_e64 s[0:1], 0, v114
	s_nop 1
	v_cndmask_b32_e64 v111, v111, v112, s[0:1]
	v_cmp_lt_f32_e64 s[0:1], 0, v115
	s_nop 1
	v_cndmask_b32_e64 v111, v111, v113, s[0:1]
	v_mul_f32_e32 v112, 0x37800000, v111
	v_cndmask_b32_e32 v111, v111, v112, vcc
	v_cmp_class_f32_e32 vcc, v81, v109
	s_mov_b64 s[6:7], 0x0
	v_lshl_add_u64 v[112:113], s[6:7], 1, v[86:87]
	s_nop 0
	v_cndmask_b32_e32 v81, v111, v81, vcc
	v_div_scale_f32 v111, s[0:1], v81, v81, 1.0
	v_rcp_f32_e32 v114, v111
	v_div_scale_f32 v115, vcc, 1.0, v81, 1.0
	v_fma_f32 v116, -v111, v114, 1.0
	v_fmac_f32_e32 v114, v116, v114
	v_mul_f32_e32 v116, v115, v114
	v_fma_f32 v117, -v111, v116, v115
	v_fmac_f32_e32 v116, v117, v114
	v_fma_f32 v111, -v111, v116, v115
	v_div_fmas_f32 v111, v111, v114, v116
	v_div_fixup_f32 v114, v111, v81, 1.0
	v_pk_mul_f32 v[60:61], v[60:61], v[114:115] op_sel_hi:[1,0]
	v_pk_mul_f32 v[56:57], v[56:57], v[114:115] op_sel_hi:[1,0]
	v_pk_mul_f32 v[44:45], v[44:45], v[114:115] op_sel_hi:[1,0]
	v_pk_mul_f32 v[36:37], v[36:37], v[114:115] op_sel_hi:[1,0]
	v_pk_mul_f32 v[62:63], v[62:63], v[114:115] op_sel_hi:[1,0]
	v_pk_fma_f32 v[60:61], v[90:91], v[60:61], v[16:17]
	v_pk_mul_f32 v[58:59], v[58:59], v[114:115] op_sel_hi:[1,0]
	v_pk_fma_f32 v[56:57], v[94:95], v[56:57], v[20:21]
	v_pk_mul_f32 v[46:47], v[46:47], v[114:115] op_sel_hi:[1,0]
	v_pk_fma_f32 v[44:45], v[98:99], v[44:45], v[24:25]
	v_pk_mul_f32 v[38:39], v[38:39], v[114:115] op_sel_hi:[1,0]
	v_pk_fma_f32 v[36:37], v[102:103], v[36:37], v[28:29]
	v_pk_fma_f32 v[62:63], v[88:89], v[62:63], v[18:19]
	v_cvt_pk_bf16_f32 v60, v60, v61
	v_pk_fma_f32 v[58:59], v[92:93], v[58:59], v[22:23]
	v_cvt_pk_bf16_f32 v61, v62, v63
	global_store_dwordx2 v[112:113], v[60:61], off
	v_cvt_pk_bf16_f32 v56, v56, v57
	v_cvt_pk_bf16_f32 v57, v58, v59
	global_store_dwordx2 v[112:113], v[56:57], off offset:512
	v_pk_fma_f32 v[46:47], v[96:97], v[46:47], v[26:27]
	v_cvt_pk_bf16_f32 v44, v44, v45
	v_pk_fma_f32 v[38:39], v[100:101], v[38:39], v[30:31]
	v_cvt_pk_bf16_f32 v45, v46, v47
	global_store_dwordx2 v[112:113], v[44:45], off offset:1024
	v_cvt_pk_bf16_f32 v36, v36, v37
	v_cvt_pk_bf16_f32 v37, v38, v39
	global_store_dwordx2 v[112:113], v[36:37], off offset:1536
	s_waitcnt vmcnt(31)
	v_pk_mul_f32 v[116:117], v[34:35], v[34:35]
	v_pk_mul_f32 v[118:119], v[32:33], v[32:33]
	s_waitcnt vmcnt(30)
	v_pk_mul_f32 v[112:113], v[42:43], v[42:43]
	v_pk_mul_f32 v[114:115], v[40:41], v[40:41]
	v_pk_mov_b32 v[120:121], v[118:119], v[116:117] op_sel:[1,0]
	v_mov_b32_e32 v119, v117
	v_pk_add_f32 v[116:117], v[120:121], v[118:119]
	v_pk_mov_b32 v[118:119], v[114:115], v[112:113] op_sel:[1,0]
	v_mov_b32_e32 v115, v113
	v_pk_add_f32 v[112:113], v[118:119], v[114:115]
	v_pk_add_f32 v[116:117], v[116:117], v[116:117] op_sel_hi:[0,1]
	v_pk_add_f32 v[112:113], v[112:113], v[112:113] op_sel_hi:[0,1]
	s_waitcnt vmcnt(29)
	v_mul_f32_e32 v112, v48, v48
	v_pk_fma_f32 v[114:115], v[48:49], v[48:49], v[112:113] op_sel_hi:[1,1,0]
	v_mul_f32_e32 v112, v50, v50
	v_pk_fma_f32 v[118:119], v[50:51], v[50:51], v[112:113] op_sel_hi:[1,1,0]
	s_waitcnt vmcnt(28)
	v_mul_f32_e32 v114, v52, v52
	v_mul_f32_e32 v118, v53, v53
	v_mul_f32_e32 v116, v54, v54
	v_mul_f32_e32 v112, v55, v55
	v_pk_add_f32 v[114:115], v[114:115], v[118:119]
	v_pk_add_f32 v[112:113], v[116:117], v[112:113]
	v_pk_add_f32 v[112:113], v[114:115], v[112:113]
	v_add_f32_e32 v81, v112, v113
	ds_bpermute_b32 v111, v65, v81
	s_waitcnt lgkmcnt(0)
	v_add_f32_e32 v81, v81, v111
	ds_bpermute_b32 v111, v104, v81
	s_waitcnt lgkmcnt(0)
	v_add_f32_e32 v81, v81, v111
	ds_bpermute_b32 v111, v105, v81
	s_waitcnt lgkmcnt(0)
	v_add_f32_e32 v81, v81, v111
	ds_bpermute_b32 v111, v106, v81
	s_waitcnt lgkmcnt(0)
	v_add_f32_e32 v81, v81, v111
	ds_bpermute_b32 v111, v107, v81
	s_waitcnt lgkmcnt(0)
	v_add_f32_e32 v81, v81, v111
	ds_bpermute_b32 v111, v108, v81
	s_waitcnt lgkmcnt(0)
	v_add_f32_e32 v81, v81, v111
	v_fmamk_f32 v81, v81, 0x3a800000, v75
	v_mul_f32_e32 v111, 0x4f800000, v81
	v_cmp_gt_f32_e32 vcc, s8, v81
	s_nop 1
	v_cndmask_b32_e32 v81, v81, v111, vcc
	v_sqrt_f32_e32 v111, v81
	s_nop 0
	v_add_u32_e32 v112, -1, v111
	v_add_u32_e32 v113, 1, v111
	v_fma_f32 v114, -v112, v111, v81
	v_fma_f32 v115, -v113, v111, v81
	v_cmp_ge_f32_e64 s[0:1], 0, v114
	s_nop 1
	v_cndmask_b32_e64 v111, v111, v112, s[0:1]
	v_cmp_lt_f32_e64 s[0:1], 0, v115
	s_nop 1
	v_cndmask_b32_e64 v111, v111, v113, s[0:1]
	v_mul_f32_e32 v112, 0x37800000, v111
	v_cndmask_b32_e32 v111, v111, v112, vcc
	v_cmp_class_f32_e32 vcc, v81, v109
	s_mov_b64 s[6:7], 0x400
	v_lshl_add_u64 v[112:113], s[6:7], 1, v[86:87]
	s_nop 0
	v_cndmask_b32_e32 v81, v111, v81, vcc
	v_div_scale_f32 v111, s[0:1], v81, v81, 1.0
	v_rcp_f32_e32 v114, v111
	v_div_scale_f32 v115, vcc, 1.0, v81, 1.0
	v_fma_f32 v116, -v111, v114, 1.0
	v_fmac_f32_e32 v114, v116, v114
	v_mul_f32_e32 v116, v115, v114
	v_fma_f32 v117, -v111, v116, v115
	v_fmac_f32_e32 v116, v117, v114
	v_fma_f32 v111, -v111, v116, v115
	v_div_fmas_f32 v111, v111, v114, v116
	v_div_fixup_f32 v114, v111, v81, 1.0
	v_pk_mul_f32 v[32:33], v[32:33], v[114:115] op_sel_hi:[1,0]
	v_pk_mul_f32 v[40:41], v[40:41], v[114:115] op_sel_hi:[1,0]
	v_pk_mul_f32 v[48:49], v[48:49], v[114:115] op_sel_hi:[1,0]
	v_pk_mul_f32 v[52:53], v[52:53], v[114:115] op_sel_hi:[1,0]
	v_pk_mul_f32 v[34:35], v[34:35], v[114:115] op_sel_hi:[1,0]
	v_pk_fma_f32 v[32:33], v[90:91], v[32:33], v[16:17]
	v_pk_mul_f32 v[42:43], v[42:43], v[114:115] op_sel_hi:[1,0]
	v_pk_fma_f32 v[40:41], v[94:95], v[40:41], v[20:21]
	v_pk_mul_f32 v[50:51], v[50:51], v[114:115] op_sel_hi:[1,0]
	v_pk_fma_f32 v[48:49], v[98:99], v[48:49], v[24:25]
	v_pk_mul_f32 v[54:55], v[54:55], v[114:115] op_sel_hi:[1,0]
	v_pk_fma_f32 v[52:53], v[102:103], v[52:53], v[28:29]
	v_pk_fma_f32 v[34:35], v[88:89], v[34:35], v[18:19]
	v_cvt_pk_bf16_f32 v32, v32, v33
	v_pk_fma_f32 v[42:43], v[92:93], v[42:43], v[22:23]
	v_cvt_pk_bf16_f32 v33, v34, v35
	global_store_dwordx2 v[112:113], v[32:33], off
	v_cvt_pk_bf16_f32 v40, v40, v41
	v_cvt_pk_bf16_f32 v41, v42, v43
	global_store_dwordx2 v[112:113], v[40:41], off offset:512
	v_pk_fma_f32 v[50:51], v[96:97], v[50:51], v[26:27]
	v_cvt_pk_bf16_f32 v48, v48, v49
	v_pk_fma_f32 v[54:55], v[100:101], v[54:55], v[30:31]
	v_cvt_pk_bf16_f32 v49, v50, v51
	global_store_dwordx2 v[112:113], v[48:49], off offset:1024
	v_cvt_pk_bf16_f32 v52, v52, v53
	v_cvt_pk_bf16_f32 v53, v54, v55
	global_store_dwordx2 v[112:113], v[52:53], off offset:1536
	s_waitcnt vmcnt(31)
	v_pk_mul_f32 v[116:117], v[178:179], v[178:179]
	v_pk_mul_f32 v[118:119], v[176:177], v[176:177]
	s_waitcnt vmcnt(30)
	v_pk_mul_f32 v[112:113], v[182:183], v[182:183]
	v_pk_mul_f32 v[114:115], v[180:181], v[180:181]
	v_pk_mov_b32 v[120:121], v[118:119], v[116:117] op_sel:[1,0]
	v_mov_b32_e32 v119, v117
	v_pk_add_f32 v[116:117], v[120:121], v[118:119]
	v_pk_mov_b32 v[118:119], v[114:115], v[112:113] op_sel:[1,0]
	v_mov_b32_e32 v115, v113
	v_pk_add_f32 v[112:113], v[118:119], v[114:115]
	v_pk_add_f32 v[116:117], v[116:117], v[116:117] op_sel_hi:[0,1]
	v_pk_add_f32 v[112:113], v[112:113], v[112:113] op_sel_hi:[0,1]
	s_waitcnt vmcnt(29)
	v_mul_f32_e32 v112, v184, v184
	v_pk_fma_f32 v[114:115], v[184:185], v[184:185], v[112:113] op_sel_hi:[1,1,0]
	v_mul_f32_e32 v112, v186, v186
	v_pk_fma_f32 v[118:119], v[186:187], v[186:187], v[112:113] op_sel_hi:[1,1,0]
	s_waitcnt vmcnt(28)
	v_mul_f32_e32 v114, v188, v188
	v_mul_f32_e32 v118, v189, v189
	v_mul_f32_e32 v116, v190, v190
	v_mul_f32_e32 v112, v191, v191
	v_pk_add_f32 v[114:115], v[114:115], v[118:119]
	v_pk_add_f32 v[112:113], v[116:117], v[112:113]
	v_pk_add_f32 v[112:113], v[114:115], v[112:113]
	v_add_f32_e32 v81, v112, v113
	ds_bpermute_b32 v111, v65, v81
	s_waitcnt lgkmcnt(0)
	v_add_f32_e32 v81, v81, v111
	ds_bpermute_b32 v111, v104, v81
	s_waitcnt lgkmcnt(0)
	v_add_f32_e32 v81, v81, v111
	ds_bpermute_b32 v111, v105, v81
	s_waitcnt lgkmcnt(0)
	v_add_f32_e32 v81, v81, v111
	ds_bpermute_b32 v111, v106, v81
	s_waitcnt lgkmcnt(0)
	v_add_f32_e32 v81, v81, v111
	ds_bpermute_b32 v111, v107, v81
	s_waitcnt lgkmcnt(0)
	v_add_f32_e32 v81, v81, v111
	ds_bpermute_b32 v111, v108, v81
	s_waitcnt lgkmcnt(0)
	v_add_f32_e32 v81, v81, v111
	v_fmamk_f32 v81, v81, 0x3a800000, v75
	v_mul_f32_e32 v111, 0x4f800000, v81
	v_cmp_gt_f32_e32 vcc, s8, v81
	s_nop 1
	v_cndmask_b32_e32 v81, v81, v111, vcc
	v_sqrt_f32_e32 v111, v81
	s_nop 0
	v_add_u32_e32 v112, -1, v111
	v_add_u32_e32 v113, 1, v111
	v_fma_f32 v114, -v112, v111, v81
	v_fma_f32 v115, -v113, v111, v81
	v_cmp_ge_f32_e64 s[0:1], 0, v114
	s_nop 1
	v_cndmask_b32_e64 v111, v111, v112, s[0:1]
	v_cmp_lt_f32_e64 s[0:1], 0, v115
	s_nop 1
	v_cndmask_b32_e64 v111, v111, v113, s[0:1]
	v_mul_f32_e32 v112, 0x37800000, v111
	v_cndmask_b32_e32 v111, v111, v112, vcc
	v_cmp_class_f32_e32 vcc, v81, v109
	s_mov_b64 s[6:7], 0x800
	v_lshl_add_u64 v[112:113], s[6:7], 1, v[86:87]
	s_nop 0
	v_cndmask_b32_e32 v81, v111, v81, vcc
	v_div_scale_f32 v111, s[0:1], v81, v81, 1.0
	v_rcp_f32_e32 v114, v111
	v_div_scale_f32 v115, vcc, 1.0, v81, 1.0
	v_fma_f32 v116, -v111, v114, 1.0
	v_fmac_f32_e32 v114, v116, v114
	v_mul_f32_e32 v116, v115, v114
	v_fma_f32 v117, -v111, v116, v115
	v_fmac_f32_e32 v116, v117, v114
	v_fma_f32 v111, -v111, v116, v115
	v_div_fmas_f32 v111, v111, v114, v116
	v_div_fixup_f32 v114, v111, v81, 1.0
	v_pk_mul_f32 v[176:177], v[176:177], v[114:115] op_sel_hi:[1,0]
	v_pk_mul_f32 v[180:181], v[180:181], v[114:115] op_sel_hi:[1,0]
	v_pk_mul_f32 v[184:185], v[184:185], v[114:115] op_sel_hi:[1,0]
	v_pk_mul_f32 v[188:189], v[188:189], v[114:115] op_sel_hi:[1,0]
	v_pk_mul_f32 v[178:179], v[178:179], v[114:115] op_sel_hi:[1,0]
	v_pk_fma_f32 v[176:177], v[90:91], v[176:177], v[16:17]
	v_pk_mul_f32 v[182:183], v[182:183], v[114:115] op_sel_hi:[1,0]
	v_pk_fma_f32 v[180:181], v[94:95], v[180:181], v[20:21]
	v_pk_mul_f32 v[186:187], v[186:187], v[114:115] op_sel_hi:[1,0]
	v_pk_fma_f32 v[184:185], v[98:99], v[184:185], v[24:25]
	v_pk_mul_f32 v[190:191], v[190:191], v[114:115] op_sel_hi:[1,0]
	v_pk_fma_f32 v[188:189], v[102:103], v[188:189], v[28:29]
	v_pk_fma_f32 v[178:179], v[88:89], v[178:179], v[18:19]
	v_cvt_pk_bf16_f32 v176, v176, v177
	v_pk_fma_f32 v[182:183], v[92:93], v[182:183], v[22:23]
	v_cvt_pk_bf16_f32 v177, v178, v179
	global_store_dwordx2 v[112:113], v[176:177], off
	v_cvt_pk_bf16_f32 v180, v180, v181
	v_cvt_pk_bf16_f32 v181, v182, v183
	global_store_dwordx2 v[112:113], v[180:181], off offset:512
	v_pk_fma_f32 v[186:187], v[96:97], v[186:187], v[26:27]
	v_cvt_pk_bf16_f32 v184, v184, v185
	v_pk_fma_f32 v[190:191], v[100:101], v[190:191], v[30:31]
	v_cvt_pk_bf16_f32 v185, v186, v187
	global_store_dwordx2 v[112:113], v[184:185], off offset:1024
	v_cvt_pk_bf16_f32 v188, v188, v189
	v_cvt_pk_bf16_f32 v189, v190, v191
	global_store_dwordx2 v[112:113], v[188:189], off offset:1536
	s_waitcnt vmcnt(31)
	v_pk_mul_f32 v[116:117], v[194:195], v[194:195]
	v_pk_mul_f32 v[118:119], v[192:193], v[192:193]
	s_waitcnt vmcnt(30)
	v_pk_mul_f32 v[112:113], v[198:199], v[198:199]
	v_pk_mul_f32 v[114:115], v[196:197], v[196:197]
	v_pk_mov_b32 v[120:121], v[118:119], v[116:117] op_sel:[1,0]
	v_mov_b32_e32 v119, v117
	v_pk_add_f32 v[116:117], v[120:121], v[118:119]
	v_pk_mov_b32 v[118:119], v[114:115], v[112:113] op_sel:[1,0]
	v_mov_b32_e32 v115, v113
	v_pk_add_f32 v[112:113], v[118:119], v[114:115]
	v_pk_add_f32 v[116:117], v[116:117], v[116:117] op_sel_hi:[0,1]
	v_pk_add_f32 v[112:113], v[112:113], v[112:113] op_sel_hi:[0,1]
	s_waitcnt vmcnt(29)
	v_mul_f32_e32 v112, v200, v200
	v_pk_fma_f32 v[114:115], v[200:201], v[200:201], v[112:113] op_sel_hi:[1,1,0]
	v_mul_f32_e32 v112, v202, v202
	v_pk_fma_f32 v[118:119], v[202:203], v[202:203], v[112:113] op_sel_hi:[1,1,0]
	s_waitcnt vmcnt(28)
	v_mul_f32_e32 v114, v204, v204
	v_mul_f32_e32 v118, v205, v205
	v_mul_f32_e32 v116, v206, v206
	v_mul_f32_e32 v112, v207, v207
	v_pk_add_f32 v[114:115], v[114:115], v[118:119]
	v_pk_add_f32 v[112:113], v[116:117], v[112:113]
	v_pk_add_f32 v[112:113], v[114:115], v[112:113]
	v_add_f32_e32 v81, v112, v113
	ds_bpermute_b32 v111, v65, v81
	s_waitcnt lgkmcnt(0)
	v_add_f32_e32 v81, v81, v111
	ds_bpermute_b32 v111, v104, v81
	s_waitcnt lgkmcnt(0)
	v_add_f32_e32 v81, v81, v111
	ds_bpermute_b32 v111, v105, v81
	s_waitcnt lgkmcnt(0)
	v_add_f32_e32 v81, v81, v111
	ds_bpermute_b32 v111, v106, v81
	s_waitcnt lgkmcnt(0)
	v_add_f32_e32 v81, v81, v111
	ds_bpermute_b32 v111, v107, v81
	s_waitcnt lgkmcnt(0)
	v_add_f32_e32 v81, v81, v111
	ds_bpermute_b32 v111, v108, v81
	s_waitcnt lgkmcnt(0)
	v_add_f32_e32 v81, v81, v111
	v_fmamk_f32 v81, v81, 0x3a800000, v75
	v_mul_f32_e32 v111, 0x4f800000, v81
	v_cmp_gt_f32_e32 vcc, s8, v81
	s_nop 1
	v_cndmask_b32_e32 v81, v81, v111, vcc
	v_sqrt_f32_e32 v111, v81
	s_nop 0
	v_add_u32_e32 v112, -1, v111
	v_add_u32_e32 v113, 1, v111
	v_fma_f32 v114, -v112, v111, v81
	v_fma_f32 v115, -v113, v111, v81
	v_cmp_ge_f32_e64 s[0:1], 0, v114
	s_nop 1
	v_cndmask_b32_e64 v111, v111, v112, s[0:1]
	v_cmp_lt_f32_e64 s[0:1], 0, v115
	s_nop 1
	v_cndmask_b32_e64 v111, v111, v113, s[0:1]
	v_mul_f32_e32 v112, 0x37800000, v111
	v_cndmask_b32_e32 v111, v111, v112, vcc
	v_cmp_class_f32_e32 vcc, v81, v109
	s_mov_b64 s[6:7], 0xc00
	v_lshl_add_u64 v[112:113], s[6:7], 1, v[86:87]
	s_nop 0
	v_cndmask_b32_e32 v81, v111, v81, vcc
	v_div_scale_f32 v111, s[0:1], v81, v81, 1.0
	v_rcp_f32_e32 v114, v111
	v_div_scale_f32 v115, vcc, 1.0, v81, 1.0
	v_fma_f32 v116, -v111, v114, 1.0
	v_fmac_f32_e32 v114, v116, v114
	v_mul_f32_e32 v116, v115, v114
	v_fma_f32 v117, -v111, v116, v115
	v_fmac_f32_e32 v116, v117, v114
	v_fma_f32 v111, -v111, v116, v115
	v_div_fmas_f32 v111, v111, v114, v116
	v_div_fixup_f32 v114, v111, v81, 1.0
	v_pk_mul_f32 v[192:193], v[192:193], v[114:115] op_sel_hi:[1,0]
	v_pk_mul_f32 v[196:197], v[196:197], v[114:115] op_sel_hi:[1,0]
	v_pk_mul_f32 v[200:201], v[200:201], v[114:115] op_sel_hi:[1,0]
	v_pk_mul_f32 v[204:205], v[204:205], v[114:115] op_sel_hi:[1,0]
	v_pk_mul_f32 v[194:195], v[194:195], v[114:115] op_sel_hi:[1,0]
	v_pk_fma_f32 v[192:193], v[90:91], v[192:193], v[16:17]
	v_pk_mul_f32 v[198:199], v[198:199], v[114:115] op_sel_hi:[1,0]
	v_pk_fma_f32 v[196:197], v[94:95], v[196:197], v[20:21]
	v_pk_mul_f32 v[202:203], v[202:203], v[114:115] op_sel_hi:[1,0]
	v_pk_fma_f32 v[200:201], v[98:99], v[200:201], v[24:25]
	v_pk_mul_f32 v[206:207], v[206:207], v[114:115] op_sel_hi:[1,0]
	v_pk_fma_f32 v[204:205], v[102:103], v[204:205], v[28:29]
	v_pk_fma_f32 v[194:195], v[88:89], v[194:195], v[18:19]
	v_cvt_pk_bf16_f32 v192, v192, v193
	v_pk_fma_f32 v[198:199], v[92:93], v[198:199], v[22:23]
	v_cvt_pk_bf16_f32 v193, v194, v195
	global_store_dwordx2 v[112:113], v[192:193], off
	v_cvt_pk_bf16_f32 v196, v196, v197
	v_cvt_pk_bf16_f32 v197, v198, v199
	global_store_dwordx2 v[112:113], v[196:197], off offset:512
	v_pk_fma_f32 v[202:203], v[96:97], v[202:203], v[26:27]
	v_cvt_pk_bf16_f32 v200, v200, v201
	v_pk_fma_f32 v[206:207], v[100:101], v[206:207], v[30:31]
	v_cvt_pk_bf16_f32 v201, v202, v203
	global_store_dwordx2 v[112:113], v[200:201], off offset:1024
	v_cvt_pk_bf16_f32 v204, v204, v205
	v_cvt_pk_bf16_f32 v205, v206, v207
	global_store_dwordx2 v[112:113], v[204:205], off offset:1536
	s_waitcnt vmcnt(31)
	v_pk_mul_f32 v[116:117], v[210:211], v[210:211]
	v_pk_mul_f32 v[118:119], v[208:209], v[208:209]
	s_waitcnt vmcnt(30)
	v_pk_mul_f32 v[112:113], v[214:215], v[214:215]
	v_pk_mul_f32 v[114:115], v[212:213], v[212:213]
	v_pk_mov_b32 v[120:121], v[118:119], v[116:117] op_sel:[1,0]
	v_mov_b32_e32 v119, v117
	v_pk_add_f32 v[116:117], v[120:121], v[118:119]
	v_pk_mov_b32 v[118:119], v[114:115], v[112:113] op_sel:[1,0]
	v_mov_b32_e32 v115, v113
	v_pk_add_f32 v[112:113], v[118:119], v[114:115]
	v_pk_add_f32 v[116:117], v[116:117], v[116:117] op_sel_hi:[0,1]
	v_pk_add_f32 v[112:113], v[112:113], v[112:113] op_sel_hi:[0,1]
	s_waitcnt vmcnt(29)
	v_mul_f32_e32 v112, v216, v216
	v_pk_fma_f32 v[114:115], v[216:217], v[216:217], v[112:113] op_sel_hi:[1,1,0]
	v_mul_f32_e32 v112, v218, v218
	v_pk_fma_f32 v[118:119], v[218:219], v[218:219], v[112:113] op_sel_hi:[1,1,0]
	s_waitcnt vmcnt(28)
	v_mul_f32_e32 v114, v220, v220
	v_mul_f32_e32 v118, v221, v221
	v_mul_f32_e32 v116, v222, v222
	v_mul_f32_e32 v112, v223, v223
	v_pk_add_f32 v[114:115], v[114:115], v[118:119]
	v_pk_add_f32 v[112:113], v[116:117], v[112:113]
	v_pk_add_f32 v[112:113], v[114:115], v[112:113]
	v_add_f32_e32 v81, v112, v113
	ds_bpermute_b32 v111, v65, v81
	s_waitcnt lgkmcnt(0)
	v_add_f32_e32 v81, v81, v111
	ds_bpermute_b32 v111, v104, v81
	s_waitcnt lgkmcnt(0)
	v_add_f32_e32 v81, v81, v111
	ds_bpermute_b32 v111, v105, v81
	s_waitcnt lgkmcnt(0)
	v_add_f32_e32 v81, v81, v111
	ds_bpermute_b32 v111, v106, v81
	s_waitcnt lgkmcnt(0)
	v_add_f32_e32 v81, v81, v111
	ds_bpermute_b32 v111, v107, v81
	s_waitcnt lgkmcnt(0)
	v_add_f32_e32 v81, v81, v111
	ds_bpermute_b32 v111, v108, v81
	s_waitcnt lgkmcnt(0)
	v_add_f32_e32 v81, v81, v111
	v_fmamk_f32 v81, v81, 0x3a800000, v75
	v_mul_f32_e32 v111, 0x4f800000, v81
	v_cmp_gt_f32_e32 vcc, s8, v81
	s_nop 1
	v_cndmask_b32_e32 v81, v81, v111, vcc
	v_sqrt_f32_e32 v111, v81
	s_nop 0
	v_add_u32_e32 v112, -1, v111
	v_add_u32_e32 v113, 1, v111
	v_fma_f32 v114, -v112, v111, v81
	v_fma_f32 v115, -v113, v111, v81
	v_cmp_ge_f32_e64 s[0:1], 0, v114
	s_nop 1
	v_cndmask_b32_e64 v111, v111, v112, s[0:1]
	v_cmp_lt_f32_e64 s[0:1], 0, v115
	s_nop 1
	v_cndmask_b32_e64 v111, v111, v113, s[0:1]
	v_mul_f32_e32 v112, 0x37800000, v111
	v_cndmask_b32_e32 v111, v111, v112, vcc
	v_cmp_class_f32_e32 vcc, v81, v109
	s_mov_b64 s[6:7], 0x1000
	v_lshl_add_u64 v[112:113], s[6:7], 1, v[86:87]
	s_nop 0
	v_cndmask_b32_e32 v81, v111, v81, vcc
	v_div_scale_f32 v111, s[0:1], v81, v81, 1.0
	v_rcp_f32_e32 v114, v111
	v_div_scale_f32 v115, vcc, 1.0, v81, 1.0
	v_fma_f32 v116, -v111, v114, 1.0
	v_fmac_f32_e32 v114, v116, v114
	v_mul_f32_e32 v116, v115, v114
	v_fma_f32 v117, -v111, v116, v115
	v_fmac_f32_e32 v116, v117, v114
	v_fma_f32 v111, -v111, v116, v115
	v_div_fmas_f32 v111, v111, v114, v116
	v_div_fixup_f32 v114, v111, v81, 1.0
	v_pk_mul_f32 v[208:209], v[208:209], v[114:115] op_sel_hi:[1,0]
	v_pk_mul_f32 v[212:213], v[212:213], v[114:115] op_sel_hi:[1,0]
	v_pk_mul_f32 v[216:217], v[216:217], v[114:115] op_sel_hi:[1,0]
	v_pk_mul_f32 v[220:221], v[220:221], v[114:115] op_sel_hi:[1,0]
	v_pk_mul_f32 v[210:211], v[210:211], v[114:115] op_sel_hi:[1,0]
	v_pk_fma_f32 v[208:209], v[90:91], v[208:209], v[16:17]
	v_pk_mul_f32 v[214:215], v[214:215], v[114:115] op_sel_hi:[1,0]
	v_pk_fma_f32 v[212:213], v[94:95], v[212:213], v[20:21]
	v_pk_mul_f32 v[218:219], v[218:219], v[114:115] op_sel_hi:[1,0]
	v_pk_fma_f32 v[216:217], v[98:99], v[216:217], v[24:25]
	v_pk_mul_f32 v[222:223], v[222:223], v[114:115] op_sel_hi:[1,0]
	v_pk_fma_f32 v[220:221], v[102:103], v[220:221], v[28:29]
	v_pk_fma_f32 v[210:211], v[88:89], v[210:211], v[18:19]
	v_cvt_pk_bf16_f32 v208, v208, v209
	v_pk_fma_f32 v[214:215], v[92:93], v[214:215], v[22:23]
	v_cvt_pk_bf16_f32 v209, v210, v211
	global_store_dwordx2 v[112:113], v[208:209], off
	v_cvt_pk_bf16_f32 v212, v212, v213
	v_cvt_pk_bf16_f32 v213, v214, v215
	global_store_dwordx2 v[112:113], v[212:213], off offset:512
	v_pk_fma_f32 v[218:219], v[96:97], v[218:219], v[26:27]
	v_cvt_pk_bf16_f32 v216, v216, v217
	v_pk_fma_f32 v[222:223], v[100:101], v[222:223], v[30:31]
	v_cvt_pk_bf16_f32 v217, v218, v219
	global_store_dwordx2 v[112:113], v[216:217], off offset:1024
	v_cvt_pk_bf16_f32 v220, v220, v221
	v_cvt_pk_bf16_f32 v221, v222, v223
	global_store_dwordx2 v[112:113], v[220:221], off offset:1536
	s_waitcnt vmcnt(31)
	v_pk_mul_f32 v[116:117], v[226:227], v[226:227]
	v_pk_mul_f32 v[118:119], v[224:225], v[224:225]
	s_waitcnt vmcnt(30)
	v_pk_mul_f32 v[112:113], v[230:231], v[230:231]
	v_pk_mul_f32 v[114:115], v[228:229], v[228:229]
	v_pk_mov_b32 v[120:121], v[118:119], v[116:117] op_sel:[1,0]
	v_mov_b32_e32 v119, v117
	v_pk_add_f32 v[116:117], v[120:121], v[118:119]
	v_pk_mov_b32 v[118:119], v[114:115], v[112:113] op_sel:[1,0]
	v_mov_b32_e32 v115, v113
	v_pk_add_f32 v[112:113], v[118:119], v[114:115]
	v_pk_add_f32 v[116:117], v[116:117], v[116:117] op_sel_hi:[0,1]
	v_pk_add_f32 v[112:113], v[112:113], v[112:113] op_sel_hi:[0,1]
	s_waitcnt vmcnt(29)
	v_mul_f32_e32 v112, v232, v232
	v_pk_fma_f32 v[114:115], v[232:233], v[232:233], v[112:113] op_sel_hi:[1,1,0]
	v_mul_f32_e32 v112, v234, v234
	v_pk_fma_f32 v[118:119], v[234:235], v[234:235], v[112:113] op_sel_hi:[1,1,0]
	s_waitcnt vmcnt(28)
	v_mul_f32_e32 v114, v236, v236
	v_mul_f32_e32 v118, v237, v237
	v_mul_f32_e32 v116, v238, v238
	v_mul_f32_e32 v112, v239, v239
	v_pk_add_f32 v[114:115], v[114:115], v[118:119]
	v_pk_add_f32 v[112:113], v[116:117], v[112:113]
	v_pk_add_f32 v[112:113], v[114:115], v[112:113]
	v_add_f32_e32 v81, v112, v113
	ds_bpermute_b32 v111, v65, v81
	s_waitcnt lgkmcnt(0)
	v_add_f32_e32 v81, v81, v111
	ds_bpermute_b32 v111, v104, v81
	s_waitcnt lgkmcnt(0)
	v_add_f32_e32 v81, v81, v111
	ds_bpermute_b32 v111, v105, v81
	s_waitcnt lgkmcnt(0)
	v_add_f32_e32 v81, v81, v111
	ds_bpermute_b32 v111, v106, v81
	s_waitcnt lgkmcnt(0)
	v_add_f32_e32 v81, v81, v111
	ds_bpermute_b32 v111, v107, v81
	s_waitcnt lgkmcnt(0)
	v_add_f32_e32 v81, v81, v111
	ds_bpermute_b32 v111, v108, v81
	s_waitcnt lgkmcnt(0)
	v_add_f32_e32 v81, v81, v111
	v_fmamk_f32 v81, v81, 0x3a800000, v75
	v_mul_f32_e32 v111, 0x4f800000, v81
	v_cmp_gt_f32_e32 vcc, s8, v81
	s_nop 1
	v_cndmask_b32_e32 v81, v81, v111, vcc
	v_sqrt_f32_e32 v111, v81
	s_nop 0
	v_add_u32_e32 v112, -1, v111
	v_add_u32_e32 v113, 1, v111
	v_fma_f32 v114, -v112, v111, v81
	v_fma_f32 v115, -v113, v111, v81
	v_cmp_ge_f32_e64 s[0:1], 0, v114
	s_nop 1
	v_cndmask_b32_e64 v111, v111, v112, s[0:1]
	v_cmp_lt_f32_e64 s[0:1], 0, v115
	s_nop 1
	v_cndmask_b32_e64 v111, v111, v113, s[0:1]
	v_mul_f32_e32 v112, 0x37800000, v111
	v_cndmask_b32_e32 v111, v111, v112, vcc
	v_cmp_class_f32_e32 vcc, v81, v109
	s_mov_b64 s[6:7], 0x1400
	v_lshl_add_u64 v[112:113], s[6:7], 1, v[86:87]
	s_nop 0
	v_cndmask_b32_e32 v81, v111, v81, vcc
	v_div_scale_f32 v111, s[0:1], v81, v81, 1.0
	v_rcp_f32_e32 v114, v111
	v_div_scale_f32 v115, vcc, 1.0, v81, 1.0
	v_fma_f32 v116, -v111, v114, 1.0
	v_fmac_f32_e32 v114, v116, v114
	v_mul_f32_e32 v116, v115, v114
	v_fma_f32 v117, -v111, v116, v115
	v_fmac_f32_e32 v116, v117, v114
	v_fma_f32 v111, -v111, v116, v115
	v_div_fmas_f32 v111, v111, v114, v116
	v_div_fixup_f32 v114, v111, v81, 1.0
	v_pk_mul_f32 v[224:225], v[224:225], v[114:115] op_sel_hi:[1,0]
	v_pk_mul_f32 v[228:229], v[228:229], v[114:115] op_sel_hi:[1,0]
	v_pk_mul_f32 v[232:233], v[232:233], v[114:115] op_sel_hi:[1,0]
	v_pk_mul_f32 v[236:237], v[236:237], v[114:115] op_sel_hi:[1,0]
	v_pk_mul_f32 v[226:227], v[226:227], v[114:115] op_sel_hi:[1,0]
	v_pk_fma_f32 v[224:225], v[90:91], v[224:225], v[16:17]
	v_pk_mul_f32 v[230:231], v[230:231], v[114:115] op_sel_hi:[1,0]
	v_pk_fma_f32 v[228:229], v[94:95], v[228:229], v[20:21]
	v_pk_mul_f32 v[234:235], v[234:235], v[114:115] op_sel_hi:[1,0]
	v_pk_fma_f32 v[232:233], v[98:99], v[232:233], v[24:25]
	v_pk_mul_f32 v[238:239], v[238:239], v[114:115] op_sel_hi:[1,0]
	v_pk_fma_f32 v[236:237], v[102:103], v[236:237], v[28:29]
	v_pk_fma_f32 v[226:227], v[88:89], v[226:227], v[18:19]
	v_cvt_pk_bf16_f32 v224, v224, v225
	v_pk_fma_f32 v[230:231], v[92:93], v[230:231], v[22:23]
	v_cvt_pk_bf16_f32 v225, v226, v227
	global_store_dwordx2 v[112:113], v[224:225], off
	v_cvt_pk_bf16_f32 v228, v228, v229
	v_cvt_pk_bf16_f32 v229, v230, v231
	global_store_dwordx2 v[112:113], v[228:229], off offset:512
	v_pk_fma_f32 v[234:235], v[96:97], v[234:235], v[26:27]
	v_cvt_pk_bf16_f32 v232, v232, v233
	v_pk_fma_f32 v[238:239], v[100:101], v[238:239], v[30:31]
	v_cvt_pk_bf16_f32 v233, v234, v235
	global_store_dwordx2 v[112:113], v[232:233], off offset:1024
	v_cvt_pk_bf16_f32 v236, v236, v237
	v_cvt_pk_bf16_f32 v237, v238, v239
	global_store_dwordx2 v[112:113], v[236:237], off offset:1536
	s_waitcnt vmcnt(31)
	v_pk_mul_f32 v[116:117], v[242:243], v[242:243]
	v_pk_mul_f32 v[118:119], v[240:241], v[240:241]
	s_waitcnt vmcnt(30)
	v_pk_mul_f32 v[112:113], v[246:247], v[246:247]
	v_pk_mul_f32 v[114:115], v[244:245], v[244:245]
	v_pk_mov_b32 v[120:121], v[118:119], v[116:117] op_sel:[1,0]
	v_mov_b32_e32 v119, v117
	v_pk_add_f32 v[116:117], v[120:121], v[118:119]
	v_pk_mov_b32 v[118:119], v[114:115], v[112:113] op_sel:[1,0]
	v_mov_b32_e32 v115, v113
	v_pk_add_f32 v[112:113], v[118:119], v[114:115]
	v_pk_add_f32 v[116:117], v[116:117], v[116:117] op_sel_hi:[0,1]
	v_pk_add_f32 v[112:113], v[112:113], v[112:113] op_sel_hi:[0,1]
	s_waitcnt vmcnt(29)
	v_mul_f32_e32 v112, v248, v248
	v_pk_fma_f32 v[114:115], v[248:249], v[248:249], v[112:113] op_sel_hi:[1,1,0]
	v_mul_f32_e32 v112, v250, v250
	v_pk_fma_f32 v[118:119], v[250:251], v[250:251], v[112:113] op_sel_hi:[1,1,0]
	s_waitcnt vmcnt(28)
	v_mul_f32_e32 v114, v124, v124
	v_mul_f32_e32 v118, v125, v125
	v_mul_f32_e32 v116, v126, v126
	v_mul_f32_e32 v112, v127, v127
	v_pk_add_f32 v[114:115], v[114:115], v[118:119]
	v_pk_add_f32 v[112:113], v[116:117], v[112:113]
	v_pk_add_f32 v[112:113], v[114:115], v[112:113]
	v_add_f32_e32 v81, v112, v113
	ds_bpermute_b32 v111, v65, v81
	s_waitcnt lgkmcnt(0)
	v_add_f32_e32 v81, v81, v111
	ds_bpermute_b32 v111, v104, v81
	s_waitcnt lgkmcnt(0)
	v_add_f32_e32 v81, v81, v111
	ds_bpermute_b32 v111, v105, v81
	s_waitcnt lgkmcnt(0)
	v_add_f32_e32 v81, v81, v111
	ds_bpermute_b32 v111, v106, v81
	s_waitcnt lgkmcnt(0)
	v_add_f32_e32 v81, v81, v111
	ds_bpermute_b32 v111, v107, v81
	s_waitcnt lgkmcnt(0)
	v_add_f32_e32 v81, v81, v111
	ds_bpermute_b32 v111, v108, v81
	s_waitcnt lgkmcnt(0)
	v_add_f32_e32 v81, v81, v111
	v_fmamk_f32 v81, v81, 0x3a800000, v75
	v_mul_f32_e32 v111, 0x4f800000, v81
	v_cmp_gt_f32_e32 vcc, s8, v81
	s_nop 1
	v_cndmask_b32_e32 v81, v81, v111, vcc
	v_sqrt_f32_e32 v111, v81
	s_nop 0
	v_add_u32_e32 v112, -1, v111
	v_add_u32_e32 v113, 1, v111
	v_fma_f32 v114, -v112, v111, v81
	v_fma_f32 v115, -v113, v111, v81
	v_cmp_ge_f32_e64 s[0:1], 0, v114
	s_nop 1
	v_cndmask_b32_e64 v111, v111, v112, s[0:1]
	v_cmp_lt_f32_e64 s[0:1], 0, v115
	s_nop 1
	v_cndmask_b32_e64 v111, v111, v113, s[0:1]
	v_mul_f32_e32 v112, 0x37800000, v111
	v_cndmask_b32_e32 v111, v111, v112, vcc
	v_cmp_class_f32_e32 vcc, v81, v109
	s_mov_b64 s[6:7], 0x1800
	v_lshl_add_u64 v[112:113], s[6:7], 1, v[86:87]
	s_nop 0
	v_cndmask_b32_e32 v81, v111, v81, vcc
	v_div_scale_f32 v111, s[0:1], v81, v81, 1.0
	v_rcp_f32_e32 v114, v111
	v_div_scale_f32 v115, vcc, 1.0, v81, 1.0
	v_fma_f32 v116, -v111, v114, 1.0
	v_fmac_f32_e32 v114, v116, v114
	v_mul_f32_e32 v116, v115, v114
	v_fma_f32 v117, -v111, v116, v115
	v_fmac_f32_e32 v116, v117, v114
	v_fma_f32 v111, -v111, v116, v115
	v_div_fmas_f32 v111, v111, v114, v116
	v_div_fixup_f32 v114, v111, v81, 1.0
	v_pk_mul_f32 v[240:241], v[240:241], v[114:115] op_sel_hi:[1,0]
	v_pk_mul_f32 v[244:245], v[244:245], v[114:115] op_sel_hi:[1,0]
	v_pk_mul_f32 v[248:249], v[248:249], v[114:115] op_sel_hi:[1,0]
	v_pk_mul_f32 v[124:125], v[124:125], v[114:115] op_sel_hi:[1,0]
	v_pk_mul_f32 v[242:243], v[242:243], v[114:115] op_sel_hi:[1,0]
	v_pk_fma_f32 v[240:241], v[90:91], v[240:241], v[16:17]
	v_pk_mul_f32 v[246:247], v[246:247], v[114:115] op_sel_hi:[1,0]
	v_pk_fma_f32 v[244:245], v[94:95], v[244:245], v[20:21]
	v_pk_mul_f32 v[250:251], v[250:251], v[114:115] op_sel_hi:[1,0]
	v_pk_fma_f32 v[248:249], v[98:99], v[248:249], v[24:25]
	v_pk_mul_f32 v[126:127], v[126:127], v[114:115] op_sel_hi:[1,0]
	v_pk_fma_f32 v[124:125], v[102:103], v[124:125], v[28:29]
	v_pk_fma_f32 v[242:243], v[88:89], v[242:243], v[18:19]
	v_cvt_pk_bf16_f32 v240, v240, v241
	v_pk_fma_f32 v[246:247], v[92:93], v[246:247], v[22:23]
	v_cvt_pk_bf16_f32 v241, v242, v243
	global_store_dwordx2 v[112:113], v[240:241], off
	v_cvt_pk_bf16_f32 v244, v244, v245
	v_cvt_pk_bf16_f32 v245, v246, v247
	global_store_dwordx2 v[112:113], v[244:245], off offset:512
	v_pk_fma_f32 v[250:251], v[96:97], v[250:251], v[26:27]
	v_cvt_pk_bf16_f32 v248, v248, v249
	v_pk_fma_f32 v[126:127], v[100:101], v[126:127], v[30:31]
	v_cvt_pk_bf16_f32 v249, v250, v251
	global_store_dwordx2 v[112:113], v[248:249], off offset:1024
	v_cvt_pk_bf16_f32 v124, v124, v125
	v_cvt_pk_bf16_f32 v125, v126, v127
	global_store_dwordx2 v[112:113], v[124:125], off offset:1536
	s_waitcnt vmcnt(31)
	v_pk_mul_f32 v[116:117], v[130:131], v[130:131]
	v_pk_mul_f32 v[118:119], v[128:129], v[128:129]
	s_waitcnt vmcnt(30)
	v_pk_mul_f32 v[112:113], v[134:135], v[134:135]
	v_pk_mul_f32 v[114:115], v[132:133], v[132:133]
	v_pk_mov_b32 v[120:121], v[118:119], v[116:117] op_sel:[1,0]
	v_mov_b32_e32 v119, v117
	v_pk_add_f32 v[116:117], v[120:121], v[118:119]
	v_pk_mov_b32 v[118:119], v[114:115], v[112:113] op_sel:[1,0]
	v_mov_b32_e32 v115, v113
	v_pk_add_f32 v[112:113], v[118:119], v[114:115]
	v_pk_add_f32 v[116:117], v[116:117], v[116:117] op_sel_hi:[0,1]
	v_pk_add_f32 v[112:113], v[112:113], v[112:113] op_sel_hi:[0,1]
	s_waitcnt vmcnt(29)
	v_mul_f32_e32 v112, v136, v136
	v_pk_fma_f32 v[114:115], v[136:137], v[136:137], v[112:113] op_sel_hi:[1,1,0]
	v_mul_f32_e32 v112, v138, v138
	v_pk_fma_f32 v[118:119], v[138:139], v[138:139], v[112:113] op_sel_hi:[1,1,0]
	s_waitcnt vmcnt(28)
	v_mul_f32_e32 v114, v140, v140
	v_mul_f32_e32 v118, v141, v141
	v_mul_f32_e32 v116, v142, v142
	v_mul_f32_e32 v112, v143, v143
	v_pk_add_f32 v[114:115], v[114:115], v[118:119]
	v_pk_add_f32 v[112:113], v[116:117], v[112:113]
	v_pk_add_f32 v[112:113], v[114:115], v[112:113]
	v_add_f32_e32 v81, v112, v113
	ds_bpermute_b32 v111, v65, v81
	s_waitcnt lgkmcnt(0)
	v_add_f32_e32 v81, v81, v111
	ds_bpermute_b32 v111, v104, v81
	s_waitcnt lgkmcnt(0)
	v_add_f32_e32 v81, v81, v111
	ds_bpermute_b32 v111, v105, v81
	s_waitcnt lgkmcnt(0)
	v_add_f32_e32 v81, v81, v111
	ds_bpermute_b32 v111, v106, v81
	s_waitcnt lgkmcnt(0)
	v_add_f32_e32 v81, v81, v111
	ds_bpermute_b32 v111, v107, v81
	s_waitcnt lgkmcnt(0)
	v_add_f32_e32 v81, v81, v111
	ds_bpermute_b32 v111, v108, v81
	s_waitcnt lgkmcnt(0)
	v_add_f32_e32 v81, v81, v111
	v_fmamk_f32 v81, v81, 0x3a800000, v75
	v_mul_f32_e32 v111, 0x4f800000, v81
	v_cmp_gt_f32_e32 vcc, s8, v81
	s_nop 1
	v_cndmask_b32_e32 v81, v81, v111, vcc
	v_sqrt_f32_e32 v111, v81
	s_nop 0
	v_add_u32_e32 v112, -1, v111
	v_add_u32_e32 v113, 1, v111
	v_fma_f32 v114, -v112, v111, v81
	v_fma_f32 v115, -v113, v111, v81
	v_cmp_ge_f32_e64 s[0:1], 0, v114
	s_nop 1
	v_cndmask_b32_e64 v111, v111, v112, s[0:1]
	v_cmp_lt_f32_e64 s[0:1], 0, v115
	s_nop 1
	v_cndmask_b32_e64 v111, v111, v113, s[0:1]
	v_mul_f32_e32 v112, 0x37800000, v111
	v_cndmask_b32_e32 v111, v111, v112, vcc
	v_cmp_class_f32_e32 vcc, v81, v109
	s_mov_b64 s[6:7], 0x1c00
	v_lshl_add_u64 v[112:113], s[6:7], 1, v[86:87]
	s_nop 0
	v_cndmask_b32_e32 v81, v111, v81, vcc
	v_div_scale_f32 v111, s[0:1], v81, v81, 1.0
	v_rcp_f32_e32 v114, v111
	v_div_scale_f32 v115, vcc, 1.0, v81, 1.0
	v_fma_f32 v116, -v111, v114, 1.0
	v_fmac_f32_e32 v114, v116, v114
	v_mul_f32_e32 v116, v115, v114
	v_fma_f32 v117, -v111, v116, v115
	v_fmac_f32_e32 v116, v117, v114
	v_fma_f32 v111, -v111, v116, v115
	v_div_fmas_f32 v111, v111, v114, v116
	v_div_fixup_f32 v114, v111, v81, 1.0
	v_pk_mul_f32 v[128:129], v[128:129], v[114:115] op_sel_hi:[1,0]
	v_pk_mul_f32 v[132:133], v[132:133], v[114:115] op_sel_hi:[1,0]
	v_pk_mul_f32 v[136:137], v[136:137], v[114:115] op_sel_hi:[1,0]
	v_pk_mul_f32 v[140:141], v[140:141], v[114:115] op_sel_hi:[1,0]
	v_pk_mul_f32 v[130:131], v[130:131], v[114:115] op_sel_hi:[1,0]
	v_pk_fma_f32 v[128:129], v[90:91], v[128:129], v[16:17]
	v_pk_mul_f32 v[134:135], v[134:135], v[114:115] op_sel_hi:[1,0]
	v_pk_fma_f32 v[132:133], v[94:95], v[132:133], v[20:21]
	v_pk_mul_f32 v[138:139], v[138:139], v[114:115] op_sel_hi:[1,0]
	v_pk_fma_f32 v[136:137], v[98:99], v[136:137], v[24:25]
	v_pk_mul_f32 v[142:143], v[142:143], v[114:115] op_sel_hi:[1,0]
	v_pk_fma_f32 v[140:141], v[102:103], v[140:141], v[28:29]
	v_pk_fma_f32 v[130:131], v[88:89], v[130:131], v[18:19]
	v_cvt_pk_bf16_f32 v128, v128, v129
	v_pk_fma_f32 v[134:135], v[92:93], v[134:135], v[22:23]
	v_cvt_pk_bf16_f32 v129, v130, v131
	global_store_dwordx2 v[112:113], v[128:129], off
	v_cvt_pk_bf16_f32 v132, v132, v133
	v_cvt_pk_bf16_f32 v133, v134, v135
	global_store_dwordx2 v[112:113], v[132:133], off offset:512
	v_pk_fma_f32 v[138:139], v[96:97], v[138:139], v[26:27]
	v_cvt_pk_bf16_f32 v136, v136, v137
	v_pk_fma_f32 v[142:143], v[100:101], v[142:143], v[30:31]
	v_cvt_pk_bf16_f32 v137, v138, v139
	global_store_dwordx2 v[112:113], v[136:137], off offset:1024
	v_cvt_pk_bf16_f32 v140, v140, v141
	v_cvt_pk_bf16_f32 v141, v142, v143
	global_store_dwordx2 v[112:113], v[140:141], off offset:1536
	s_branch .LBB0_249

.LBB0_495:
	v_lshrrev_b32_e32 v16, 8, v93
	v_mul_hi_i32_i24_e32 v17, 0x9000, v16
	v_mul_i32_i24_e32 v16, 0x9000, v16
	v_lshl_add_u64 v[16:17], s[96:97], 0, v[16:17]
	v_lshlrev_b32_e32 v32, 3, v93
	v_lshl_add_u64 v[18:19], v[16:17], 0, s[50:51]
	v_ashrrev_i32_e32 v33, 31, v32
	v_lshl_add_u64 v[24:25], v[16:17], 0, s[52:53]
	v_lshl_add_u64 v[16:17], v[18:19], 0, v[52:53]
	v_lshlrev_b64 v[68:69], 11, v[32:33]
	global_load_dwordx4 v[76:79], v[56:57], off offset:16
	global_load_dwordx4 v[72:75], v[56:57], off
	global_load_dwordx4 v[80:83], v[16:17], off offset:16
	global_load_dwordx4 v[94:97], v[16:17], off
	v_lshl_add_u64 v[20:21], v[24:25], 0, v[52:53]
	v_lshl_add_u64 v[16:17], v[18:19], 0, v[62:63]
	v_lshl_add_u64 v[32:33], s[22:23], 0, v[68:69]
	global_load_dwordx4 v[98:101], v[16:17], off offset:16
	global_load_dwordx4 v[102:105], v[16:17], off
	s_nop 0
	global_load_dwordx4 v[16:19], v[20:21], off offset:16
	s_nop 0
	global_load_dwordx4 v[20:23], v[20:21], off
	s_nop 0
	global_load_dwordx4 v[106:109], v[56:57], off offset:2064
	global_load_dwordx4 v[110:113], v[56:57], off offset:2048
	v_lshl_add_u64 v[28:29], v[24:25], 0, v[62:63]
	v_lshl_add_u64 v[32:33], v[32:33], 0, v[64:65]
	global_load_dwordx4 v[24:27], v[28:29], off offset:16
	s_nop 0
	global_load_dwordx4 v[28:31], v[28:29], off
	s_nop 0
	global_load_dwordx4 v[44:47], v[32:33], off
	global_load_dwordx4 v[40:43], v[32:33], off offset:1024
	v_ashrrev_i32_e32 v61, 31, v60
	v_lshlrev_b64 v[66:67], 11, v[60:61]
	v_lshl_add_u64 v[66:67], v[58:59], 0, v[66:67]
	v_lshl_add_u64 v[68:69], v[54:55], 0, v[68:69]
	s_mov_b64 s[6:7], 0xc500800
	v_lshl_add_u64 v[226:227], v[66:67], 0, s[6:7]
	global_load_dwordx4 v[32:35], v[226:227], off
	global_load_dwordx4 v[36:39], v[226:227], off offset:1024
	s_mov_b64 s[6:7], 0xc501000
	v_lshl_add_u64 v[224:225], v[66:67], 0, s[6:7]
	global_load_dwordx4 v[176:179], v[224:225], off
	global_load_dwordx4 v[180:183], v[224:225], off offset:1024
	s_mov_b64 s[6:7], 0xc501800
	v_lshl_add_u64 v[226:227], v[66:67], 0, s[6:7]
	global_load_dwordx4 v[184:187], v[226:227], off
	global_load_dwordx4 v[188:191], v[226:227], off offset:1024
	s_mov_b64 s[6:7], 0xc502000
	v_lshl_add_u64 v[224:225], v[66:67], 0, s[6:7]
	global_load_dwordx4 v[192:195], v[224:225], off
	global_load_dwordx4 v[196:199], v[224:225], off offset:1024
	s_mov_b64 s[6:7], 0xc502800
	v_lshl_add_u64 v[226:227], v[66:67], 0, s[6:7]
	global_load_dwordx4 v[200:203], v[226:227], off
	global_load_dwordx4 v[204:207], v[226:227], off offset:1024
	s_mov_b64 s[6:7], 0xc503000
	v_lshl_add_u64 v[224:225], v[66:67], 0, s[6:7]
	global_load_dwordx4 v[208:211], v[224:225], off
	global_load_dwordx4 v[212:215], v[224:225], off offset:1024
	s_mov_b64 s[6:7], 0xc503800
	v_lshl_add_u64 v[226:227], v[66:67], 0, s[6:7]
	global_load_dwordx4 v[216:219], v[226:227], off
	global_load_dwordx4 v[220:223], v[226:227], off offset:1024
	s_waitcnt vmcnt(16)
	v_pk_add_f32 v[100:101], v[100:101], 1.0 op_sel_hi:[1,0]
	v_pk_add_f32 v[70:71], v[96:97], 1.0 op_sel_hi:[1,0]
	v_pk_add_f32 v[84:85], v[94:95], 1.0 op_sel_hi:[1,0]
	v_pk_add_f32 v[82:83], v[82:83], 1.0 op_sel_hi:[1,0]
	v_pk_add_f32 v[80:81], v[80:81], 1.0 op_sel_hi:[1,0]
	v_pk_add_f32 v[94:95], v[104:105], 1.0 op_sel_hi:[1,0]
	v_pk_add_f32 v[96:97], v[102:103], 1.0 op_sel_hi:[1,0]
	v_pk_add_f32 v[98:99], v[98:99], 1.0 op_sel_hi:[1,0]
	v_pk_mul_f32 v[70:71], v[74:75], v[70:71]
	v_pk_mul_f32 v[72:73], v[72:73], v[84:85]
	v_pk_mul_f32 v[74:75], v[78:79], v[82:83]
	v_pk_mul_f32 v[76:77], v[76:77], v[80:81]
	v_pk_mul_f32 v[78:79], v[112:113], v[94:95]
	v_pk_mul_f32 v[80:81], v[110:111], v[96:97]
	v_pk_mul_f32 v[82:83], v[108:109], v[100:101]
	v_pk_mul_f32 v[84:85], v[106:107], v[98:99]
	s_waitcnt vmcnt(14)
	v_lshlrev_b32_e32 v96, 16, v42
	v_and_b32_e32 v61, 0xffff0000, v42
	v_lshlrev_b32_e32 v98, 16, v43
	v_and_b32_e32 v99, 0xffff0000, v43
	v_lshlrev_b32_e32 v43, 16, v45
	v_lshlrev_b32_e32 v42, 16, v44
	v_and_b32_e32 v45, 0xffff0000, v45
	v_and_b32_e32 v44, 0xffff0000, v44
	v_lshlrev_b32_e32 v103, 16, v47
	v_lshlrev_b32_e32 v102, 16, v46
	v_and_b32_e32 v47, 0xffff0000, v47
	v_and_b32_e32 v46, 0xffff0000, v46
	v_lshlrev_b32_e32 v94, 16, v40
	v_and_b32_e32 v95, 0xffff0000, v40
	v_pk_mul_f32 v[100:101], v[44:45], v[44:45]
	v_pk_mul_f32 v[104:105], v[46:47], v[46:47]
	v_lshlrev_b32_e32 v108, 16, v41
	v_pk_fma_f32 v[100:101], v[42:43], v[42:43], v[100:101]
	v_pk_fma_f32 v[104:105], v[102:103], v[102:103], v[104:105]
	v_mul_f32_e32 v97, v94, v94
	v_mul_f32_e32 v107, v95, v95
	v_and_b32_e32 v109, 0xffff0000, v41
	v_mul_f32_e32 v40, v108, v108
	v_mov_b32_e32 v106, v96
	v_pk_add_f32 v[100:101], v[100:101], v[100:101] op_sel_hi:[0,1]
	v_pk_add_f32 v[104:105], v[104:105], v[104:105] op_sel_hi:[0,1]
	v_pk_fma_f32 v[40:41], v[108:109], v[108:109], v[40:41] op_sel_hi:[1,1,0]
	v_pk_add_f32 v[106:107], v[96:97], v[106:107]
	v_mul_f32_e32 v40, v61, v61
	v_mul_f32_e32 v100, v98, v98
	v_mul_f32_e32 v104, v99, v99
	v_mul_f32_e32 v110, v96, v96
	v_mov_b32_e32 v111, v107
	v_pk_add_f32 v[40:41], v[110:111], v[40:41]
	v_pk_add_f32 v[100:101], v[100:101], v[104:105]
	v_pk_add_f32 v[40:41], v[40:41], v[100:101]
	v_add_f32_e32 v40, v40, v41
	ds_bpermute_b32 v41, v51, v40
	s_waitcnt lgkmcnt(0)
	v_add_f32_e32 v40, v40, v41
	ds_bpermute_b32 v41, v87, v40
	s_waitcnt lgkmcnt(0)
	v_add_f32_e32 v40, v40, v41
	ds_bpermute_b32 v41, v88, v40
	s_waitcnt lgkmcnt(0)
	v_add_f32_e32 v40, v40, v41
	ds_bpermute_b32 v41, v89, v40
	s_waitcnt lgkmcnt(0)
	v_add_f32_e32 v40, v40, v41
	ds_bpermute_b32 v41, v90, v40
	s_waitcnt lgkmcnt(0)
	v_add_f32_e32 v40, v40, v41
	ds_bpermute_b32 v41, v91, v40
	s_waitcnt lgkmcnt(0)
	v_add_f32_e32 v40, v40, v41
	v_fmamk_f32 v40, v40, 0x3a800000, v49
	v_mul_f32_e32 v41, 0x4f800000, v40
	v_cmp_gt_f32_e32 vcc, s8, v40
	s_nop 1
	v_cndmask_b32_e32 v40, v40, v41, vcc
	v_sqrt_f32_e32 v41, v40
	s_nop 0
	v_add_u32_e32 v97, -1, v41
	v_fma_f32 v100, -v97, v41, v40
	v_cmp_ge_f32_e64 s[0:1], 0, v100
	v_add_u32_e32 v100, 1, v41
	s_nop 0
	v_cndmask_b32_e64 v97, v41, v97, s[0:1]
	v_fma_f32 v41, -v100, v41, v40
	v_cmp_lt_f32_e64 s[0:1], 0, v41
	s_nop 1
	v_cndmask_b32_e64 v41, v97, v100, s[0:1]
	v_mul_f32_e32 v97, 0x37800000, v41
	v_cndmask_b32_e32 v41, v41, v97, vcc
	v_cmp_class_f32_e32 vcc, v40, v92
	s_nop 1
	v_cndmask_b32_e32 v40, v41, v40, vcc
	v_div_scale_f32 v41, s[0:1], v40, v40, 1.0
	v_rcp_f32_e32 v97, v41
	s_nop 0
	v_fma_f32 v100, -v41, v97, 1.0
	v_fmac_f32_e32 v97, v100, v97
	v_div_scale_f32 v100, vcc, 1.0, v40, 1.0
	v_mul_f32_e32 v101, v100, v97
	v_fma_f32 v104, -v41, v101, v100
	v_fmac_f32_e32 v101, v104, v97
	v_fma_f32 v41, -v41, v101, v100
	v_div_fmas_f32 v41, v41, v97, v101
	v_div_fixup_f32 v100, v41, v40, 1.0
	v_mov_b32_e32 v40, v42
	v_mov_b32_e32 v41, v44
	v_mov_b32_e32 v44, v43
	v_pk_mul_f32 v[40:41], v[100:101], v[40:41] op_sel_hi:[0,1]
	v_pk_mul_f32 v[42:43], v[100:101], v[44:45] op_sel_hi:[0,1]
	v_mov_b32_e32 v44, v102
	v_mov_b32_e32 v45, v46
	v_mov_b32_e32 v46, v103
	v_pk_fma_f32 v[42:43], v[70:71], v[42:43], v[22:23]
	v_pk_fma_f32 v[40:41], v[72:73], v[40:41], v[20:21]
	v_pk_mul_f32 v[44:45], v[100:101], v[44:45] op_sel_hi:[0,1]
	v_pk_mul_f32 v[46:47], v[100:101], v[46:47] op_sel_hi:[0,1]
	s_mov_b64 s[6:7], 0x0
	v_lshl_add_u64 v[104:105], s[6:7], 1, v[68:69]
	v_pk_fma_f32 v[46:47], v[74:75], v[46:47], v[18:19]
	v_pk_fma_f32 v[44:45], v[76:77], v[44:45], v[16:17]
	v_cvt_pk_bf16_f32 v40, v40, v41
	v_cvt_pk_bf16_f32 v41, v42, v43
	v_mov_b32_e32 v97, v61
	v_cvt_pk_bf16_f32 v42, v44, v45
	v_cvt_pk_bf16_f32 v43, v46, v47
	global_store_dwordx4 v[104:105], v[40:43], off
	v_pk_mul_f32 v[44:45], v[96:97], v[100:101] op_sel_hi:[1,0]
	v_pk_mul_f32 v[46:47], v[98:99], v[100:101] op_sel_hi:[1,0]
	v_pk_mul_f32 v[40:41], v[94:95], v[100:101] op_sel_hi:[1,0]
	v_pk_mul_f32 v[42:43], v[108:109], v[100:101] op_sel_hi:[1,0]
	v_pk_fma_f32 v[40:41], v[80:81], v[40:41], v[28:29]
	v_pk_fma_f32 v[42:43], v[78:79], v[42:43], v[30:31]
	v_pk_fma_f32 v[46:47], v[82:83], v[46:47], v[26:27]
	v_pk_fma_f32 v[44:45], v[84:85], v[44:45], v[24:25]
	v_cvt_pk_bf16_f32 v40, v40, v41
	v_cvt_pk_bf16_f32 v41, v42, v43
	s_nop 0
	v_cvt_pk_bf16_f32 v42, v44, v45
	v_cvt_pk_bf16_f32 v43, v46, v47
	global_store_dwordx4 v[104:105], v[40:43], off offset:1024
	s_nop 0
	s_nop 0
	s_nop 0
	s_nop 0
	s_nop 0
	s_nop 0
	s_nop 0
	s_nop 0
	s_waitcnt vmcnt(14)
	v_lshlrev_b32_e32 v96, 16, v38
	v_and_b32_e32 v61, 0xffff0000, v38
	v_lshlrev_b32_e32 v98, 16, v39
	v_and_b32_e32 v99, 0xffff0000, v39
	v_lshlrev_b32_e32 v39, 16, v33
	v_lshlrev_b32_e32 v38, 16, v32
	v_and_b32_e32 v33, 0xffff0000, v33
	v_and_b32_e32 v32, 0xffff0000, v32
	v_lshlrev_b32_e32 v103, 16, v35
	v_lshlrev_b32_e32 v102, 16, v34
	v_and_b32_e32 v35, 0xffff0000, v35
	v_and_b32_e32 v34, 0xffff0000, v34
	v_lshlrev_b32_e32 v94, 16, v36
	v_and_b32_e32 v95, 0xffff0000, v36
	v_pk_mul_f32 v[100:101], v[32:33], v[32:33]
	v_pk_mul_f32 v[104:105], v[34:35], v[34:35]
	v_lshlrev_b32_e32 v108, 16, v37
	v_pk_fma_f32 v[100:101], v[38:39], v[38:39], v[100:101]
	v_pk_fma_f32 v[104:105], v[102:103], v[102:103], v[104:105]
	v_mul_f32_e32 v97, v94, v94
	v_mul_f32_e32 v107, v95, v95
	v_and_b32_e32 v109, 0xffff0000, v37
	v_mul_f32_e32 v36, v108, v108
	v_mov_b32_e32 v106, v96
	v_pk_add_f32 v[100:101], v[100:101], v[100:101] op_sel_hi:[0,1]
	v_pk_add_f32 v[104:105], v[104:105], v[104:105] op_sel_hi:[0,1]
	v_pk_fma_f32 v[36:37], v[108:109], v[108:109], v[36:37] op_sel_hi:[1,1,0]
	v_pk_add_f32 v[106:107], v[96:97], v[106:107]
	v_mul_f32_e32 v36, v61, v61
	v_mul_f32_e32 v100, v98, v98
	v_mul_f32_e32 v104, v99, v99
	v_mul_f32_e32 v110, v96, v96
	v_mov_b32_e32 v111, v107
	v_pk_add_f32 v[36:37], v[110:111], v[36:37]
	v_pk_add_f32 v[100:101], v[100:101], v[104:105]
	v_pk_add_f32 v[36:37], v[36:37], v[100:101]
	v_add_f32_e32 v36, v36, v37
	ds_bpermute_b32 v37, v51, v36
	s_waitcnt lgkmcnt(0)
	v_add_f32_e32 v36, v36, v37
	ds_bpermute_b32 v37, v87, v36
	s_waitcnt lgkmcnt(0)
	v_add_f32_e32 v36, v36, v37
	ds_bpermute_b32 v37, v88, v36
	s_waitcnt lgkmcnt(0)
	v_add_f32_e32 v36, v36, v37
	ds_bpermute_b32 v37, v89, v36
	s_waitcnt lgkmcnt(0)
	v_add_f32_e32 v36, v36, v37
	ds_bpermute_b32 v37, v90, v36
	s_waitcnt lgkmcnt(0)
	v_add_f32_e32 v36, v36, v37
	ds_bpermute_b32 v37, v91, v36
	s_waitcnt lgkmcnt(0)
	v_add_f32_e32 v36, v36, v37
	v_fmamk_f32 v36, v36, 0x3a800000, v49
	v_mul_f32_e32 v37, 0x4f800000, v36
	v_cmp_gt_f32_e32 vcc, s8, v36
	s_nop 1
	v_cndmask_b32_e32 v36, v36, v37, vcc
	v_sqrt_f32_e32 v37, v36
	s_nop 0
	v_add_u32_e32 v97, -1, v37
	v_fma_f32 v100, -v97, v37, v36
	v_cmp_ge_f32_e64 s[0:1], 0, v100
	v_add_u32_e32 v100, 1, v37
	s_nop 0
	v_cndmask_b32_e64 v97, v37, v97, s[0:1]
	v_fma_f32 v37, -v100, v37, v36
	v_cmp_lt_f32_e64 s[0:1], 0, v37
	s_nop 1
	v_cndmask_b32_e64 v37, v97, v100, s[0:1]
	v_mul_f32_e32 v97, 0x37800000, v37
	v_cndmask_b32_e32 v37, v37, v97, vcc
	v_cmp_class_f32_e32 vcc, v36, v92
	s_nop 1
	v_cndmask_b32_e32 v36, v37, v36, vcc
	v_div_scale_f32 v37, s[0:1], v36, v36, 1.0
	v_rcp_f32_e32 v97, v37
	s_nop 0
	v_fma_f32 v100, -v37, v97, 1.0
	v_fmac_f32_e32 v97, v100, v97
	v_div_scale_f32 v100, vcc, 1.0, v36, 1.0
	v_mul_f32_e32 v101, v100, v97
	v_fma_f32 v104, -v37, v101, v100
	v_fmac_f32_e32 v101, v104, v97
	v_fma_f32 v37, -v37, v101, v100
	v_div_fmas_f32 v37, v37, v97, v101
	v_div_fixup_f32 v100, v37, v36, 1.0
	v_mov_b32_e32 v36, v38
	v_mov_b32_e32 v37, v32
	v_mov_b32_e32 v32, v39
	v_pk_mul_f32 v[36:37], v[100:101], v[36:37] op_sel_hi:[0,1]
	v_pk_mul_f32 v[38:39], v[100:101], v[32:33] op_sel_hi:[0,1]
	v_mov_b32_e32 v32, v102
	v_mov_b32_e32 v33, v34
	v_mov_b32_e32 v34, v103
	v_pk_fma_f32 v[38:39], v[70:71], v[38:39], v[22:23]
	v_pk_fma_f32 v[36:37], v[72:73], v[36:37], v[20:21]
	v_pk_mul_f32 v[32:33], v[100:101], v[32:33] op_sel_hi:[0,1]
	v_pk_mul_f32 v[34:35], v[100:101], v[34:35] op_sel_hi:[0,1]
	s_mov_b64 s[6:7], 0x400
	v_lshl_add_u64 v[104:105], s[6:7], 1, v[68:69]
	v_pk_fma_f32 v[34:35], v[74:75], v[34:35], v[18:19]
	v_pk_fma_f32 v[32:33], v[76:77], v[32:33], v[16:17]
	v_cvt_pk_bf16_f32 v36, v36, v37
	v_cvt_pk_bf16_f32 v37, v38, v39
	v_mov_b32_e32 v97, v61
	v_cvt_pk_bf16_f32 v38, v32, v33
	v_cvt_pk_bf16_f32 v39, v34, v35
	global_store_dwordx4 v[104:105], v[36:39], off
	v_pk_mul_f32 v[32:33], v[96:97], v[100:101] op_sel_hi:[1,0]
	v_pk_mul_f32 v[34:35], v[98:99], v[100:101] op_sel_hi:[1,0]
	v_pk_mul_f32 v[36:37], v[94:95], v[100:101] op_sel_hi:[1,0]
	v_pk_mul_f32 v[38:39], v[108:109], v[100:101] op_sel_hi:[1,0]
	v_pk_fma_f32 v[36:37], v[80:81], v[36:37], v[28:29]
	v_pk_fma_f32 v[38:39], v[78:79], v[38:39], v[30:31]
	v_pk_fma_f32 v[34:35], v[82:83], v[34:35], v[26:27]
	v_pk_fma_f32 v[32:33], v[84:85], v[32:33], v[24:25]
	v_cvt_pk_bf16_f32 v36, v36, v37
	v_cvt_pk_bf16_f32 v37, v38, v39
	s_nop 0
	v_cvt_pk_bf16_f32 v38, v32, v33
	v_cvt_pk_bf16_f32 v39, v34, v35
	global_store_dwordx4 v[104:105], v[36:39], off offset:1024
	s_nop 0
	s_nop 0
	s_nop 0
	s_nop 0
	s_nop 0
	s_nop 0
	s_nop 0
	s_nop 0
	s_waitcnt vmcnt(14)
	v_lshlrev_b32_e32 v96, 16, v182
	v_and_b32_e32 v61, 0xffff0000, v182
	v_lshlrev_b32_e32 v98, 16, v183
	v_and_b32_e32 v99, 0xffff0000, v183
	v_lshlrev_b32_e32 v183, 16, v177
	v_lshlrev_b32_e32 v182, 16, v176
	v_and_b32_e32 v177, 0xffff0000, v177
	v_and_b32_e32 v176, 0xffff0000, v176
	v_lshlrev_b32_e32 v103, 16, v179
	v_lshlrev_b32_e32 v102, 16, v178
	v_and_b32_e32 v179, 0xffff0000, v179
	v_and_b32_e32 v178, 0xffff0000, v178
	v_lshlrev_b32_e32 v94, 16, v180
	v_and_b32_e32 v95, 0xffff0000, v180
	v_pk_mul_f32 v[100:101], v[176:177], v[176:177]
	v_pk_mul_f32 v[104:105], v[178:179], v[178:179]
	v_lshlrev_b32_e32 v108, 16, v181
	v_pk_fma_f32 v[100:101], v[182:183], v[182:183], v[100:101]
	v_pk_fma_f32 v[104:105], v[102:103], v[102:103], v[104:105]
	v_mul_f32_e32 v97, v94, v94
	v_mul_f32_e32 v107, v95, v95
	v_and_b32_e32 v109, 0xffff0000, v181
	v_mul_f32_e32 v180, v108, v108
	v_mov_b32_e32 v106, v96
	v_pk_add_f32 v[100:101], v[100:101], v[100:101] op_sel_hi:[0,1]
	v_pk_add_f32 v[104:105], v[104:105], v[104:105] op_sel_hi:[0,1]
	v_pk_fma_f32 v[180:181], v[108:109], v[108:109], v[180:181] op_sel_hi:[1,1,0]
	v_pk_add_f32 v[106:107], v[96:97], v[106:107]
	v_mul_f32_e32 v180, v61, v61
	v_mul_f32_e32 v100, v98, v98
	v_mul_f32_e32 v104, v99, v99
	v_mul_f32_e32 v110, v96, v96
	v_mov_b32_e32 v111, v107
	v_pk_add_f32 v[180:181], v[110:111], v[180:181]
	v_pk_add_f32 v[100:101], v[100:101], v[104:105]
	v_pk_add_f32 v[180:181], v[180:181], v[100:101]
	v_add_f32_e32 v180, v180, v181
	ds_bpermute_b32 v181, v51, v180
	s_waitcnt lgkmcnt(0)
	v_add_f32_e32 v180, v180, v181
	ds_bpermute_b32 v181, v87, v180
	s_waitcnt lgkmcnt(0)
	v_add_f32_e32 v180, v180, v181
	ds_bpermute_b32 v181, v88, v180
	s_waitcnt lgkmcnt(0)
	v_add_f32_e32 v180, v180, v181
	ds_bpermute_b32 v181, v89, v180
	s_waitcnt lgkmcnt(0)
	v_add_f32_e32 v180, v180, v181
	ds_bpermute_b32 v181, v90, v180
	s_waitcnt lgkmcnt(0)
	v_add_f32_e32 v180, v180, v181
	ds_bpermute_b32 v181, v91, v180
	s_waitcnt lgkmcnt(0)
	v_add_f32_e32 v180, v180, v181
	v_fmamk_f32 v180, v180, 0x3a800000, v49
	v_mul_f32_e32 v181, 0x4f800000, v180
	v_cmp_gt_f32_e32 vcc, s8, v180
	s_nop 1
	v_cndmask_b32_e32 v180, v180, v181, vcc
	v_sqrt_f32_e32 v181, v180
	s_nop 0
	v_add_u32_e32 v97, -1, v181
	v_fma_f32 v100, -v97, v181, v180
	v_cmp_ge_f32_e64 s[0:1], 0, v100
	v_add_u32_e32 v100, 1, v181
	s_nop 0
	v_cndmask_b32_e64 v97, v181, v97, s[0:1]
	v_fma_f32 v181, -v100, v181, v180
	v_cmp_lt_f32_e64 s[0:1], 0, v181
	s_nop 1
	v_cndmask_b32_e64 v181, v97, v100, s[0:1]
	v_mul_f32_e32 v97, 0x37800000, v181
	v_cndmask_b32_e32 v181, v181, v97, vcc
	v_cmp_class_f32_e32 vcc, v180, v92
	s_nop 1
	v_cndmask_b32_e32 v180, v181, v180, vcc
	v_div_scale_f32 v181, s[0:1], v180, v180, 1.0
	v_rcp_f32_e32 v97, v181
	s_nop 0
	v_fma_f32 v100, -v181, v97, 1.0
	v_fmac_f32_e32 v97, v100, v97
	v_div_scale_f32 v100, vcc, 1.0, v180, 1.0
	v_mul_f32_e32 v101, v100, v97
	v_fma_f32 v104, -v181, v101, v100
	v_fmac_f32_e32 v101, v104, v97
	v_fma_f32 v181, -v181, v101, v100
	v_div_fmas_f32 v181, v181, v97, v101
	v_div_fixup_f32 v100, v181, v180, 1.0
	v_mov_b32_e32 v180, v182
	v_mov_b32_e32 v181, v176
	v_mov_b32_e32 v176, v183
	v_pk_mul_f32 v[180:181], v[100:101], v[180:181] op_sel_hi:[0,1]
	v_pk_mul_f32 v[182:183], v[100:101], v[176:177] op_sel_hi:[0,1]
	v_mov_b32_e32 v176, v102
	v_mov_b32_e32 v177, v178
	v_mov_b32_e32 v178, v103
	v_pk_fma_f32 v[182:183], v[70:71], v[182:183], v[22:23]
	v_pk_fma_f32 v[180:181], v[72:73], v[180:181], v[20:21]
	v_pk_mul_f32 v[176:177], v[100:101], v[176:177] op_sel_hi:[0,1]
	v_pk_mul_f32 v[178:179], v[100:101], v[178:179] op_sel_hi:[0,1]
	s_mov_b64 s[6:7], 0x800
	v_lshl_add_u64 v[104:105], s[6:7], 1, v[68:69]
	v_pk_fma_f32 v[178:179], v[74:75], v[178:179], v[18:19]
	v_pk_fma_f32 v[176:177], v[76:77], v[176:177], v[16:17]
	v_cvt_pk_bf16_f32 v180, v180, v181
	v_cvt_pk_bf16_f32 v181, v182, v183
	v_mov_b32_e32 v97, v61
	v_cvt_pk_bf16_f32 v182, v176, v177
	v_cvt_pk_bf16_f32 v183, v178, v179
	global_store_dwordx4 v[104:105], v[180:183], off
	v_pk_mul_f32 v[176:177], v[96:97], v[100:101] op_sel_hi:[1,0]
	v_pk_mul_f32 v[178:179], v[98:99], v[100:101] op_sel_hi:[1,0]
	v_pk_mul_f32 v[180:181], v[94:95], v[100:101] op_sel_hi:[1,0]
	v_pk_mul_f32 v[182:183], v[108:109], v[100:101] op_sel_hi:[1,0]
	v_pk_fma_f32 v[180:181], v[80:81], v[180:181], v[28:29]
	v_pk_fma_f32 v[182:183], v[78:79], v[182:183], v[30:31]
	v_pk_fma_f32 v[178:179], v[82:83], v[178:179], v[26:27]
	v_pk_fma_f32 v[176:177], v[84:85], v[176:177], v[24:25]
	v_cvt_pk_bf16_f32 v180, v180, v181
	v_cvt_pk_bf16_f32 v181, v182, v183
	s_nop 0
	v_cvt_pk_bf16_f32 v182, v176, v177
	v_cvt_pk_bf16_f32 v183, v178, v179
	global_store_dwordx4 v[104:105], v[180:183], off offset:1024
	s_nop 0
	s_nop 0
	s_nop 0
	s_nop 0
	s_nop 0
	s_nop 0
	s_nop 0
	s_nop 0
	s_waitcnt vmcnt(14)
	v_lshlrev_b32_e32 v96, 16, v190
	v_and_b32_e32 v61, 0xffff0000, v190
	v_lshlrev_b32_e32 v98, 16, v191
	v_and_b32_e32 v99, 0xffff0000, v191
	v_lshlrev_b32_e32 v191, 16, v185
	v_lshlrev_b32_e32 v190, 16, v184
	v_and_b32_e32 v185, 0xffff0000, v185
	v_and_b32_e32 v184, 0xffff0000, v184
	v_lshlrev_b32_e32 v103, 16, v187
	v_lshlrev_b32_e32 v102, 16, v186
	v_and_b32_e32 v187, 0xffff0000, v187
	v_and_b32_e32 v186, 0xffff0000, v186
	v_lshlrev_b32_e32 v94, 16, v188
	v_and_b32_e32 v95, 0xffff0000, v188
	v_pk_mul_f32 v[100:101], v[184:185], v[184:185]
	v_pk_mul_f32 v[104:105], v[186:187], v[186:187]
	v_lshlrev_b32_e32 v108, 16, v189
	v_pk_fma_f32 v[100:101], v[190:191], v[190:191], v[100:101]
	v_pk_fma_f32 v[104:105], v[102:103], v[102:103], v[104:105]
	v_mul_f32_e32 v97, v94, v94
	v_mul_f32_e32 v107, v95, v95
	v_and_b32_e32 v109, 0xffff0000, v189
	v_mul_f32_e32 v188, v108, v108
	v_mov_b32_e32 v106, v96
	v_pk_add_f32 v[100:101], v[100:101], v[100:101] op_sel_hi:[0,1]
	v_pk_add_f32 v[104:105], v[104:105], v[104:105] op_sel_hi:[0,1]
	v_pk_fma_f32 v[188:189], v[108:109], v[108:109], v[188:189] op_sel_hi:[1,1,0]
	v_pk_add_f32 v[106:107], v[96:97], v[106:107]
	v_mul_f32_e32 v188, v61, v61
	v_mul_f32_e32 v100, v98, v98
	v_mul_f32_e32 v104, v99, v99
	v_mul_f32_e32 v110, v96, v96
	v_mov_b32_e32 v111, v107
	v_pk_add_f32 v[188:189], v[110:111], v[188:189]
	v_pk_add_f32 v[100:101], v[100:101], v[104:105]
	v_pk_add_f32 v[188:189], v[188:189], v[100:101]
	v_add_f32_e32 v188, v188, v189
	ds_bpermute_b32 v189, v51, v188
	s_waitcnt lgkmcnt(0)
	v_add_f32_e32 v188, v188, v189
	ds_bpermute_b32 v189, v87, v188
	s_waitcnt lgkmcnt(0)
	v_add_f32_e32 v188, v188, v189
	ds_bpermute_b32 v189, v88, v188
	s_waitcnt lgkmcnt(0)
	v_add_f32_e32 v188, v188, v189
	ds_bpermute_b32 v189, v89, v188
	s_waitcnt lgkmcnt(0)
	v_add_f32_e32 v188, v188, v189
	ds_bpermute_b32 v189, v90, v188
	s_waitcnt lgkmcnt(0)
	v_add_f32_e32 v188, v188, v189
	ds_bpermute_b32 v189, v91, v188
	s_waitcnt lgkmcnt(0)
	v_add_f32_e32 v188, v188, v189
	v_fmamk_f32 v188, v188, 0x3a800000, v49
	v_mul_f32_e32 v189, 0x4f800000, v188
	v_cmp_gt_f32_e32 vcc, s8, v188
	s_nop 1
	v_cndmask_b32_e32 v188, v188, v189, vcc
	v_sqrt_f32_e32 v189, v188
	s_nop 0
	v_add_u32_e32 v97, -1, v189
	v_fma_f32 v100, -v97, v189, v188
	v_cmp_ge_f32_e64 s[0:1], 0, v100
	v_add_u32_e32 v100, 1, v189
	s_nop 0
	v_cndmask_b32_e64 v97, v189, v97, s[0:1]
	v_fma_f32 v189, -v100, v189, v188
	v_cmp_lt_f32_e64 s[0:1], 0, v189
	s_nop 1
	v_cndmask_b32_e64 v189, v97, v100, s[0:1]
	v_mul_f32_e32 v97, 0x37800000, v189
	v_cndmask_b32_e32 v189, v189, v97, vcc
	v_cmp_class_f32_e32 vcc, v188, v92
	s_nop 1
	v_cndmask_b32_e32 v188, v189, v188, vcc
	v_div_scale_f32 v189, s[0:1], v188, v188, 1.0
	v_rcp_f32_e32 v97, v189
	s_nop 0
	v_fma_f32 v100, -v189, v97, 1.0
	v_fmac_f32_e32 v97, v100, v97
	v_div_scale_f32 v100, vcc, 1.0, v188, 1.0
	v_mul_f32_e32 v101, v100, v97
	v_fma_f32 v104, -v189, v101, v100
	v_fmac_f32_e32 v101, v104, v97
	v_fma_f32 v189, -v189, v101, v100
	v_div_fmas_f32 v189, v189, v97, v101
	v_div_fixup_f32 v100, v189, v188, 1.0
	v_mov_b32_e32 v188, v190
	v_mov_b32_e32 v189, v184
	v_mov_b32_e32 v184, v191
	v_pk_mul_f32 v[188:189], v[100:101], v[188:189] op_sel_hi:[0,1]
	v_pk_mul_f32 v[190:191], v[100:101], v[184:185] op_sel_hi:[0,1]
	v_mov_b32_e32 v184, v102
	v_mov_b32_e32 v185, v186
	v_mov_b32_e32 v186, v103
	v_pk_fma_f32 v[190:191], v[70:71], v[190:191], v[22:23]
	v_pk_fma_f32 v[188:189], v[72:73], v[188:189], v[20:21]
	v_pk_mul_f32 v[184:185], v[100:101], v[184:185] op_sel_hi:[0,1]
	v_pk_mul_f32 v[186:187], v[100:101], v[186:187] op_sel_hi:[0,1]
	s_mov_b64 s[6:7], 0xc00
	v_lshl_add_u64 v[104:105], s[6:7], 1, v[68:69]
	v_pk_fma_f32 v[186:187], v[74:75], v[186:187], v[18:19]
	v_pk_fma_f32 v[184:185], v[76:77], v[184:185], v[16:17]
	v_cvt_pk_bf16_f32 v188, v188, v189
	v_cvt_pk_bf16_f32 v189, v190, v191
	v_mov_b32_e32 v97, v61
	v_cvt_pk_bf16_f32 v190, v184, v185
	v_cvt_pk_bf16_f32 v191, v186, v187
	global_store_dwordx4 v[104:105], v[188:191], off
	v_pk_mul_f32 v[184:185], v[96:97], v[100:101] op_sel_hi:[1,0]
	v_pk_mul_f32 v[186:187], v[98:99], v[100:101] op_sel_hi:[1,0]
	v_pk_mul_f32 v[188:189], v[94:95], v[100:101] op_sel_hi:[1,0]
	v_pk_mul_f32 v[190:191], v[108:109], v[100:101] op_sel_hi:[1,0]
	v_pk_fma_f32 v[188:189], v[80:81], v[188:189], v[28:29]
	v_pk_fma_f32 v[190:191], v[78:79], v[190:191], v[30:31]
	v_pk_fma_f32 v[186:187], v[82:83], v[186:187], v[26:27]
	v_pk_fma_f32 v[184:185], v[84:85], v[184:185], v[24:25]
	v_cvt_pk_bf16_f32 v188, v188, v189
	v_cvt_pk_bf16_f32 v189, v190, v191
	s_nop 0
	v_cvt_pk_bf16_f32 v190, v184, v185
	v_cvt_pk_bf16_f32 v191, v186, v187
	global_store_dwordx4 v[104:105], v[188:191], off offset:1024
	s_nop 0
	s_nop 0
	s_nop 0
	s_nop 0
	s_nop 0
	s_nop 0
	s_nop 0
	s_nop 0
	s_waitcnt vmcnt(14)
	v_lshlrev_b32_e32 v96, 16, v198
	v_and_b32_e32 v61, 0xffff0000, v198
	v_lshlrev_b32_e32 v98, 16, v199
	v_and_b32_e32 v99, 0xffff0000, v199
	v_lshlrev_b32_e32 v199, 16, v193
	v_lshlrev_b32_e32 v198, 16, v192
	v_and_b32_e32 v193, 0xffff0000, v193
	v_and_b32_e32 v192, 0xffff0000, v192
	v_lshlrev_b32_e32 v103, 16, v195
	v_lshlrev_b32_e32 v102, 16, v194
	v_and_b32_e32 v195, 0xffff0000, v195
	v_and_b32_e32 v194, 0xffff0000, v194
	v_lshlrev_b32_e32 v94, 16, v196
	v_and_b32_e32 v95, 0xffff0000, v196
	v_pk_mul_f32 v[100:101], v[192:193], v[192:193]
	v_pk_mul_f32 v[104:105], v[194:195], v[194:195]
	v_lshlrev_b32_e32 v108, 16, v197
	v_pk_fma_f32 v[100:101], v[198:199], v[198:199], v[100:101]
	v_pk_fma_f32 v[104:105], v[102:103], v[102:103], v[104:105]
	v_mul_f32_e32 v97, v94, v94
	v_mul_f32_e32 v107, v95, v95
	v_and_b32_e32 v109, 0xffff0000, v197
	v_mul_f32_e32 v196, v108, v108
	v_mov_b32_e32 v106, v96
	v_pk_add_f32 v[100:101], v[100:101], v[100:101] op_sel_hi:[0,1]
	v_pk_add_f32 v[104:105], v[104:105], v[104:105] op_sel_hi:[0,1]
	v_pk_fma_f32 v[196:197], v[108:109], v[108:109], v[196:197] op_sel_hi:[1,1,0]
	v_pk_add_f32 v[106:107], v[96:97], v[106:107]
	v_mul_f32_e32 v196, v61, v61
	v_mul_f32_e32 v100, v98, v98
	v_mul_f32_e32 v104, v99, v99
	v_mul_f32_e32 v110, v96, v96
	v_mov_b32_e32 v111, v107
	v_pk_add_f32 v[196:197], v[110:111], v[196:197]
	v_pk_add_f32 v[100:101], v[100:101], v[104:105]
	v_pk_add_f32 v[196:197], v[196:197], v[100:101]
	v_add_f32_e32 v196, v196, v197
	ds_bpermute_b32 v197, v51, v196
	s_waitcnt lgkmcnt(0)
	v_add_f32_e32 v196, v196, v197
	ds_bpermute_b32 v197, v87, v196
	s_waitcnt lgkmcnt(0)
	v_add_f32_e32 v196, v196, v197
	ds_bpermute_b32 v197, v88, v196
	s_waitcnt lgkmcnt(0)
	v_add_f32_e32 v196, v196, v197
	ds_bpermute_b32 v197, v89, v196
	s_waitcnt lgkmcnt(0)
	v_add_f32_e32 v196, v196, v197
	ds_bpermute_b32 v197, v90, v196
	s_waitcnt lgkmcnt(0)
	v_add_f32_e32 v196, v196, v197
	ds_bpermute_b32 v197, v91, v196
	s_waitcnt lgkmcnt(0)
	v_add_f32_e32 v196, v196, v197
	v_fmamk_f32 v196, v196, 0x3a800000, v49
	v_mul_f32_e32 v197, 0x4f800000, v196
	v_cmp_gt_f32_e32 vcc, s8, v196
	s_nop 1
	v_cndmask_b32_e32 v196, v196, v197, vcc
	v_sqrt_f32_e32 v197, v196
	s_nop 0
	v_add_u32_e32 v97, -1, v197
	v_fma_f32 v100, -v97, v197, v196
	v_cmp_ge_f32_e64 s[0:1], 0, v100
	v_add_u32_e32 v100, 1, v197
	s_nop 0
	v_cndmask_b32_e64 v97, v197, v97, s[0:1]
	v_fma_f32 v197, -v100, v197, v196
	v_cmp_lt_f32_e64 s[0:1], 0, v197
	s_nop 1
	v_cndmask_b32_e64 v197, v97, v100, s[0:1]
	v_mul_f32_e32 v97, 0x37800000, v197
	v_cndmask_b32_e32 v197, v197, v97, vcc
	v_cmp_class_f32_e32 vcc, v196, v92
	s_nop 1
	v_cndmask_b32_e32 v196, v197, v196, vcc
	v_div_scale_f32 v197, s[0:1], v196, v196, 1.0
	v_rcp_f32_e32 v97, v197
	s_nop 0
	v_fma_f32 v100, -v197, v97, 1.0
	v_fmac_f32_e32 v97, v100, v97
	v_div_scale_f32 v100, vcc, 1.0, v196, 1.0
	v_mul_f32_e32 v101, v100, v97
	v_fma_f32 v104, -v197, v101, v100
	v_fmac_f32_e32 v101, v104, v97
	v_fma_f32 v197, -v197, v101, v100
	v_div_fmas_f32 v197, v197, v97, v101
	v_div_fixup_f32 v100, v197, v196, 1.0
	v_mov_b32_e32 v196, v198
	v_mov_b32_e32 v197, v192
	v_mov_b32_e32 v192, v199
	v_pk_mul_f32 v[196:197], v[100:101], v[196:197] op_sel_hi:[0,1]
	v_pk_mul_f32 v[198:199], v[100:101], v[192:193] op_sel_hi:[0,1]
	v_mov_b32_e32 v192, v102
	v_mov_b32_e32 v193, v194
	v_mov_b32_e32 v194, v103
	v_pk_fma_f32 v[198:199], v[70:71], v[198:199], v[22:23]
	v_pk_fma_f32 v[196:197], v[72:73], v[196:197], v[20:21]
	v_pk_mul_f32 v[192:193], v[100:101], v[192:193] op_sel_hi:[0,1]
	v_pk_mul_f32 v[194:195], v[100:101], v[194:195] op_sel_hi:[0,1]
	s_mov_b64 s[6:7], 0x1000
	v_lshl_add_u64 v[104:105], s[6:7], 1, v[68:69]
	v_pk_fma_f32 v[194:195], v[74:75], v[194:195], v[18:19]
	v_pk_fma_f32 v[192:193], v[76:77], v[192:193], v[16:17]
	v_cvt_pk_bf16_f32 v196, v196, v197
	v_cvt_pk_bf16_f32 v197, v198, v199
	v_mov_b32_e32 v97, v61
	v_cvt_pk_bf16_f32 v198, v192, v193
	v_cvt_pk_bf16_f32 v199, v194, v195
	global_store_dwordx4 v[104:105], v[196:199], off
	v_pk_mul_f32 v[192:193], v[96:97], v[100:101] op_sel_hi:[1,0]
	v_pk_mul_f32 v[194:195], v[98:99], v[100:101] op_sel_hi:[1,0]
	v_pk_mul_f32 v[196:197], v[94:95], v[100:101] op_sel_hi:[1,0]
	v_pk_mul_f32 v[198:199], v[108:109], v[100:101] op_sel_hi:[1,0]
	v_pk_fma_f32 v[196:197], v[80:81], v[196:197], v[28:29]
	v_pk_fma_f32 v[198:199], v[78:79], v[198:199], v[30:31]
	v_pk_fma_f32 v[194:195], v[82:83], v[194:195], v[26:27]
	v_pk_fma_f32 v[192:193], v[84:85], v[192:193], v[24:25]
	v_cvt_pk_bf16_f32 v196, v196, v197
	v_cvt_pk_bf16_f32 v197, v198, v199
	s_nop 0
	v_cvt_pk_bf16_f32 v198, v192, v193
	v_cvt_pk_bf16_f32 v199, v194, v195
	global_store_dwordx4 v[104:105], v[196:199], off offset:1024
	s_nop 0
	s_nop 0
	s_nop 0
	s_nop 0
	s_nop 0
	s_nop 0
	s_nop 0
	s_nop 0
	s_waitcnt vmcnt(14)
	v_lshlrev_b32_e32 v96, 16, v206
	v_and_b32_e32 v61, 0xffff0000, v206
	v_lshlrev_b32_e32 v98, 16, v207
	v_and_b32_e32 v99, 0xffff0000, v207
	v_lshlrev_b32_e32 v207, 16, v201
	v_lshlrev_b32_e32 v206, 16, v200
	v_and_b32_e32 v201, 0xffff0000, v201
	v_and_b32_e32 v200, 0xffff0000, v200
	v_lshlrev_b32_e32 v103, 16, v203
	v_lshlrev_b32_e32 v102, 16, v202
	v_and_b32_e32 v203, 0xffff0000, v203
	v_and_b32_e32 v202, 0xffff0000, v202
	v_lshlrev_b32_e32 v94, 16, v204
	v_and_b32_e32 v95, 0xffff0000, v204
	v_pk_mul_f32 v[100:101], v[200:201], v[200:201]
	v_pk_mul_f32 v[104:105], v[202:203], v[202:203]
	v_lshlrev_b32_e32 v108, 16, v205
	v_pk_fma_f32 v[100:101], v[206:207], v[206:207], v[100:101]
	v_pk_fma_f32 v[104:105], v[102:103], v[102:103], v[104:105]
	v_mul_f32_e32 v97, v94, v94
	v_mul_f32_e32 v107, v95, v95
	v_and_b32_e32 v109, 0xffff0000, v205
	v_mul_f32_e32 v204, v108, v108
	v_mov_b32_e32 v106, v96
	v_pk_add_f32 v[100:101], v[100:101], v[100:101] op_sel_hi:[0,1]
	v_pk_add_f32 v[104:105], v[104:105], v[104:105] op_sel_hi:[0,1]
	v_pk_fma_f32 v[204:205], v[108:109], v[108:109], v[204:205] op_sel_hi:[1,1,0]
	v_pk_add_f32 v[106:107], v[96:97], v[106:107]
	v_mul_f32_e32 v204, v61, v61
	v_mul_f32_e32 v100, v98, v98
	v_mul_f32_e32 v104, v99, v99
	v_mul_f32_e32 v110, v96, v96
	v_mov_b32_e32 v111, v107
	v_pk_add_f32 v[204:205], v[110:111], v[204:205]
	v_pk_add_f32 v[100:101], v[100:101], v[104:105]
	v_pk_add_f32 v[204:205], v[204:205], v[100:101]
	v_add_f32_e32 v204, v204, v205
	ds_bpermute_b32 v205, v51, v204
	s_waitcnt lgkmcnt(0)
	v_add_f32_e32 v204, v204, v205
	ds_bpermute_b32 v205, v87, v204
	s_waitcnt lgkmcnt(0)
	v_add_f32_e32 v204, v204, v205
	ds_bpermute_b32 v205, v88, v204
	s_waitcnt lgkmcnt(0)
	v_add_f32_e32 v204, v204, v205
	ds_bpermute_b32 v205, v89, v204
	s_waitcnt lgkmcnt(0)
	v_add_f32_e32 v204, v204, v205
	ds_bpermute_b32 v205, v90, v204
	s_waitcnt lgkmcnt(0)
	v_add_f32_e32 v204, v204, v205
	ds_bpermute_b32 v205, v91, v204
	s_waitcnt lgkmcnt(0)
	v_add_f32_e32 v204, v204, v205
	v_fmamk_f32 v204, v204, 0x3a800000, v49
	v_mul_f32_e32 v205, 0x4f800000, v204
	v_cmp_gt_f32_e32 vcc, s8, v204
	s_nop 1
	v_cndmask_b32_e32 v204, v204, v205, vcc
	v_sqrt_f32_e32 v205, v204
	s_nop 0
	v_add_u32_e32 v97, -1, v205
	v_fma_f32 v100, -v97, v205, v204
	v_cmp_ge_f32_e64 s[0:1], 0, v100
	v_add_u32_e32 v100, 1, v205
	s_nop 0
	v_cndmask_b32_e64 v97, v205, v97, s[0:1]
	v_fma_f32 v205, -v100, v205, v204
	v_cmp_lt_f32_e64 s[0:1], 0, v205
	s_nop 1
	v_cndmask_b32_e64 v205, v97, v100, s[0:1]
	v_mul_f32_e32 v97, 0x37800000, v205
	v_cndmask_b32_e32 v205, v205, v97, vcc
	v_cmp_class_f32_e32 vcc, v204, v92
	s_nop 1
	v_cndmask_b32_e32 v204, v205, v204, vcc
	v_div_scale_f32 v205, s[0:1], v204, v204, 1.0
	v_rcp_f32_e32 v97, v205
	s_nop 0
	v_fma_f32 v100, -v205, v97, 1.0
	v_fmac_f32_e32 v97, v100, v97
	v_div_scale_f32 v100, vcc, 1.0, v204, 1.0
	v_mul_f32_e32 v101, v100, v97
	v_fma_f32 v104, -v205, v101, v100
	v_fmac_f32_e32 v101, v104, v97
	v_fma_f32 v205, -v205, v101, v100
	v_div_fmas_f32 v205, v205, v97, v101
	v_div_fixup_f32 v100, v205, v204, 1.0
	v_mov_b32_e32 v204, v206
	v_mov_b32_e32 v205, v200
	v_mov_b32_e32 v200, v207
	v_pk_mul_f32 v[204:205], v[100:101], v[204:205] op_sel_hi:[0,1]
	v_pk_mul_f32 v[206:207], v[100:101], v[200:201] op_sel_hi:[0,1]
	v_mov_b32_e32 v200, v102
	v_mov_b32_e32 v201, v202
	v_mov_b32_e32 v202, v103
	v_pk_fma_f32 v[206:207], v[70:71], v[206:207], v[22:23]
	v_pk_fma_f32 v[204:205], v[72:73], v[204:205], v[20:21]
	v_pk_mul_f32 v[200:201], v[100:101], v[200:201] op_sel_hi:[0,1]
	v_pk_mul_f32 v[202:203], v[100:101], v[202:203] op_sel_hi:[0,1]
	s_mov_b64 s[6:7], 0x1400
	v_lshl_add_u64 v[104:105], s[6:7], 1, v[68:69]
	v_pk_fma_f32 v[202:203], v[74:75], v[202:203], v[18:19]
	v_pk_fma_f32 v[200:201], v[76:77], v[200:201], v[16:17]
	v_cvt_pk_bf16_f32 v204, v204, v205
	v_cvt_pk_bf16_f32 v205, v206, v207
	v_mov_b32_e32 v97, v61
	v_cvt_pk_bf16_f32 v206, v200, v201
	v_cvt_pk_bf16_f32 v207, v202, v203
	global_store_dwordx4 v[104:105], v[204:207], off
	v_pk_mul_f32 v[200:201], v[96:97], v[100:101] op_sel_hi:[1,0]
	v_pk_mul_f32 v[202:203], v[98:99], v[100:101] op_sel_hi:[1,0]
	v_pk_mul_f32 v[204:205], v[94:95], v[100:101] op_sel_hi:[1,0]
	v_pk_mul_f32 v[206:207], v[108:109], v[100:101] op_sel_hi:[1,0]
	v_pk_fma_f32 v[204:205], v[80:81], v[204:205], v[28:29]
	v_pk_fma_f32 v[206:207], v[78:79], v[206:207], v[30:31]
	v_pk_fma_f32 v[202:203], v[82:83], v[202:203], v[26:27]
	v_pk_fma_f32 v[200:201], v[84:85], v[200:201], v[24:25]
	v_cvt_pk_bf16_f32 v204, v204, v205
	v_cvt_pk_bf16_f32 v205, v206, v207
	s_nop 0
	v_cvt_pk_bf16_f32 v206, v200, v201
	v_cvt_pk_bf16_f32 v207, v202, v203
	global_store_dwordx4 v[104:105], v[204:207], off offset:1024
	s_nop 0
	s_nop 0
	s_nop 0
	s_nop 0
	s_nop 0
	s_nop 0
	s_nop 0
	s_nop 0
	s_waitcnt vmcnt(14)
	v_lshlrev_b32_e32 v96, 16, v214
	v_and_b32_e32 v61, 0xffff0000, v214
	v_lshlrev_b32_e32 v98, 16, v215
	v_and_b32_e32 v99, 0xffff0000, v215
	v_lshlrev_b32_e32 v215, 16, v209
	v_lshlrev_b32_e32 v214, 16, v208
	v_and_b32_e32 v209, 0xffff0000, v209
	v_and_b32_e32 v208, 0xffff0000, v208
	v_lshlrev_b32_e32 v103, 16, v211
	v_lshlrev_b32_e32 v102, 16, v210
	v_and_b32_e32 v211, 0xffff0000, v211
	v_and_b32_e32 v210, 0xffff0000, v210
	v_lshlrev_b32_e32 v94, 16, v212
	v_and_b32_e32 v95, 0xffff0000, v212
	v_pk_mul_f32 v[100:101], v[208:209], v[208:209]
	v_pk_mul_f32 v[104:105], v[210:211], v[210:211]
	v_lshlrev_b32_e32 v108, 16, v213
	v_pk_fma_f32 v[100:101], v[214:215], v[214:215], v[100:101]
	v_pk_fma_f32 v[104:105], v[102:103], v[102:103], v[104:105]
	v_mul_f32_e32 v97, v94, v94
	v_mul_f32_e32 v107, v95, v95
	v_and_b32_e32 v109, 0xffff0000, v213
	v_mul_f32_e32 v212, v108, v108
	v_mov_b32_e32 v106, v96
	v_pk_add_f32 v[100:101], v[100:101], v[100:101] op_sel_hi:[0,1]
	v_pk_add_f32 v[104:105], v[104:105], v[104:105] op_sel_hi:[0,1]
	v_pk_fma_f32 v[212:213], v[108:109], v[108:109], v[212:213] op_sel_hi:[1,1,0]
	v_pk_add_f32 v[106:107], v[96:97], v[106:107]
	v_mul_f32_e32 v212, v61, v61
	v_mul_f32_e32 v100, v98, v98
	v_mul_f32_e32 v104, v99, v99
	v_mul_f32_e32 v110, v96, v96
	v_mov_b32_e32 v111, v107
	v_pk_add_f32 v[212:213], v[110:111], v[212:213]
	v_pk_add_f32 v[100:101], v[100:101], v[104:105]
	v_pk_add_f32 v[212:213], v[212:213], v[100:101]
	v_add_f32_e32 v212, v212, v213
	ds_bpermute_b32 v213, v51, v212
	s_waitcnt lgkmcnt(0)
	v_add_f32_e32 v212, v212, v213
	ds_bpermute_b32 v213, v87, v212
	s_waitcnt lgkmcnt(0)
	v_add_f32_e32 v212, v212, v213
	ds_bpermute_b32 v213, v88, v212
	s_waitcnt lgkmcnt(0)
	v_add_f32_e32 v212, v212, v213
	ds_bpermute_b32 v213, v89, v212
	s_waitcnt lgkmcnt(0)
	v_add_f32_e32 v212, v212, v213
	ds_bpermute_b32 v213, v90, v212
	s_waitcnt lgkmcnt(0)
	v_add_f32_e32 v212, v212, v213
	ds_bpermute_b32 v213, v91, v212
	s_waitcnt lgkmcnt(0)
	v_add_f32_e32 v212, v212, v213
	v_fmamk_f32 v212, v212, 0x3a800000, v49
	v_mul_f32_e32 v213, 0x4f800000, v212
	v_cmp_gt_f32_e32 vcc, s8, v212
	s_nop 1
	v_cndmask_b32_e32 v212, v212, v213, vcc
	v_sqrt_f32_e32 v213, v212
	s_nop 0
	v_add_u32_e32 v97, -1, v213
	v_fma_f32 v100, -v97, v213, v212
	v_cmp_ge_f32_e64 s[0:1], 0, v100
	v_add_u32_e32 v100, 1, v213
	s_nop 0
	v_cndmask_b32_e64 v97, v213, v97, s[0:1]
	v_fma_f32 v213, -v100, v213, v212
	v_cmp_lt_f32_e64 s[0:1], 0, v213
	s_nop 1
	v_cndmask_b32_e64 v213, v97, v100, s[0:1]
	v_mul_f32_e32 v97, 0x37800000, v213
	v_cndmask_b32_e32 v213, v213, v97, vcc
	v_cmp_class_f32_e32 vcc, v212, v92
	s_nop 1
	v_cndmask_b32_e32 v212, v213, v212, vcc
	v_div_scale_f32 v213, s[0:1], v212, v212, 1.0
	v_rcp_f32_e32 v97, v213
	s_nop 0
	v_fma_f32 v100, -v213, v97, 1.0
	v_fmac_f32_e32 v97, v100, v97
	v_div_scale_f32 v100, vcc, 1.0, v212, 1.0
	v_mul_f32_e32 v101, v100, v97
	v_fma_f32 v104, -v213, v101, v100
	v_fmac_f32_e32 v101, v104, v97
	v_fma_f32 v213, -v213, v101, v100
	v_div_fmas_f32 v213, v213, v97, v101
	v_div_fixup_f32 v100, v213, v212, 1.0
	v_mov_b32_e32 v212, v214
	v_mov_b32_e32 v213, v208
	v_mov_b32_e32 v208, v215
	v_pk_mul_f32 v[212:213], v[100:101], v[212:213] op_sel_hi:[0,1]
	v_pk_mul_f32 v[214:215], v[100:101], v[208:209] op_sel_hi:[0,1]
	v_mov_b32_e32 v208, v102
	v_mov_b32_e32 v209, v210
	v_mov_b32_e32 v210, v103
	v_pk_fma_f32 v[214:215], v[70:71], v[214:215], v[22:23]
	v_pk_fma_f32 v[212:213], v[72:73], v[212:213], v[20:21]
	v_pk_mul_f32 v[208:209], v[100:101], v[208:209] op_sel_hi:[0,1]
	v_pk_mul_f32 v[210:211], v[100:101], v[210:211] op_sel_hi:[0,1]
	s_mov_b64 s[6:7], 0x1800
	v_lshl_add_u64 v[104:105], s[6:7], 1, v[68:69]
	v_pk_fma_f32 v[210:211], v[74:75], v[210:211], v[18:19]
	v_pk_fma_f32 v[208:209], v[76:77], v[208:209], v[16:17]
	v_cvt_pk_bf16_f32 v212, v212, v213
	v_cvt_pk_bf16_f32 v213, v214, v215
	v_mov_b32_e32 v97, v61
	v_cvt_pk_bf16_f32 v214, v208, v209
	v_cvt_pk_bf16_f32 v215, v210, v211
	global_store_dwordx4 v[104:105], v[212:215], off
	v_pk_mul_f32 v[208:209], v[96:97], v[100:101] op_sel_hi:[1,0]
	v_pk_mul_f32 v[210:211], v[98:99], v[100:101] op_sel_hi:[1,0]
	v_pk_mul_f32 v[212:213], v[94:95], v[100:101] op_sel_hi:[1,0]
	v_pk_mul_f32 v[214:215], v[108:109], v[100:101] op_sel_hi:[1,0]
	v_pk_fma_f32 v[212:213], v[80:81], v[212:213], v[28:29]
	v_pk_fma_f32 v[214:215], v[78:79], v[214:215], v[30:31]
	v_pk_fma_f32 v[210:211], v[82:83], v[210:211], v[26:27]
	v_pk_fma_f32 v[208:209], v[84:85], v[208:209], v[24:25]
	v_cvt_pk_bf16_f32 v212, v212, v213
	v_cvt_pk_bf16_f32 v213, v214, v215
	s_nop 0
	v_cvt_pk_bf16_f32 v214, v208, v209
	v_cvt_pk_bf16_f32 v215, v210, v211
	global_store_dwordx4 v[104:105], v[212:215], off offset:1024
	s_nop 0
	s_nop 0
	s_nop 0
	s_nop 0
	s_nop 0
	s_nop 0
	s_nop 0
	s_nop 0
	s_waitcnt vmcnt(14)
	v_lshlrev_b32_e32 v96, 16, v222
	v_and_b32_e32 v61, 0xffff0000, v222
	v_lshlrev_b32_e32 v98, 16, v223
	v_and_b32_e32 v99, 0xffff0000, v223
	v_lshlrev_b32_e32 v223, 16, v217
	v_lshlrev_b32_e32 v222, 16, v216
	v_and_b32_e32 v217, 0xffff0000, v217
	v_and_b32_e32 v216, 0xffff0000, v216
	v_lshlrev_b32_e32 v103, 16, v219
	v_lshlrev_b32_e32 v102, 16, v218
	v_and_b32_e32 v219, 0xffff0000, v219
	v_and_b32_e32 v218, 0xffff0000, v218
	v_lshlrev_b32_e32 v94, 16, v220
	v_and_b32_e32 v95, 0xffff0000, v220
	v_pk_mul_f32 v[100:101], v[216:217], v[216:217]
	v_pk_mul_f32 v[104:105], v[218:219], v[218:219]
	v_lshlrev_b32_e32 v108, 16, v221
	v_pk_fma_f32 v[100:101], v[222:223], v[222:223], v[100:101]
	v_pk_fma_f32 v[104:105], v[102:103], v[102:103], v[104:105]
	v_mul_f32_e32 v97, v94, v94
	v_mul_f32_e32 v107, v95, v95
	v_and_b32_e32 v109, 0xffff0000, v221
	v_mul_f32_e32 v220, v108, v108
	v_mov_b32_e32 v106, v96
	v_pk_add_f32 v[100:101], v[100:101], v[100:101] op_sel_hi:[0,1]
	v_pk_add_f32 v[104:105], v[104:105], v[104:105] op_sel_hi:[0,1]
	v_pk_fma_f32 v[220:221], v[108:109], v[108:109], v[220:221] op_sel_hi:[1,1,0]
	v_pk_add_f32 v[106:107], v[96:97], v[106:107]
	v_mul_f32_e32 v220, v61, v61
	v_mul_f32_e32 v100, v98, v98
	v_mul_f32_e32 v104, v99, v99
	v_mul_f32_e32 v110, v96, v96
	v_mov_b32_e32 v111, v107
	v_pk_add_f32 v[220:221], v[110:111], v[220:221]
	v_pk_add_f32 v[100:101], v[100:101], v[104:105]
	v_pk_add_f32 v[220:221], v[220:221], v[100:101]
	v_add_f32_e32 v220, v220, v221
	ds_bpermute_b32 v221, v51, v220
	s_waitcnt lgkmcnt(0)
	v_add_f32_e32 v220, v220, v221
	ds_bpermute_b32 v221, v87, v220
	s_waitcnt lgkmcnt(0)
	v_add_f32_e32 v220, v220, v221
	ds_bpermute_b32 v221, v88, v220
	s_waitcnt lgkmcnt(0)
	v_add_f32_e32 v220, v220, v221
	ds_bpermute_b32 v221, v89, v220
	s_waitcnt lgkmcnt(0)
	v_add_f32_e32 v220, v220, v221
	ds_bpermute_b32 v221, v90, v220
	s_waitcnt lgkmcnt(0)
	v_add_f32_e32 v220, v220, v221
	ds_bpermute_b32 v221, v91, v220
	s_waitcnt lgkmcnt(0)
	v_add_f32_e32 v220, v220, v221
	v_fmamk_f32 v220, v220, 0x3a800000, v49
	v_mul_f32_e32 v221, 0x4f800000, v220
	v_cmp_gt_f32_e32 vcc, s8, v220
	s_nop 1
	v_cndmask_b32_e32 v220, v220, v221, vcc
	v_sqrt_f32_e32 v221, v220
	s_nop 0
	v_add_u32_e32 v97, -1, v221
	v_fma_f32 v100, -v97, v221, v220
	v_cmp_ge_f32_e64 s[0:1], 0, v100
	v_add_u32_e32 v100, 1, v221
	s_nop 0
	v_cndmask_b32_e64 v97, v221, v97, s[0:1]
	v_fma_f32 v221, -v100, v221, v220
	v_cmp_lt_f32_e64 s[0:1], 0, v221
	s_nop 1
	v_cndmask_b32_e64 v221, v97, v100, s[0:1]
	v_mul_f32_e32 v97, 0x37800000, v221
	v_cndmask_b32_e32 v221, v221, v97, vcc
	v_cmp_class_f32_e32 vcc, v220, v92
	s_nop 1
	v_cndmask_b32_e32 v220, v221, v220, vcc
	v_div_scale_f32 v221, s[0:1], v220, v220, 1.0
	v_rcp_f32_e32 v97, v221
	s_nop 0
	v_fma_f32 v100, -v221, v97, 1.0
	v_fmac_f32_e32 v97, v100, v97
	v_div_scale_f32 v100, vcc, 1.0, v220, 1.0
	v_mul_f32_e32 v101, v100, v97
	v_fma_f32 v104, -v221, v101, v100
	v_fmac_f32_e32 v101, v104, v97
	v_fma_f32 v221, -v221, v101, v100
	v_div_fmas_f32 v221, v221, v97, v101
	v_div_fixup_f32 v100, v221, v220, 1.0
	v_mov_b32_e32 v220, v222
	v_mov_b32_e32 v221, v216
	v_mov_b32_e32 v216, v223
	v_pk_mul_f32 v[220:221], v[100:101], v[220:221] op_sel_hi:[0,1]
	v_pk_mul_f32 v[222:223], v[100:101], v[216:217] op_sel_hi:[0,1]
	v_mov_b32_e32 v216, v102
	v_mov_b32_e32 v217, v218
	v_mov_b32_e32 v218, v103
	v_pk_fma_f32 v[222:223], v[70:71], v[222:223], v[22:23]
	v_pk_fma_f32 v[220:221], v[72:73], v[220:221], v[20:21]
	v_pk_mul_f32 v[216:217], v[100:101], v[216:217] op_sel_hi:[0,1]
	v_pk_mul_f32 v[218:219], v[100:101], v[218:219] op_sel_hi:[0,1]
	s_mov_b64 s[6:7], 0x1c00
	v_lshl_add_u64 v[104:105], s[6:7], 1, v[68:69]
	v_pk_fma_f32 v[218:219], v[74:75], v[218:219], v[18:19]
	v_pk_fma_f32 v[216:217], v[76:77], v[216:217], v[16:17]
	v_cvt_pk_bf16_f32 v220, v220, v221
	v_cvt_pk_bf16_f32 v221, v222, v223
	v_mov_b32_e32 v97, v61
	v_cvt_pk_bf16_f32 v222, v216, v217
	v_cvt_pk_bf16_f32 v223, v218, v219
	global_store_dwordx4 v[104:105], v[220:223], off
	v_pk_mul_f32 v[216:217], v[96:97], v[100:101] op_sel_hi:[1,0]
	v_pk_mul_f32 v[218:219], v[98:99], v[100:101] op_sel_hi:[1,0]
	v_pk_mul_f32 v[220:221], v[94:95], v[100:101] op_sel_hi:[1,0]
	v_pk_mul_f32 v[222:223], v[108:109], v[100:101] op_sel_hi:[1,0]
	v_pk_fma_f32 v[220:221], v[80:81], v[220:221], v[28:29]
	v_pk_fma_f32 v[222:223], v[78:79], v[222:223], v[30:31]
	v_pk_fma_f32 v[218:219], v[82:83], v[218:219], v[26:27]
	v_pk_fma_f32 v[216:217], v[84:85], v[216:217], v[24:25]
	v_cvt_pk_bf16_f32 v220, v220, v221
	v_cvt_pk_bf16_f32 v221, v222, v223
	s_nop 0
	v_cvt_pk_bf16_f32 v222, v216, v217
	v_cvt_pk_bf16_f32 v223, v218, v219
	global_store_dwordx4 v[104:105], v[220:223], off offset:1024
	s_nop 0
	s_nop 0
	s_nop 0
	s_nop 0
	s_nop 0
	s_nop 0
	s_nop 0
	s_nop 0
	s_branch .LBB0_494

.LBB0_1145:
	v_lshrrev_b32_e32 v16, 8, v93
	v_mul_hi_i32_i24_e32 v17, 0x9000, v16
	v_mul_i32_i24_e32 v16, 0x9000, v16
	v_lshl_add_u64 v[16:17], s[96:97], 0, v[16:17]
	v_lshl_add_u64 v[18:19], v[16:17], 0, s[14:15]
	v_lshl_add_u64 v[24:25], v[16:17], 0, s[16:17]
	v_lshl_add_u64 v[16:17], v[18:19], 0, v[52:53]
	v_lshl_add_u64 v[26:27], v[24:25], 0, v[52:53]
	v_lshl_add_u64 v[28:29], v[18:19], 0, v[62:63]
	v_lshl_add_u64 v[32:33], v[24:25], 0, v[62:63]
	global_load_dwordx4 v[76:79], v[56:57], off offset:16
	global_load_dwordx4 v[72:75], v[56:57], off
	global_load_dwordx4 v[80:83], v[16:17], off offset:16
	global_load_dwordx4 v[94:97], v[16:17], off
	global_load_dwordx4 v[98:101], v[28:29], off offset:16
	global_load_dwordx4 v[102:105], v[28:29], off
	s_nop 0
	global_load_dwordx4 v[16:19], v[26:27], off offset:16
	global_load_dwordx4 v[20:23], v[26:27], off
	global_load_dwordx4 v[106:109], v[56:57], off offset:2064
	global_load_dwordx4 v[110:113], v[56:57], off offset:2048
	s_nop 0
	global_load_dwordx4 v[24:27], v[32:33], off offset:16
	global_load_dwordx4 v[28:31], v[32:33], off
	v_lshlrev_b32_e32 v32, 3, v93
	v_ashrrev_i32_e32 v33, 31, v32
	v_lshlrev_b64 v[68:69], 11, v[32:33]
	v_lshl_add_u64 v[32:33], s[22:23], 0, v[68:69]
	v_lshl_add_u64 v[32:33], v[32:33], 0, v[64:65]
	global_load_dwordx4 v[44:47], v[32:33], off
	global_load_dwordx4 v[40:43], v[32:33], off offset:1024
	v_ashrrev_i32_e32 v61, 31, v60
	v_lshlrev_b64 v[66:67], 11, v[60:61]
	v_lshl_add_u64 v[66:67], v[58:59], 0, v[66:67]
	v_lshl_add_u64 v[68:69], v[54:55], 0, v[68:69]
	s_mov_b64 s[6:7], 0xc500800
	v_lshl_add_u64 v[226:227], v[66:67], 0, s[6:7]
	global_load_dwordx4 v[32:35], v[226:227], off
	global_load_dwordx4 v[36:39], v[226:227], off offset:1024
	s_mov_b64 s[6:7], 0xc501000
	v_lshl_add_u64 v[224:225], v[66:67], 0, s[6:7]
	global_load_dwordx4 v[176:179], v[224:225], off
	global_load_dwordx4 v[180:183], v[224:225], off offset:1024
	s_mov_b64 s[6:7], 0xc501800
	v_lshl_add_u64 v[226:227], v[66:67], 0, s[6:7]
	global_load_dwordx4 v[184:187], v[226:227], off
	global_load_dwordx4 v[188:191], v[226:227], off offset:1024
	s_mov_b64 s[6:7], 0xc502000
	v_lshl_add_u64 v[224:225], v[66:67], 0, s[6:7]
	global_load_dwordx4 v[192:195], v[224:225], off
	global_load_dwordx4 v[196:199], v[224:225], off offset:1024
	s_mov_b64 s[6:7], 0xc502800
	v_lshl_add_u64 v[226:227], v[66:67], 0, s[6:7]
	global_load_dwordx4 v[200:203], v[226:227], off
	global_load_dwordx4 v[204:207], v[226:227], off offset:1024
	s_mov_b64 s[6:7], 0xc503000
	v_lshl_add_u64 v[224:225], v[66:67], 0, s[6:7]
	global_load_dwordx4 v[208:211], v[224:225], off
	global_load_dwordx4 v[212:215], v[224:225], off offset:1024
	s_mov_b64 s[6:7], 0xc503800
	v_lshl_add_u64 v[226:227], v[66:67], 0, s[6:7]
	global_load_dwordx4 v[216:219], v[226:227], off
	global_load_dwordx4 v[220:223], v[226:227], off offset:1024
	s_waitcnt vmcnt(16)
	v_pk_add_f32 v[100:101], v[100:101], 1.0 op_sel_hi:[1,0]
	v_pk_add_f32 v[98:99], v[98:99], 1.0 op_sel_hi:[1,0]
	v_pk_add_f32 v[82:83], v[82:83], 1.0 op_sel_hi:[1,0]
	v_pk_add_f32 v[70:71], v[96:97], 1.0 op_sel_hi:[1,0]
	v_pk_add_f32 v[84:85], v[94:95], 1.0 op_sel_hi:[1,0]
	v_pk_add_f32 v[80:81], v[80:81], 1.0 op_sel_hi:[1,0]
	v_pk_add_f32 v[94:95], v[104:105], 1.0 op_sel_hi:[1,0]
	v_pk_add_f32 v[96:97], v[102:103], 1.0 op_sel_hi:[1,0]
	v_pk_mul_f32 v[70:71], v[74:75], v[70:71]
	v_pk_mul_f32 v[72:73], v[72:73], v[84:85]
	v_pk_mul_f32 v[74:75], v[78:79], v[82:83]
	v_pk_mul_f32 v[76:77], v[76:77], v[80:81]
	v_pk_mul_f32 v[78:79], v[112:113], v[94:95]
	v_pk_mul_f32 v[80:81], v[110:111], v[96:97]
	v_pk_mul_f32 v[82:83], v[108:109], v[100:101]
	v_pk_mul_f32 v[84:85], v[106:107], v[98:99]
	s_waitcnt vmcnt(14)
	v_lshlrev_b32_e32 v96, 16, v42
	v_and_b32_e32 v61, 0xffff0000, v42
	v_lshlrev_b32_e32 v98, 16, v43
	v_and_b32_e32 v99, 0xffff0000, v43
	v_lshlrev_b32_e32 v43, 16, v45
	v_lshlrev_b32_e32 v42, 16, v44
	v_and_b32_e32 v45, 0xffff0000, v45
	v_and_b32_e32 v44, 0xffff0000, v44
	v_lshlrev_b32_e32 v103, 16, v47
	v_lshlrev_b32_e32 v102, 16, v46
	v_and_b32_e32 v47, 0xffff0000, v47
	v_and_b32_e32 v46, 0xffff0000, v46
	v_lshlrev_b32_e32 v94, 16, v40
	v_and_b32_e32 v95, 0xffff0000, v40
	v_pk_mul_f32 v[100:101], v[44:45], v[44:45]
	v_pk_mul_f32 v[104:105], v[46:47], v[46:47]
	v_lshlrev_b32_e32 v108, 16, v41
	v_pk_fma_f32 v[100:101], v[42:43], v[42:43], v[100:101]
	v_pk_fma_f32 v[104:105], v[102:103], v[102:103], v[104:105]
	v_mul_f32_e32 v97, v94, v94
	v_mul_f32_e32 v107, v95, v95
	v_and_b32_e32 v109, 0xffff0000, v41
	v_mul_f32_e32 v40, v108, v108
	v_mov_b32_e32 v106, v96
	v_pk_add_f32 v[100:101], v[100:101], v[100:101] op_sel_hi:[0,1]
	v_pk_add_f32 v[104:105], v[104:105], v[104:105] op_sel_hi:[0,1]
	v_pk_fma_f32 v[40:41], v[108:109], v[108:109], v[40:41] op_sel_hi:[1,1,0]
	v_pk_add_f32 v[106:107], v[96:97], v[106:107]
	v_mul_f32_e32 v40, v61, v61
	v_mul_f32_e32 v100, v98, v98
	v_mul_f32_e32 v104, v99, v99
	v_mul_f32_e32 v110, v96, v96
	v_mov_b32_e32 v111, v107
	v_pk_add_f32 v[40:41], v[110:111], v[40:41]
	v_pk_add_f32 v[100:101], v[100:101], v[104:105]
	v_pk_add_f32 v[40:41], v[40:41], v[100:101]
	v_add_f32_e32 v40, v40, v41
	ds_bpermute_b32 v41, v51, v40
	s_waitcnt lgkmcnt(0)
	v_add_f32_e32 v40, v40, v41
	ds_bpermute_b32 v41, v87, v40
	s_waitcnt lgkmcnt(0)
	v_add_f32_e32 v40, v40, v41
	ds_bpermute_b32 v41, v88, v40
	s_waitcnt lgkmcnt(0)
	v_add_f32_e32 v40, v40, v41
	ds_bpermute_b32 v41, v89, v40
	s_waitcnt lgkmcnt(0)
	v_add_f32_e32 v40, v40, v41
	ds_bpermute_b32 v41, v90, v40
	s_waitcnt lgkmcnt(0)
	v_add_f32_e32 v40, v40, v41
	ds_bpermute_b32 v41, v91, v40
	s_waitcnt lgkmcnt(0)
	v_add_f32_e32 v40, v40, v41
	v_fmamk_f32 v40, v40, 0x3a800000, v49
	v_mul_f32_e32 v41, 0x4f800000, v40
	v_cmp_gt_f32_e32 vcc, s9, v40
	s_nop 1
	v_cndmask_b32_e32 v40, v40, v41, vcc
	v_sqrt_f32_e32 v41, v40
	s_nop 0
	v_add_u32_e32 v97, -1, v41
	v_fma_f32 v100, -v97, v41, v40
	v_cmp_ge_f32_e64 s[0:1], 0, v100
	v_add_u32_e32 v100, 1, v41
	s_nop 0
	v_cndmask_b32_e64 v97, v41, v97, s[0:1]
	v_fma_f32 v41, -v100, v41, v40
	v_cmp_lt_f32_e64 s[0:1], 0, v41
	s_nop 1
	v_cndmask_b32_e64 v41, v97, v100, s[0:1]
	v_mul_f32_e32 v97, 0x37800000, v41
	v_cndmask_b32_e32 v41, v41, v97, vcc
	v_cmp_class_f32_e32 vcc, v40, v92
	s_nop 1
	v_cndmask_b32_e32 v40, v41, v40, vcc
	v_div_scale_f32 v41, s[0:1], v40, v40, 1.0
	v_rcp_f32_e32 v97, v41
	s_nop 0
	v_fma_f32 v100, -v41, v97, 1.0
	v_fmac_f32_e32 v97, v100, v97
	v_div_scale_f32 v100, vcc, 1.0, v40, 1.0
	v_mul_f32_e32 v101, v100, v97
	v_fma_f32 v104, -v41, v101, v100
	v_fmac_f32_e32 v101, v104, v97
	v_fma_f32 v41, -v41, v101, v100
	v_div_fmas_f32 v41, v41, v97, v101
	v_div_fixup_f32 v100, v41, v40, 1.0
	v_mov_b32_e32 v40, v42
	v_mov_b32_e32 v41, v44
	v_mov_b32_e32 v44, v43
	v_pk_mul_f32 v[40:41], v[100:101], v[40:41] op_sel_hi:[0,1]
	v_pk_mul_f32 v[42:43], v[100:101], v[44:45] op_sel_hi:[0,1]
	v_mov_b32_e32 v44, v102
	v_mov_b32_e32 v45, v46
	v_mov_b32_e32 v46, v103
	v_pk_fma_f32 v[42:43], v[70:71], v[42:43], v[22:23]
	v_pk_fma_f32 v[40:41], v[72:73], v[40:41], v[20:21]
	v_pk_mul_f32 v[44:45], v[100:101], v[44:45] op_sel_hi:[0,1]
	v_pk_mul_f32 v[46:47], v[100:101], v[46:47] op_sel_hi:[0,1]
	s_mov_b64 s[6:7], 0x0
	v_lshl_add_u64 v[104:105], s[6:7], 1, v[68:69]
	v_pk_fma_f32 v[46:47], v[74:75], v[46:47], v[18:19]
	v_pk_fma_f32 v[44:45], v[76:77], v[44:45], v[16:17]
	v_cvt_pk_bf16_f32 v40, v40, v41
	v_cvt_pk_bf16_f32 v41, v42, v43
	v_mov_b32_e32 v97, v61
	v_cvt_pk_bf16_f32 v42, v44, v45
	v_cvt_pk_bf16_f32 v43, v46, v47
	global_store_dwordx4 v[104:105], v[40:43], off
	v_pk_mul_f32 v[44:45], v[96:97], v[100:101] op_sel_hi:[1,0]
	v_pk_mul_f32 v[46:47], v[98:99], v[100:101] op_sel_hi:[1,0]
	v_pk_mul_f32 v[40:41], v[94:95], v[100:101] op_sel_hi:[1,0]
	v_pk_mul_f32 v[42:43], v[108:109], v[100:101] op_sel_hi:[1,0]
	v_pk_fma_f32 v[40:41], v[80:81], v[40:41], v[28:29]
	v_pk_fma_f32 v[42:43], v[78:79], v[42:43], v[30:31]
	v_pk_fma_f32 v[46:47], v[82:83], v[46:47], v[26:27]
	v_pk_fma_f32 v[44:45], v[84:85], v[44:45], v[24:25]
	v_cvt_pk_bf16_f32 v40, v40, v41
	v_cvt_pk_bf16_f32 v41, v42, v43
	s_nop 0
	v_cvt_pk_bf16_f32 v42, v44, v45
	v_cvt_pk_bf16_f32 v43, v46, v47
	global_store_dwordx4 v[104:105], v[40:43], off offset:1024
	s_nop 0
	s_nop 0
	s_nop 0
	s_nop 0
	s_nop 0
	s_nop 0
	s_nop 0
	s_nop 0
	s_waitcnt vmcnt(14)
	v_lshlrev_b32_e32 v96, 16, v38
	v_and_b32_e32 v61, 0xffff0000, v38
	v_lshlrev_b32_e32 v98, 16, v39
	v_and_b32_e32 v99, 0xffff0000, v39
	v_lshlrev_b32_e32 v39, 16, v33
	v_lshlrev_b32_e32 v38, 16, v32
	v_and_b32_e32 v33, 0xffff0000, v33
	v_and_b32_e32 v32, 0xffff0000, v32
	v_lshlrev_b32_e32 v103, 16, v35
	v_lshlrev_b32_e32 v102, 16, v34
	v_and_b32_e32 v35, 0xffff0000, v35
	v_and_b32_e32 v34, 0xffff0000, v34
	v_lshlrev_b32_e32 v94, 16, v36
	v_and_b32_e32 v95, 0xffff0000, v36
	v_pk_mul_f32 v[100:101], v[32:33], v[32:33]
	v_pk_mul_f32 v[104:105], v[34:35], v[34:35]
	v_lshlrev_b32_e32 v108, 16, v37
	v_pk_fma_f32 v[100:101], v[38:39], v[38:39], v[100:101]
	v_pk_fma_f32 v[104:105], v[102:103], v[102:103], v[104:105]
	v_mul_f32_e32 v97, v94, v94
	v_mul_f32_e32 v107, v95, v95
	v_and_b32_e32 v109, 0xffff0000, v37
	v_mul_f32_e32 v36, v108, v108
	v_mov_b32_e32 v106, v96
	v_pk_add_f32 v[100:101], v[100:101], v[100:101] op_sel_hi:[0,1]
	v_pk_add_f32 v[104:105], v[104:105], v[104:105] op_sel_hi:[0,1]
	v_pk_fma_f32 v[36:37], v[108:109], v[108:109], v[36:37] op_sel_hi:[1,1,0]
	v_pk_add_f32 v[106:107], v[96:97], v[106:107]
	v_mul_f32_e32 v36, v61, v61
	v_mul_f32_e32 v100, v98, v98
	v_mul_f32_e32 v104, v99, v99
	v_mul_f32_e32 v110, v96, v96
	v_mov_b32_e32 v111, v107
	v_pk_add_f32 v[36:37], v[110:111], v[36:37]
	v_pk_add_f32 v[100:101], v[100:101], v[104:105]
	v_pk_add_f32 v[36:37], v[36:37], v[100:101]
	v_add_f32_e32 v36, v36, v37
	ds_bpermute_b32 v37, v51, v36
	s_waitcnt lgkmcnt(0)
	v_add_f32_e32 v36, v36, v37
	ds_bpermute_b32 v37, v87, v36
	s_waitcnt lgkmcnt(0)
	v_add_f32_e32 v36, v36, v37
	ds_bpermute_b32 v37, v88, v36
	s_waitcnt lgkmcnt(0)
	v_add_f32_e32 v36, v36, v37
	ds_bpermute_b32 v37, v89, v36
	s_waitcnt lgkmcnt(0)
	v_add_f32_e32 v36, v36, v37
	ds_bpermute_b32 v37, v90, v36
	s_waitcnt lgkmcnt(0)
	v_add_f32_e32 v36, v36, v37
	ds_bpermute_b32 v37, v91, v36
	s_waitcnt lgkmcnt(0)
	v_add_f32_e32 v36, v36, v37
	v_fmamk_f32 v36, v36, 0x3a800000, v49
	v_mul_f32_e32 v37, 0x4f800000, v36
	v_cmp_gt_f32_e32 vcc, s9, v36
	s_nop 1
	v_cndmask_b32_e32 v36, v36, v37, vcc
	v_sqrt_f32_e32 v37, v36
	s_nop 0
	v_add_u32_e32 v97, -1, v37
	v_fma_f32 v100, -v97, v37, v36
	v_cmp_ge_f32_e64 s[0:1], 0, v100
	v_add_u32_e32 v100, 1, v37
	s_nop 0
	v_cndmask_b32_e64 v97, v37, v97, s[0:1]
	v_fma_f32 v37, -v100, v37, v36
	v_cmp_lt_f32_e64 s[0:1], 0, v37
	s_nop 1
	v_cndmask_b32_e64 v37, v97, v100, s[0:1]
	v_mul_f32_e32 v97, 0x37800000, v37
	v_cndmask_b32_e32 v37, v37, v97, vcc
	v_cmp_class_f32_e32 vcc, v36, v92
	s_nop 1
	v_cndmask_b32_e32 v36, v37, v36, vcc
	v_div_scale_f32 v37, s[0:1], v36, v36, 1.0
	v_rcp_f32_e32 v97, v37
	s_nop 0
	v_fma_f32 v100, -v37, v97, 1.0
	v_fmac_f32_e32 v97, v100, v97
	v_div_scale_f32 v100, vcc, 1.0, v36, 1.0
	v_mul_f32_e32 v101, v100, v97
	v_fma_f32 v104, -v37, v101, v100
	v_fmac_f32_e32 v101, v104, v97
	v_fma_f32 v37, -v37, v101, v100
	v_div_fmas_f32 v37, v37, v97, v101
	v_div_fixup_f32 v100, v37, v36, 1.0
	v_mov_b32_e32 v36, v38
	v_mov_b32_e32 v37, v32
	v_mov_b32_e32 v32, v39
	v_pk_mul_f32 v[36:37], v[100:101], v[36:37] op_sel_hi:[0,1]
	v_pk_mul_f32 v[38:39], v[100:101], v[32:33] op_sel_hi:[0,1]
	v_mov_b32_e32 v32, v102
	v_mov_b32_e32 v33, v34
	v_mov_b32_e32 v34, v103
	v_pk_fma_f32 v[38:39], v[70:71], v[38:39], v[22:23]
	v_pk_fma_f32 v[36:37], v[72:73], v[36:37], v[20:21]
	v_pk_mul_f32 v[32:33], v[100:101], v[32:33] op_sel_hi:[0,1]
	v_pk_mul_f32 v[34:35], v[100:101], v[34:35] op_sel_hi:[0,1]
	s_mov_b64 s[6:7], 0x400
	v_lshl_add_u64 v[104:105], s[6:7], 1, v[68:69]
	v_pk_fma_f32 v[34:35], v[74:75], v[34:35], v[18:19]
	v_pk_fma_f32 v[32:33], v[76:77], v[32:33], v[16:17]
	v_cvt_pk_bf16_f32 v36, v36, v37
	v_cvt_pk_bf16_f32 v37, v38, v39
	v_mov_b32_e32 v97, v61
	v_cvt_pk_bf16_f32 v38, v32, v33
	v_cvt_pk_bf16_f32 v39, v34, v35
	global_store_dwordx4 v[104:105], v[36:39], off
	v_pk_mul_f32 v[32:33], v[96:97], v[100:101] op_sel_hi:[1,0]
	v_pk_mul_f32 v[34:35], v[98:99], v[100:101] op_sel_hi:[1,0]
	v_pk_mul_f32 v[36:37], v[94:95], v[100:101] op_sel_hi:[1,0]
	v_pk_mul_f32 v[38:39], v[108:109], v[100:101] op_sel_hi:[1,0]
	v_pk_fma_f32 v[36:37], v[80:81], v[36:37], v[28:29]
	v_pk_fma_f32 v[38:39], v[78:79], v[38:39], v[30:31]
	v_pk_fma_f32 v[34:35], v[82:83], v[34:35], v[26:27]
	v_pk_fma_f32 v[32:33], v[84:85], v[32:33], v[24:25]
	v_cvt_pk_bf16_f32 v36, v36, v37
	v_cvt_pk_bf16_f32 v37, v38, v39
	s_nop 0
	v_cvt_pk_bf16_f32 v38, v32, v33
	v_cvt_pk_bf16_f32 v39, v34, v35
	global_store_dwordx4 v[104:105], v[36:39], off offset:1024
	s_nop 0
	s_nop 0
	s_nop 0
	s_nop 0
	s_nop 0
	s_nop 0
	s_nop 0
	s_nop 0
	s_waitcnt vmcnt(14)
	v_lshlrev_b32_e32 v96, 16, v182
	v_and_b32_e32 v61, 0xffff0000, v182
	v_lshlrev_b32_e32 v98, 16, v183
	v_and_b32_e32 v99, 0xffff0000, v183
	v_lshlrev_b32_e32 v183, 16, v177
	v_lshlrev_b32_e32 v182, 16, v176
	v_and_b32_e32 v177, 0xffff0000, v177
	v_and_b32_e32 v176, 0xffff0000, v176
	v_lshlrev_b32_e32 v103, 16, v179
	v_lshlrev_b32_e32 v102, 16, v178
	v_and_b32_e32 v179, 0xffff0000, v179
	v_and_b32_e32 v178, 0xffff0000, v178
	v_lshlrev_b32_e32 v94, 16, v180
	v_and_b32_e32 v95, 0xffff0000, v180
	v_pk_mul_f32 v[100:101], v[176:177], v[176:177]
	v_pk_mul_f32 v[104:105], v[178:179], v[178:179]
	v_lshlrev_b32_e32 v108, 16, v181
	v_pk_fma_f32 v[100:101], v[182:183], v[182:183], v[100:101]
	v_pk_fma_f32 v[104:105], v[102:103], v[102:103], v[104:105]
	v_mul_f32_e32 v97, v94, v94
	v_mul_f32_e32 v107, v95, v95
	v_and_b32_e32 v109, 0xffff0000, v181
	v_mul_f32_e32 v180, v108, v108
	v_mov_b32_e32 v106, v96
	v_pk_add_f32 v[100:101], v[100:101], v[100:101] op_sel_hi:[0,1]
	v_pk_add_f32 v[104:105], v[104:105], v[104:105] op_sel_hi:[0,1]
	v_pk_fma_f32 v[180:181], v[108:109], v[108:109], v[180:181] op_sel_hi:[1,1,0]
	v_pk_add_f32 v[106:107], v[96:97], v[106:107]
	v_mul_f32_e32 v180, v61, v61
	v_mul_f32_e32 v100, v98, v98
	v_mul_f32_e32 v104, v99, v99
	v_mul_f32_e32 v110, v96, v96
	v_mov_b32_e32 v111, v107
	v_pk_add_f32 v[180:181], v[110:111], v[180:181]
	v_pk_add_f32 v[100:101], v[100:101], v[104:105]
	v_pk_add_f32 v[180:181], v[180:181], v[100:101]
	v_add_f32_e32 v180, v180, v181
	ds_bpermute_b32 v181, v51, v180
	s_waitcnt lgkmcnt(0)
	v_add_f32_e32 v180, v180, v181
	ds_bpermute_b32 v181, v87, v180
	s_waitcnt lgkmcnt(0)
	v_add_f32_e32 v180, v180, v181
	ds_bpermute_b32 v181, v88, v180
	s_waitcnt lgkmcnt(0)
	v_add_f32_e32 v180, v180, v181
	ds_bpermute_b32 v181, v89, v180
	s_waitcnt lgkmcnt(0)
	v_add_f32_e32 v180, v180, v181
	ds_bpermute_b32 v181, v90, v180
	s_waitcnt lgkmcnt(0)
	v_add_f32_e32 v180, v180, v181
	ds_bpermute_b32 v181, v91, v180
	s_waitcnt lgkmcnt(0)
	v_add_f32_e32 v180, v180, v181
	v_fmamk_f32 v180, v180, 0x3a800000, v49
	v_mul_f32_e32 v181, 0x4f800000, v180
	v_cmp_gt_f32_e32 vcc, s9, v180
	s_nop 1
	v_cndmask_b32_e32 v180, v180, v181, vcc
	v_sqrt_f32_e32 v181, v180
	s_nop 0
	v_add_u32_e32 v97, -1, v181
	v_fma_f32 v100, -v97, v181, v180
	v_cmp_ge_f32_e64 s[0:1], 0, v100
	v_add_u32_e32 v100, 1, v181
	s_nop 0
	v_cndmask_b32_e64 v97, v181, v97, s[0:1]
	v_fma_f32 v181, -v100, v181, v180
	v_cmp_lt_f32_e64 s[0:1], 0, v181
	s_nop 1
	v_cndmask_b32_e64 v181, v97, v100, s[0:1]
	v_mul_f32_e32 v97, 0x37800000, v181
	v_cndmask_b32_e32 v181, v181, v97, vcc
	v_cmp_class_f32_e32 vcc, v180, v92
	s_nop 1
	v_cndmask_b32_e32 v180, v181, v180, vcc
	v_div_scale_f32 v181, s[0:1], v180, v180, 1.0
	v_rcp_f32_e32 v97, v181
	s_nop 0
	v_fma_f32 v100, -v181, v97, 1.0
	v_fmac_f32_e32 v97, v100, v97
	v_div_scale_f32 v100, vcc, 1.0, v180, 1.0
	v_mul_f32_e32 v101, v100, v97
	v_fma_f32 v104, -v181, v101, v100
	v_fmac_f32_e32 v101, v104, v97
	v_fma_f32 v181, -v181, v101, v100
	v_div_fmas_f32 v181, v181, v97, v101
	v_div_fixup_f32 v100, v181, v180, 1.0
	v_mov_b32_e32 v180, v182
	v_mov_b32_e32 v181, v176
	v_mov_b32_e32 v176, v183
	v_pk_mul_f32 v[180:181], v[100:101], v[180:181] op_sel_hi:[0,1]
	v_pk_mul_f32 v[182:183], v[100:101], v[176:177] op_sel_hi:[0,1]
	v_mov_b32_e32 v176, v102
	v_mov_b32_e32 v177, v178
	v_mov_b32_e32 v178, v103
	v_pk_fma_f32 v[182:183], v[70:71], v[182:183], v[22:23]
	v_pk_fma_f32 v[180:181], v[72:73], v[180:181], v[20:21]
	v_pk_mul_f32 v[176:177], v[100:101], v[176:177] op_sel_hi:[0,1]
	v_pk_mul_f32 v[178:179], v[100:101], v[178:179] op_sel_hi:[0,1]
	s_mov_b64 s[6:7], 0x800
	v_lshl_add_u64 v[104:105], s[6:7], 1, v[68:69]
	v_pk_fma_f32 v[178:179], v[74:75], v[178:179], v[18:19]
	v_pk_fma_f32 v[176:177], v[76:77], v[176:177], v[16:17]
	v_cvt_pk_bf16_f32 v180, v180, v181
	v_cvt_pk_bf16_f32 v181, v182, v183
	v_mov_b32_e32 v97, v61
	v_cvt_pk_bf16_f32 v182, v176, v177
	v_cvt_pk_bf16_f32 v183, v178, v179
	global_store_dwordx4 v[104:105], v[180:183], off
	v_pk_mul_f32 v[176:177], v[96:97], v[100:101] op_sel_hi:[1,0]
	v_pk_mul_f32 v[178:179], v[98:99], v[100:101] op_sel_hi:[1,0]
	v_pk_mul_f32 v[180:181], v[94:95], v[100:101] op_sel_hi:[1,0]
	v_pk_mul_f32 v[182:183], v[108:109], v[100:101] op_sel_hi:[1,0]
	v_pk_fma_f32 v[180:181], v[80:81], v[180:181], v[28:29]
	v_pk_fma_f32 v[182:183], v[78:79], v[182:183], v[30:31]
	v_pk_fma_f32 v[178:179], v[82:83], v[178:179], v[26:27]
	v_pk_fma_f32 v[176:177], v[84:85], v[176:177], v[24:25]
	v_cvt_pk_bf16_f32 v180, v180, v181
	v_cvt_pk_bf16_f32 v181, v182, v183
	s_nop 0
	v_cvt_pk_bf16_f32 v182, v176, v177
	v_cvt_pk_bf16_f32 v183, v178, v179
	global_store_dwordx4 v[104:105], v[180:183], off offset:1024
	s_nop 0
	s_nop 0
	s_nop 0
	s_nop 0
	s_nop 0
	s_nop 0
	s_nop 0
	s_nop 0
	s_waitcnt vmcnt(14)
	v_lshlrev_b32_e32 v96, 16, v190
	v_and_b32_e32 v61, 0xffff0000, v190
	v_lshlrev_b32_e32 v98, 16, v191
	v_and_b32_e32 v99, 0xffff0000, v191
	v_lshlrev_b32_e32 v191, 16, v185
	v_lshlrev_b32_e32 v190, 16, v184
	v_and_b32_e32 v185, 0xffff0000, v185
	v_and_b32_e32 v184, 0xffff0000, v184
	v_lshlrev_b32_e32 v103, 16, v187
	v_lshlrev_b32_e32 v102, 16, v186
	v_and_b32_e32 v187, 0xffff0000, v187
	v_and_b32_e32 v186, 0xffff0000, v186
	v_lshlrev_b32_e32 v94, 16, v188
	v_and_b32_e32 v95, 0xffff0000, v188
	v_pk_mul_f32 v[100:101], v[184:185], v[184:185]
	v_pk_mul_f32 v[104:105], v[186:187], v[186:187]
	v_lshlrev_b32_e32 v108, 16, v189
	v_pk_fma_f32 v[100:101], v[190:191], v[190:191], v[100:101]
	v_pk_fma_f32 v[104:105], v[102:103], v[102:103], v[104:105]
	v_mul_f32_e32 v97, v94, v94
	v_mul_f32_e32 v107, v95, v95
	v_and_b32_e32 v109, 0xffff0000, v189
	v_mul_f32_e32 v188, v108, v108
	v_mov_b32_e32 v106, v96
	v_pk_add_f32 v[100:101], v[100:101], v[100:101] op_sel_hi:[0,1]
	v_pk_add_f32 v[104:105], v[104:105], v[104:105] op_sel_hi:[0,1]
	v_pk_fma_f32 v[188:189], v[108:109], v[108:109], v[188:189] op_sel_hi:[1,1,0]
	v_pk_add_f32 v[106:107], v[96:97], v[106:107]
	v_mul_f32_e32 v188, v61, v61
	v_mul_f32_e32 v100, v98, v98
	v_mul_f32_e32 v104, v99, v99
	v_mul_f32_e32 v110, v96, v96
	v_mov_b32_e32 v111, v107
	v_pk_add_f32 v[188:189], v[110:111], v[188:189]
	v_pk_add_f32 v[100:101], v[100:101], v[104:105]
	v_pk_add_f32 v[188:189], v[188:189], v[100:101]
	v_add_f32_e32 v188, v188, v189
	ds_bpermute_b32 v189, v51, v188
	s_waitcnt lgkmcnt(0)
	v_add_f32_e32 v188, v188, v189
	ds_bpermute_b32 v189, v87, v188
	s_waitcnt lgkmcnt(0)
	v_add_f32_e32 v188, v188, v189
	ds_bpermute_b32 v189, v88, v188
	s_waitcnt lgkmcnt(0)
	v_add_f32_e32 v188, v188, v189
	ds_bpermute_b32 v189, v89, v188
	s_waitcnt lgkmcnt(0)
	v_add_f32_e32 v188, v188, v189
	ds_bpermute_b32 v189, v90, v188
	s_waitcnt lgkmcnt(0)
	v_add_f32_e32 v188, v188, v189
	ds_bpermute_b32 v189, v91, v188
	s_waitcnt lgkmcnt(0)
	v_add_f32_e32 v188, v188, v189
	v_fmamk_f32 v188, v188, 0x3a800000, v49
	v_mul_f32_e32 v189, 0x4f800000, v188
	v_cmp_gt_f32_e32 vcc, s9, v188
	s_nop 1
	v_cndmask_b32_e32 v188, v188, v189, vcc
	v_sqrt_f32_e32 v189, v188
	s_nop 0
	v_add_u32_e32 v97, -1, v189
	v_fma_f32 v100, -v97, v189, v188
	v_cmp_ge_f32_e64 s[0:1], 0, v100
	v_add_u32_e32 v100, 1, v189
	s_nop 0
	v_cndmask_b32_e64 v97, v189, v97, s[0:1]
	v_fma_f32 v189, -v100, v189, v188
	v_cmp_lt_f32_e64 s[0:1], 0, v189
	s_nop 1
	v_cndmask_b32_e64 v189, v97, v100, s[0:1]
	v_mul_f32_e32 v97, 0x37800000, v189
	v_cndmask_b32_e32 v189, v189, v97, vcc
	v_cmp_class_f32_e32 vcc, v188, v92
	s_nop 1
	v_cndmask_b32_e32 v188, v189, v188, vcc
	v_div_scale_f32 v189, s[0:1], v188, v188, 1.0
	v_rcp_f32_e32 v97, v189
	s_nop 0
	v_fma_f32 v100, -v189, v97, 1.0
	v_fmac_f32_e32 v97, v100, v97
	v_div_scale_f32 v100, vcc, 1.0, v188, 1.0
	v_mul_f32_e32 v101, v100, v97
	v_fma_f32 v104, -v189, v101, v100
	v_fmac_f32_e32 v101, v104, v97
	v_fma_f32 v189, -v189, v101, v100
	v_div_fmas_f32 v189, v189, v97, v101
	v_div_fixup_f32 v100, v189, v188, 1.0
	v_mov_b32_e32 v188, v190
	v_mov_b32_e32 v189, v184
	v_mov_b32_e32 v184, v191
	v_pk_mul_f32 v[188:189], v[100:101], v[188:189] op_sel_hi:[0,1]
	v_pk_mul_f32 v[190:191], v[100:101], v[184:185] op_sel_hi:[0,1]
	v_mov_b32_e32 v184, v102
	v_mov_b32_e32 v185, v186
	v_mov_b32_e32 v186, v103
	v_pk_fma_f32 v[190:191], v[70:71], v[190:191], v[22:23]
	v_pk_fma_f32 v[188:189], v[72:73], v[188:189], v[20:21]
	v_pk_mul_f32 v[184:185], v[100:101], v[184:185] op_sel_hi:[0,1]
	v_pk_mul_f32 v[186:187], v[100:101], v[186:187] op_sel_hi:[0,1]
	s_mov_b64 s[6:7], 0xc00
	v_lshl_add_u64 v[104:105], s[6:7], 1, v[68:69]
	v_pk_fma_f32 v[186:187], v[74:75], v[186:187], v[18:19]
	v_pk_fma_f32 v[184:185], v[76:77], v[184:185], v[16:17]
	v_cvt_pk_bf16_f32 v188, v188, v189
	v_cvt_pk_bf16_f32 v189, v190, v191
	v_mov_b32_e32 v97, v61
	v_cvt_pk_bf16_f32 v190, v184, v185
	v_cvt_pk_bf16_f32 v191, v186, v187
	global_store_dwordx4 v[104:105], v[188:191], off
	v_pk_mul_f32 v[184:185], v[96:97], v[100:101] op_sel_hi:[1,0]
	v_pk_mul_f32 v[186:187], v[98:99], v[100:101] op_sel_hi:[1,0]
	v_pk_mul_f32 v[188:189], v[94:95], v[100:101] op_sel_hi:[1,0]
	v_pk_mul_f32 v[190:191], v[108:109], v[100:101] op_sel_hi:[1,0]
	v_pk_fma_f32 v[188:189], v[80:81], v[188:189], v[28:29]
	v_pk_fma_f32 v[190:191], v[78:79], v[190:191], v[30:31]
	v_pk_fma_f32 v[186:187], v[82:83], v[186:187], v[26:27]
	v_pk_fma_f32 v[184:185], v[84:85], v[184:185], v[24:25]
	v_cvt_pk_bf16_f32 v188, v188, v189
	v_cvt_pk_bf16_f32 v189, v190, v191
	s_nop 0
	v_cvt_pk_bf16_f32 v190, v184, v185
	v_cvt_pk_bf16_f32 v191, v186, v187
	global_store_dwordx4 v[104:105], v[188:191], off offset:1024
	s_nop 0
	s_nop 0
	s_nop 0
	s_nop 0
	s_nop 0
	s_nop 0
	s_nop 0
	s_nop 0
	s_waitcnt vmcnt(14)
	v_lshlrev_b32_e32 v96, 16, v198
	v_and_b32_e32 v61, 0xffff0000, v198
	v_lshlrev_b32_e32 v98, 16, v199
	v_and_b32_e32 v99, 0xffff0000, v199
	v_lshlrev_b32_e32 v199, 16, v193
	v_lshlrev_b32_e32 v198, 16, v192
	v_and_b32_e32 v193, 0xffff0000, v193
	v_and_b32_e32 v192, 0xffff0000, v192
	v_lshlrev_b32_e32 v103, 16, v195
	v_lshlrev_b32_e32 v102, 16, v194
	v_and_b32_e32 v195, 0xffff0000, v195
	v_and_b32_e32 v194, 0xffff0000, v194
	v_lshlrev_b32_e32 v94, 16, v196
	v_and_b32_e32 v95, 0xffff0000, v196
	v_pk_mul_f32 v[100:101], v[192:193], v[192:193]
	v_pk_mul_f32 v[104:105], v[194:195], v[194:195]
	v_lshlrev_b32_e32 v108, 16, v197
	v_pk_fma_f32 v[100:101], v[198:199], v[198:199], v[100:101]
	v_pk_fma_f32 v[104:105], v[102:103], v[102:103], v[104:105]
	v_mul_f32_e32 v97, v94, v94
	v_mul_f32_e32 v107, v95, v95
	v_and_b32_e32 v109, 0xffff0000, v197
	v_mul_f32_e32 v196, v108, v108
	v_mov_b32_e32 v106, v96
	v_pk_add_f32 v[100:101], v[100:101], v[100:101] op_sel_hi:[0,1]
	v_pk_add_f32 v[104:105], v[104:105], v[104:105] op_sel_hi:[0,1]
	v_pk_fma_f32 v[196:197], v[108:109], v[108:109], v[196:197] op_sel_hi:[1,1,0]
	v_pk_add_f32 v[106:107], v[96:97], v[106:107]
	v_mul_f32_e32 v196, v61, v61
	v_mul_f32_e32 v100, v98, v98
	v_mul_f32_e32 v104, v99, v99
	v_mul_f32_e32 v110, v96, v96
	v_mov_b32_e32 v111, v107
	v_pk_add_f32 v[196:197], v[110:111], v[196:197]
	v_pk_add_f32 v[100:101], v[100:101], v[104:105]
	v_pk_add_f32 v[196:197], v[196:197], v[100:101]
	v_add_f32_e32 v196, v196, v197
	ds_bpermute_b32 v197, v51, v196
	s_waitcnt lgkmcnt(0)
	v_add_f32_e32 v196, v196, v197
	ds_bpermute_b32 v197, v87, v196
	s_waitcnt lgkmcnt(0)
	v_add_f32_e32 v196, v196, v197
	ds_bpermute_b32 v197, v88, v196
	s_waitcnt lgkmcnt(0)
	v_add_f32_e32 v196, v196, v197
	ds_bpermute_b32 v197, v89, v196
	s_waitcnt lgkmcnt(0)
	v_add_f32_e32 v196, v196, v197
	ds_bpermute_b32 v197, v90, v196
	s_waitcnt lgkmcnt(0)
	v_add_f32_e32 v196, v196, v197
	ds_bpermute_b32 v197, v91, v196
	s_waitcnt lgkmcnt(0)
	v_add_f32_e32 v196, v196, v197
	v_fmamk_f32 v196, v196, 0x3a800000, v49
	v_mul_f32_e32 v197, 0x4f800000, v196
	v_cmp_gt_f32_e32 vcc, s9, v196
	s_nop 1
	v_cndmask_b32_e32 v196, v196, v197, vcc
	v_sqrt_f32_e32 v197, v196
	s_nop 0
	v_add_u32_e32 v97, -1, v197
	v_fma_f32 v100, -v97, v197, v196
	v_cmp_ge_f32_e64 s[0:1], 0, v100
	v_add_u32_e32 v100, 1, v197
	s_nop 0
	v_cndmask_b32_e64 v97, v197, v97, s[0:1]
	v_fma_f32 v197, -v100, v197, v196
	v_cmp_lt_f32_e64 s[0:1], 0, v197
	s_nop 1
	v_cndmask_b32_e64 v197, v97, v100, s[0:1]
	v_mul_f32_e32 v97, 0x37800000, v197
	v_cndmask_b32_e32 v197, v197, v97, vcc
	v_cmp_class_f32_e32 vcc, v196, v92
	s_nop 1
	v_cndmask_b32_e32 v196, v197, v196, vcc
	v_div_scale_f32 v197, s[0:1], v196, v196, 1.0
	v_rcp_f32_e32 v97, v197
	s_nop 0
	v_fma_f32 v100, -v197, v97, 1.0
	v_fmac_f32_e32 v97, v100, v97
	v_div_scale_f32 v100, vcc, 1.0, v196, 1.0
	v_mul_f32_e32 v101, v100, v97
	v_fma_f32 v104, -v197, v101, v100
	v_fmac_f32_e32 v101, v104, v97
	v_fma_f32 v197, -v197, v101, v100
	v_div_fmas_f32 v197, v197, v97, v101
	v_div_fixup_f32 v100, v197, v196, 1.0
	v_mov_b32_e32 v196, v198
	v_mov_b32_e32 v197, v192
	v_mov_b32_e32 v192, v199
	v_pk_mul_f32 v[196:197], v[100:101], v[196:197] op_sel_hi:[0,1]
	v_pk_mul_f32 v[198:199], v[100:101], v[192:193] op_sel_hi:[0,1]
	v_mov_b32_e32 v192, v102
	v_mov_b32_e32 v193, v194
	v_mov_b32_e32 v194, v103
	v_pk_fma_f32 v[198:199], v[70:71], v[198:199], v[22:23]
	v_pk_fma_f32 v[196:197], v[72:73], v[196:197], v[20:21]
	v_pk_mul_f32 v[192:193], v[100:101], v[192:193] op_sel_hi:[0,1]
	v_pk_mul_f32 v[194:195], v[100:101], v[194:195] op_sel_hi:[0,1]
	s_mov_b64 s[6:7], 0x1000
	v_lshl_add_u64 v[104:105], s[6:7], 1, v[68:69]
	v_pk_fma_f32 v[194:195], v[74:75], v[194:195], v[18:19]
	v_pk_fma_f32 v[192:193], v[76:77], v[192:193], v[16:17]
	v_cvt_pk_bf16_f32 v196, v196, v197
	v_cvt_pk_bf16_f32 v197, v198, v199
	v_mov_b32_e32 v97, v61
	v_cvt_pk_bf16_f32 v198, v192, v193
	v_cvt_pk_bf16_f32 v199, v194, v195
	global_store_dwordx4 v[104:105], v[196:199], off
	v_pk_mul_f32 v[192:193], v[96:97], v[100:101] op_sel_hi:[1,0]
	v_pk_mul_f32 v[194:195], v[98:99], v[100:101] op_sel_hi:[1,0]
	v_pk_mul_f32 v[196:197], v[94:95], v[100:101] op_sel_hi:[1,0]
	v_pk_mul_f32 v[198:199], v[108:109], v[100:101] op_sel_hi:[1,0]
	v_pk_fma_f32 v[196:197], v[80:81], v[196:197], v[28:29]
	v_pk_fma_f32 v[198:199], v[78:79], v[198:199], v[30:31]
	v_pk_fma_f32 v[194:195], v[82:83], v[194:195], v[26:27]
	v_pk_fma_f32 v[192:193], v[84:85], v[192:193], v[24:25]
	v_cvt_pk_bf16_f32 v196, v196, v197
	v_cvt_pk_bf16_f32 v197, v198, v199
	s_nop 0
	v_cvt_pk_bf16_f32 v198, v192, v193
	v_cvt_pk_bf16_f32 v199, v194, v195
	global_store_dwordx4 v[104:105], v[196:199], off offset:1024
	s_nop 0
	s_nop 0
	s_nop 0
	s_nop 0
	s_nop 0
	s_nop 0
	s_nop 0
	s_nop 0
	s_waitcnt vmcnt(14)
	v_lshlrev_b32_e32 v96, 16, v206
	v_and_b32_e32 v61, 0xffff0000, v206
	v_lshlrev_b32_e32 v98, 16, v207
	v_and_b32_e32 v99, 0xffff0000, v207
	v_lshlrev_b32_e32 v207, 16, v201
	v_lshlrev_b32_e32 v206, 16, v200
	v_and_b32_e32 v201, 0xffff0000, v201
	v_and_b32_e32 v200, 0xffff0000, v200
	v_lshlrev_b32_e32 v103, 16, v203
	v_lshlrev_b32_e32 v102, 16, v202
	v_and_b32_e32 v203, 0xffff0000, v203
	v_and_b32_e32 v202, 0xffff0000, v202
	v_lshlrev_b32_e32 v94, 16, v204
	v_and_b32_e32 v95, 0xffff0000, v204
	v_pk_mul_f32 v[100:101], v[200:201], v[200:201]
	v_pk_mul_f32 v[104:105], v[202:203], v[202:203]
	v_lshlrev_b32_e32 v108, 16, v205
	v_pk_fma_f32 v[100:101], v[206:207], v[206:207], v[100:101]
	v_pk_fma_f32 v[104:105], v[102:103], v[102:103], v[104:105]
	v_mul_f32_e32 v97, v94, v94
	v_mul_f32_e32 v107, v95, v95
	v_and_b32_e32 v109, 0xffff0000, v205
	v_mul_f32_e32 v204, v108, v108
	v_mov_b32_e32 v106, v96
	v_pk_add_f32 v[100:101], v[100:101], v[100:101] op_sel_hi:[0,1]
	v_pk_add_f32 v[104:105], v[104:105], v[104:105] op_sel_hi:[0,1]
	v_pk_fma_f32 v[204:205], v[108:109], v[108:109], v[204:205] op_sel_hi:[1,1,0]
	v_pk_add_f32 v[106:107], v[96:97], v[106:107]
	v_mul_f32_e32 v204, v61, v61
	v_mul_f32_e32 v100, v98, v98
	v_mul_f32_e32 v104, v99, v99
	v_mul_f32_e32 v110, v96, v96
	v_mov_b32_e32 v111, v107
	v_pk_add_f32 v[204:205], v[110:111], v[204:205]
	v_pk_add_f32 v[100:101], v[100:101], v[104:105]
	v_pk_add_f32 v[204:205], v[204:205], v[100:101]
	v_add_f32_e32 v204, v204, v205
	ds_bpermute_b32 v205, v51, v204
	s_waitcnt lgkmcnt(0)
	v_add_f32_e32 v204, v204, v205
	ds_bpermute_b32 v205, v87, v204
	s_waitcnt lgkmcnt(0)
	v_add_f32_e32 v204, v204, v205
	ds_bpermute_b32 v205, v88, v204
	s_waitcnt lgkmcnt(0)
	v_add_f32_e32 v204, v204, v205
	ds_bpermute_b32 v205, v89, v204
	s_waitcnt lgkmcnt(0)
	v_add_f32_e32 v204, v204, v205
	ds_bpermute_b32 v205, v90, v204
	s_waitcnt lgkmcnt(0)
	v_add_f32_e32 v204, v204, v205
	ds_bpermute_b32 v205, v91, v204
	s_waitcnt lgkmcnt(0)
	v_add_f32_e32 v204, v204, v205
	v_fmamk_f32 v204, v204, 0x3a800000, v49
	v_mul_f32_e32 v205, 0x4f800000, v204
	v_cmp_gt_f32_e32 vcc, s9, v204
	s_nop 1
	v_cndmask_b32_e32 v204, v204, v205, vcc
	v_sqrt_f32_e32 v205, v204
	s_nop 0
	v_add_u32_e32 v97, -1, v205
	v_fma_f32 v100, -v97, v205, v204
	v_cmp_ge_f32_e64 s[0:1], 0, v100
	v_add_u32_e32 v100, 1, v205
	s_nop 0
	v_cndmask_b32_e64 v97, v205, v97, s[0:1]
	v_fma_f32 v205, -v100, v205, v204
	v_cmp_lt_f32_e64 s[0:1], 0, v205
	s_nop 1
	v_cndmask_b32_e64 v205, v97, v100, s[0:1]
	v_mul_f32_e32 v97, 0x37800000, v205
	v_cndmask_b32_e32 v205, v205, v97, vcc
	v_cmp_class_f32_e32 vcc, v204, v92
	s_nop 1
	v_cndmask_b32_e32 v204, v205, v204, vcc
	v_div_scale_f32 v205, s[0:1], v204, v204, 1.0
	v_rcp_f32_e32 v97, v205
	s_nop 0
	v_fma_f32 v100, -v205, v97, 1.0
	v_fmac_f32_e32 v97, v100, v97
	v_div_scale_f32 v100, vcc, 1.0, v204, 1.0
	v_mul_f32_e32 v101, v100, v97
	v_fma_f32 v104, -v205, v101, v100
	v_fmac_f32_e32 v101, v104, v97
	v_fma_f32 v205, -v205, v101, v100
	v_div_fmas_f32 v205, v205, v97, v101
	v_div_fixup_f32 v100, v205, v204, 1.0
	v_mov_b32_e32 v204, v206
	v_mov_b32_e32 v205, v200
	v_mov_b32_e32 v200, v207
	v_pk_mul_f32 v[204:205], v[100:101], v[204:205] op_sel_hi:[0,1]
	v_pk_mul_f32 v[206:207], v[100:101], v[200:201] op_sel_hi:[0,1]
	v_mov_b32_e32 v200, v102
	v_mov_b32_e32 v201, v202
	v_mov_b32_e32 v202, v103
	v_pk_fma_f32 v[206:207], v[70:71], v[206:207], v[22:23]
	v_pk_fma_f32 v[204:205], v[72:73], v[204:205], v[20:21]
	v_pk_mul_f32 v[200:201], v[100:101], v[200:201] op_sel_hi:[0,1]
	v_pk_mul_f32 v[202:203], v[100:101], v[202:203] op_sel_hi:[0,1]
	s_mov_b64 s[6:7], 0x1400
	v_lshl_add_u64 v[104:105], s[6:7], 1, v[68:69]
	v_pk_fma_f32 v[202:203], v[74:75], v[202:203], v[18:19]
	v_pk_fma_f32 v[200:201], v[76:77], v[200:201], v[16:17]
	v_cvt_pk_bf16_f32 v204, v204, v205
	v_cvt_pk_bf16_f32 v205, v206, v207
	v_mov_b32_e32 v97, v61
	v_cvt_pk_bf16_f32 v206, v200, v201
	v_cvt_pk_bf16_f32 v207, v202, v203
	global_store_dwordx4 v[104:105], v[204:207], off
	v_pk_mul_f32 v[200:201], v[96:97], v[100:101] op_sel_hi:[1,0]
	v_pk_mul_f32 v[202:203], v[98:99], v[100:101] op_sel_hi:[1,0]
	v_pk_mul_f32 v[204:205], v[94:95], v[100:101] op_sel_hi:[1,0]
	v_pk_mul_f32 v[206:207], v[108:109], v[100:101] op_sel_hi:[1,0]
	v_pk_fma_f32 v[204:205], v[80:81], v[204:205], v[28:29]
	v_pk_fma_f32 v[206:207], v[78:79], v[206:207], v[30:31]
	v_pk_fma_f32 v[202:203], v[82:83], v[202:203], v[26:27]
	v_pk_fma_f32 v[200:201], v[84:85], v[200:201], v[24:25]
	v_cvt_pk_bf16_f32 v204, v204, v205
	v_cvt_pk_bf16_f32 v205, v206, v207
	s_nop 0
	v_cvt_pk_bf16_f32 v206, v200, v201
	v_cvt_pk_bf16_f32 v207, v202, v203
	global_store_dwordx4 v[104:105], v[204:207], off offset:1024
	s_nop 0
	s_nop 0
	s_nop 0
	s_nop 0
	s_nop 0
	s_nop 0
	s_nop 0
	s_nop 0
	s_waitcnt vmcnt(14)
	v_lshlrev_b32_e32 v96, 16, v214
	v_and_b32_e32 v61, 0xffff0000, v214
	v_lshlrev_b32_e32 v98, 16, v215
	v_and_b32_e32 v99, 0xffff0000, v215
	v_lshlrev_b32_e32 v215, 16, v209
	v_lshlrev_b32_e32 v214, 16, v208
	v_and_b32_e32 v209, 0xffff0000, v209
	v_and_b32_e32 v208, 0xffff0000, v208
	v_lshlrev_b32_e32 v103, 16, v211
	v_lshlrev_b32_e32 v102, 16, v210
	v_and_b32_e32 v211, 0xffff0000, v211
	v_and_b32_e32 v210, 0xffff0000, v210
	v_lshlrev_b32_e32 v94, 16, v212
	v_and_b32_e32 v95, 0xffff0000, v212
	v_pk_mul_f32 v[100:101], v[208:209], v[208:209]
	v_pk_mul_f32 v[104:105], v[210:211], v[210:211]
	v_lshlrev_b32_e32 v108, 16, v213
	v_pk_fma_f32 v[100:101], v[214:215], v[214:215], v[100:101]
	v_pk_fma_f32 v[104:105], v[102:103], v[102:103], v[104:105]
	v_mul_f32_e32 v97, v94, v94
	v_mul_f32_e32 v107, v95, v95
	v_and_b32_e32 v109, 0xffff0000, v213
	v_mul_f32_e32 v212, v108, v108
	v_mov_b32_e32 v106, v96
	v_pk_add_f32 v[100:101], v[100:101], v[100:101] op_sel_hi:[0,1]
	v_pk_add_f32 v[104:105], v[104:105], v[104:105] op_sel_hi:[0,1]
	v_pk_fma_f32 v[212:213], v[108:109], v[108:109], v[212:213] op_sel_hi:[1,1,0]
	v_pk_add_f32 v[106:107], v[96:97], v[106:107]
	v_mul_f32_e32 v212, v61, v61
	v_mul_f32_e32 v100, v98, v98
	v_mul_f32_e32 v104, v99, v99
	v_mul_f32_e32 v110, v96, v96
	v_mov_b32_e32 v111, v107
	v_pk_add_f32 v[212:213], v[110:111], v[212:213]
	v_pk_add_f32 v[100:101], v[100:101], v[104:105]
	v_pk_add_f32 v[212:213], v[212:213], v[100:101]
	v_add_f32_e32 v212, v212, v213
	ds_bpermute_b32 v213, v51, v212
	s_waitcnt lgkmcnt(0)
	v_add_f32_e32 v212, v212, v213
	ds_bpermute_b32 v213, v87, v212
	s_waitcnt lgkmcnt(0)
	v_add_f32_e32 v212, v212, v213
	ds_bpermute_b32 v213, v88, v212
	s_waitcnt lgkmcnt(0)
	v_add_f32_e32 v212, v212, v213
	ds_bpermute_b32 v213, v89, v212
	s_waitcnt lgkmcnt(0)
	v_add_f32_e32 v212, v212, v213
	ds_bpermute_b32 v213, v90, v212
	s_waitcnt lgkmcnt(0)
	v_add_f32_e32 v212, v212, v213
	ds_bpermute_b32 v213, v91, v212
	s_waitcnt lgkmcnt(0)
	v_add_f32_e32 v212, v212, v213
	v_fmamk_f32 v212, v212, 0x3a800000, v49
	v_mul_f32_e32 v213, 0x4f800000, v212
	v_cmp_gt_f32_e32 vcc, s9, v212
	s_nop 1
	v_cndmask_b32_e32 v212, v212, v213, vcc
	v_sqrt_f32_e32 v213, v212
	s_nop 0
	v_add_u32_e32 v97, -1, v213
	v_fma_f32 v100, -v97, v213, v212
	v_cmp_ge_f32_e64 s[0:1], 0, v100
	v_add_u32_e32 v100, 1, v213
	s_nop 0
	v_cndmask_b32_e64 v97, v213, v97, s[0:1]
	v_fma_f32 v213, -v100, v213, v212
	v_cmp_lt_f32_e64 s[0:1], 0, v213
	s_nop 1
	v_cndmask_b32_e64 v213, v97, v100, s[0:1]
	v_mul_f32_e32 v97, 0x37800000, v213
	v_cndmask_b32_e32 v213, v213, v97, vcc
	v_cmp_class_f32_e32 vcc, v212, v92
	s_nop 1
	v_cndmask_b32_e32 v212, v213, v212, vcc
	v_div_scale_f32 v213, s[0:1], v212, v212, 1.0
	v_rcp_f32_e32 v97, v213
	s_nop 0
	v_fma_f32 v100, -v213, v97, 1.0
	v_fmac_f32_e32 v97, v100, v97
	v_div_scale_f32 v100, vcc, 1.0, v212, 1.0
	v_mul_f32_e32 v101, v100, v97
	v_fma_f32 v104, -v213, v101, v100
	v_fmac_f32_e32 v101, v104, v97
	v_fma_f32 v213, -v213, v101, v100
	v_div_fmas_f32 v213, v213, v97, v101
	v_div_fixup_f32 v100, v213, v212, 1.0
	v_mov_b32_e32 v212, v214
	v_mov_b32_e32 v213, v208
	v_mov_b32_e32 v208, v215
	v_pk_mul_f32 v[212:213], v[100:101], v[212:213] op_sel_hi:[0,1]
	v_pk_mul_f32 v[214:215], v[100:101], v[208:209] op_sel_hi:[0,1]
	v_mov_b32_e32 v208, v102
	v_mov_b32_e32 v209, v210
	v_mov_b32_e32 v210, v103
	v_pk_fma_f32 v[214:215], v[70:71], v[214:215], v[22:23]
	v_pk_fma_f32 v[212:213], v[72:73], v[212:213], v[20:21]
	v_pk_mul_f32 v[208:209], v[100:101], v[208:209] op_sel_hi:[0,1]
	v_pk_mul_f32 v[210:211], v[100:101], v[210:211] op_sel_hi:[0,1]
	s_mov_b64 s[6:7], 0x1800
	v_lshl_add_u64 v[104:105], s[6:7], 1, v[68:69]
	v_pk_fma_f32 v[210:211], v[74:75], v[210:211], v[18:19]
	v_pk_fma_f32 v[208:209], v[76:77], v[208:209], v[16:17]
	v_cvt_pk_bf16_f32 v212, v212, v213
	v_cvt_pk_bf16_f32 v213, v214, v215
	v_mov_b32_e32 v97, v61
	v_cvt_pk_bf16_f32 v214, v208, v209
	v_cvt_pk_bf16_f32 v215, v210, v211
	global_store_dwordx4 v[104:105], v[212:215], off
	v_pk_mul_f32 v[208:209], v[96:97], v[100:101] op_sel_hi:[1,0]
	v_pk_mul_f32 v[210:211], v[98:99], v[100:101] op_sel_hi:[1,0]
	v_pk_mul_f32 v[212:213], v[94:95], v[100:101] op_sel_hi:[1,0]
	v_pk_mul_f32 v[214:215], v[108:109], v[100:101] op_sel_hi:[1,0]
	v_pk_fma_f32 v[212:213], v[80:81], v[212:213], v[28:29]
	v_pk_fma_f32 v[214:215], v[78:79], v[214:215], v[30:31]
	v_pk_fma_f32 v[210:211], v[82:83], v[210:211], v[26:27]
	v_pk_fma_f32 v[208:209], v[84:85], v[208:209], v[24:25]
	v_cvt_pk_bf16_f32 v212, v212, v213
	v_cvt_pk_bf16_f32 v213, v214, v215
	s_nop 0
	v_cvt_pk_bf16_f32 v214, v208, v209
	v_cvt_pk_bf16_f32 v215, v210, v211
	global_store_dwordx4 v[104:105], v[212:215], off offset:1024
	s_nop 0
	s_nop 0
	s_nop 0
	s_nop 0
	s_nop 0
	s_nop 0
	s_nop 0
	s_nop 0
	s_waitcnt vmcnt(14)
	v_lshlrev_b32_e32 v96, 16, v222
	v_and_b32_e32 v61, 0xffff0000, v222
	v_lshlrev_b32_e32 v98, 16, v223
	v_and_b32_e32 v99, 0xffff0000, v223
	v_lshlrev_b32_e32 v223, 16, v217
	v_lshlrev_b32_e32 v222, 16, v216
	v_and_b32_e32 v217, 0xffff0000, v217
	v_and_b32_e32 v216, 0xffff0000, v216
	v_lshlrev_b32_e32 v103, 16, v219
	v_lshlrev_b32_e32 v102, 16, v218
	v_and_b32_e32 v219, 0xffff0000, v219
	v_and_b32_e32 v218, 0xffff0000, v218
	v_lshlrev_b32_e32 v94, 16, v220
	v_and_b32_e32 v95, 0xffff0000, v220
	v_pk_mul_f32 v[100:101], v[216:217], v[216:217]
	v_pk_mul_f32 v[104:105], v[218:219], v[218:219]
	v_lshlrev_b32_e32 v108, 16, v221
	v_pk_fma_f32 v[100:101], v[222:223], v[222:223], v[100:101]
	v_pk_fma_f32 v[104:105], v[102:103], v[102:103], v[104:105]
	v_mul_f32_e32 v97, v94, v94
	v_mul_f32_e32 v107, v95, v95
	v_and_b32_e32 v109, 0xffff0000, v221
	v_mul_f32_e32 v220, v108, v108
	v_mov_b32_e32 v106, v96
	v_pk_add_f32 v[100:101], v[100:101], v[100:101] op_sel_hi:[0,1]
	v_pk_add_f32 v[104:105], v[104:105], v[104:105] op_sel_hi:[0,1]
	v_pk_fma_f32 v[220:221], v[108:109], v[108:109], v[220:221] op_sel_hi:[1,1,0]
	v_pk_add_f32 v[106:107], v[96:97], v[106:107]
	v_mul_f32_e32 v220, v61, v61
	v_mul_f32_e32 v100, v98, v98
	v_mul_f32_e32 v104, v99, v99
	v_mul_f32_e32 v110, v96, v96
	v_mov_b32_e32 v111, v107
	v_pk_add_f32 v[220:221], v[110:111], v[220:221]
	v_pk_add_f32 v[100:101], v[100:101], v[104:105]
	v_pk_add_f32 v[220:221], v[220:221], v[100:101]
	v_add_f32_e32 v220, v220, v221
	ds_bpermute_b32 v221, v51, v220
	s_waitcnt lgkmcnt(0)
	v_add_f32_e32 v220, v220, v221
	ds_bpermute_b32 v221, v87, v220
	s_waitcnt lgkmcnt(0)
	v_add_f32_e32 v220, v220, v221
	ds_bpermute_b32 v221, v88, v220
	s_waitcnt lgkmcnt(0)
	v_add_f32_e32 v220, v220, v221
	ds_bpermute_b32 v221, v89, v220
	s_waitcnt lgkmcnt(0)
	v_add_f32_e32 v220, v220, v221
	ds_bpermute_b32 v221, v90, v220
	s_waitcnt lgkmcnt(0)
	v_add_f32_e32 v220, v220, v221
	ds_bpermute_b32 v221, v91, v220
	s_waitcnt lgkmcnt(0)
	v_add_f32_e32 v220, v220, v221
	v_fmamk_f32 v220, v220, 0x3a800000, v49
	v_mul_f32_e32 v221, 0x4f800000, v220
	v_cmp_gt_f32_e32 vcc, s9, v220
	s_nop 1
	v_cndmask_b32_e32 v220, v220, v221, vcc
	v_sqrt_f32_e32 v221, v220
	s_nop 0
	v_add_u32_e32 v97, -1, v221
	v_fma_f32 v100, -v97, v221, v220
	v_cmp_ge_f32_e64 s[0:1], 0, v100
	v_add_u32_e32 v100, 1, v221
	s_nop 0
	v_cndmask_b32_e64 v97, v221, v97, s[0:1]
	v_fma_f32 v221, -v100, v221, v220
	v_cmp_lt_f32_e64 s[0:1], 0, v221
	s_nop 1
	v_cndmask_b32_e64 v221, v97, v100, s[0:1]
	v_mul_f32_e32 v97, 0x37800000, v221
	v_cndmask_b32_e32 v221, v221, v97, vcc
	v_cmp_class_f32_e32 vcc, v220, v92
	s_nop 1
	v_cndmask_b32_e32 v220, v221, v220, vcc
	v_div_scale_f32 v221, s[0:1], v220, v220, 1.0
	v_rcp_f32_e32 v97, v221
	s_nop 0
	v_fma_f32 v100, -v221, v97, 1.0
	v_fmac_f32_e32 v97, v100, v97
	v_div_scale_f32 v100, vcc, 1.0, v220, 1.0
	v_mul_f32_e32 v101, v100, v97
	v_fma_f32 v104, -v221, v101, v100
	v_fmac_f32_e32 v101, v104, v97
	v_fma_f32 v221, -v221, v101, v100
	v_div_fmas_f32 v221, v221, v97, v101
	v_div_fixup_f32 v100, v221, v220, 1.0
	v_mov_b32_e32 v220, v222
	v_mov_b32_e32 v221, v216
	v_mov_b32_e32 v216, v223
	v_pk_mul_f32 v[220:221], v[100:101], v[220:221] op_sel_hi:[0,1]
	v_pk_mul_f32 v[222:223], v[100:101], v[216:217] op_sel_hi:[0,1]
	v_mov_b32_e32 v216, v102
	v_mov_b32_e32 v217, v218
	v_mov_b32_e32 v218, v103
	v_pk_fma_f32 v[222:223], v[70:71], v[222:223], v[22:23]
	v_pk_fma_f32 v[220:221], v[72:73], v[220:221], v[20:21]
	v_pk_mul_f32 v[216:217], v[100:101], v[216:217] op_sel_hi:[0,1]
	v_pk_mul_f32 v[218:219], v[100:101], v[218:219] op_sel_hi:[0,1]
	s_mov_b64 s[6:7], 0x1c00
	v_lshl_add_u64 v[104:105], s[6:7], 1, v[68:69]
	v_pk_fma_f32 v[218:219], v[74:75], v[218:219], v[18:19]
	v_pk_fma_f32 v[216:217], v[76:77], v[216:217], v[16:17]
	v_cvt_pk_bf16_f32 v220, v220, v221
	v_cvt_pk_bf16_f32 v221, v222, v223
	v_mov_b32_e32 v97, v61
	v_cvt_pk_bf16_f32 v222, v216, v217
	v_cvt_pk_bf16_f32 v223, v218, v219
	global_store_dwordx4 v[104:105], v[220:223], off
	v_pk_mul_f32 v[216:217], v[96:97], v[100:101] op_sel_hi:[1,0]
	v_pk_mul_f32 v[218:219], v[98:99], v[100:101] op_sel_hi:[1,0]
	v_pk_mul_f32 v[220:221], v[94:95], v[100:101] op_sel_hi:[1,0]
	v_pk_mul_f32 v[222:223], v[108:109], v[100:101] op_sel_hi:[1,0]
	v_pk_fma_f32 v[220:221], v[80:81], v[220:221], v[28:29]
	v_pk_fma_f32 v[222:223], v[78:79], v[222:223], v[30:31]
	v_pk_fma_f32 v[218:219], v[82:83], v[218:219], v[26:27]
	v_pk_fma_f32 v[216:217], v[84:85], v[216:217], v[24:25]
	v_cvt_pk_bf16_f32 v220, v220, v221
	v_cvt_pk_bf16_f32 v221, v222, v223
	s_nop 0
	v_cvt_pk_bf16_f32 v222, v216, v217
	v_cvt_pk_bf16_f32 v223, v218, v219
	global_store_dwordx4 v[104:105], v[220:223], off offset:1024
	s_nop 0
	s_nop 0
	s_nop 0
	s_nop 0
	s_nop 0
	s_nop 0
	s_nop 0
	s_nop 0
	s_branch .LBB0_1144

.LBB0_1390:
	v_ashrrev_i32_e32 v59, 31, v58
	v_lshlrev_b64 v[32:33], 14, v[58:59]
	v_lshl_add_u64 v[32:33], s[22:23], 0, v[32:33]
	v_lshl_add_u64 v[32:33], v[32:33], 0, v[52:53]
	global_load_dwordx4 v[44:47], v[32:33], off
	global_load_dwordx4 v[40:43], v[32:33], off offset:1024
	v_lshlrev_b64 v[32:33], 15, v[58:59]
	v_lshl_add_u64 v[60:61], v[54:55], 0, v[32:33]
	s_mov_b64 s[14:15], 0xc500800
	v_lshl_add_u64 v[226:227], v[56:57], 0, s[14:15]
	global_load_dwordx4 v[32:35], v[226:227], off
	global_load_dwordx4 v[36:39], v[226:227], off offset:1024
	s_mov_b64 s[14:15], 0xc501000
	v_lshl_add_u64 v[224:225], v[56:57], 0, s[14:15]
	global_load_dwordx4 v[176:179], v[224:225], off
	global_load_dwordx4 v[180:183], v[224:225], off offset:1024
	s_mov_b64 s[14:15], 0xc501800
	v_lshl_add_u64 v[226:227], v[56:57], 0, s[14:15]
	global_load_dwordx4 v[184:187], v[226:227], off
	global_load_dwordx4 v[188:191], v[226:227], off offset:1024
	s_mov_b64 s[14:15], 0xc502000
	v_lshl_add_u64 v[224:225], v[56:57], 0, s[14:15]
	global_load_dwordx4 v[192:195], v[224:225], off
	global_load_dwordx4 v[196:199], v[224:225], off offset:1024
	s_mov_b64 s[14:15], 0xc502800
	v_lshl_add_u64 v[226:227], v[56:57], 0, s[14:15]
	global_load_dwordx4 v[200:203], v[226:227], off
	global_load_dwordx4 v[204:207], v[226:227], off offset:1024
	s_mov_b64 s[14:15], 0xc503000
	v_lshl_add_u64 v[224:225], v[56:57], 0, s[14:15]
	global_load_dwordx4 v[208:211], v[224:225], off
	global_load_dwordx4 v[212:215], v[224:225], off offset:1024
	s_mov_b64 s[14:15], 0xc503800
	v_lshl_add_u64 v[226:227], v[56:57], 0, s[14:15]
	global_load_dwordx4 v[216:219], v[226:227], off
	global_load_dwordx4 v[220:223], v[226:227], off offset:1024
	s_waitcnt vmcnt(14)
	v_lshlrev_b32_e32 v72, 16, v42
	v_and_b32_e32 v59, 0xffff0000, v42
	v_lshlrev_b32_e32 v74, 16, v43
	v_and_b32_e32 v75, 0xffff0000, v43
	v_lshlrev_b32_e32 v43, 16, v45
	v_lshlrev_b32_e32 v42, 16, v44
	v_and_b32_e32 v45, 0xffff0000, v45
	v_and_b32_e32 v44, 0xffff0000, v44
	v_lshlrev_b32_e32 v79, 16, v47
	v_lshlrev_b32_e32 v78, 16, v46
	v_and_b32_e32 v47, 0xffff0000, v47
	v_and_b32_e32 v46, 0xffff0000, v46
	v_lshlrev_b32_e32 v70, 16, v40
	v_and_b32_e32 v71, 0xffff0000, v40
	v_pk_mul_f32 v[76:77], v[44:45], v[44:45]
	v_pk_mul_f32 v[80:81], v[46:47], v[46:47]
	v_lshlrev_b32_e32 v84, 16, v41
	v_pk_fma_f32 v[76:77], v[42:43], v[42:43], v[76:77]
	v_pk_fma_f32 v[80:81], v[78:79], v[78:79], v[80:81]
	v_mul_f32_e32 v73, v70, v70
	v_mul_f32_e32 v83, v71, v71
	v_and_b32_e32 v85, 0xffff0000, v41
	v_mul_f32_e32 v40, v84, v84
	v_mov_b32_e32 v82, v72
	v_pk_add_f32 v[76:77], v[76:77], v[76:77] op_sel_hi:[0,1]
	v_pk_add_f32 v[80:81], v[80:81], v[80:81] op_sel_hi:[0,1]
	v_pk_fma_f32 v[40:41], v[84:85], v[84:85], v[40:41] op_sel_hi:[1,1,0]
	v_pk_add_f32 v[82:83], v[72:73], v[82:83]
	v_mul_f32_e32 v40, v59, v59
	v_mul_f32_e32 v76, v74, v74
	v_mul_f32_e32 v80, v75, v75
	v_mul_f32_e32 v86, v72, v72
	v_mov_b32_e32 v87, v83
	v_pk_add_f32 v[40:41], v[86:87], v[40:41]
	v_pk_add_f32 v[76:77], v[76:77], v[80:81]
	v_pk_add_f32 v[40:41], v[40:41], v[76:77]
	v_add_f32_e32 v40, v40, v41
	ds_bpermute_b32 v41, v62, v40
	s_waitcnt lgkmcnt(0)
	v_add_f32_e32 v40, v40, v41
	ds_bpermute_b32 v41, v63, v40
	s_waitcnt lgkmcnt(0)
	v_add_f32_e32 v40, v40, v41
	ds_bpermute_b32 v41, v64, v40
	s_waitcnt lgkmcnt(0)
	v_add_f32_e32 v40, v40, v41
	ds_bpermute_b32 v41, v65, v40
	s_waitcnt lgkmcnt(0)
	v_add_f32_e32 v40, v40, v41
	ds_bpermute_b32 v41, v66, v40
	s_waitcnt lgkmcnt(0)
	v_add_f32_e32 v40, v40, v41
	ds_bpermute_b32 v41, v67, v40
	s_waitcnt lgkmcnt(0)
	v_add_f32_e32 v40, v40, v41
	v_fmamk_f32 v40, v40, 0x3a800000, v68
	v_mul_f32_e32 v41, 0x4f800000, v40
	v_cmp_gt_f32_e32 vcc, s3, v40
	s_nop 1
	v_cndmask_b32_e32 v40, v40, v41, vcc
	v_sqrt_f32_e32 v41, v40
	s_nop 0
	v_add_u32_e32 v73, -1, v41
	v_fma_f32 v76, -v73, v41, v40
	v_cmp_ge_f32_e64 s[0:1], 0, v76
	v_add_u32_e32 v76, 1, v41
	s_nop 0
	v_cndmask_b32_e64 v73, v41, v73, s[0:1]
	v_fma_f32 v41, -v76, v41, v40
	v_cmp_lt_f32_e64 s[0:1], 0, v41
	s_nop 1
	v_cndmask_b32_e64 v41, v73, v76, s[0:1]
	v_mul_f32_e32 v73, 0x37800000, v41
	v_cndmask_b32_e32 v41, v41, v73, vcc
	v_cmp_class_f32_e32 vcc, v40, v69
	s_nop 1
	v_cndmask_b32_e32 v40, v41, v40, vcc
	v_div_scale_f32 v41, s[0:1], v40, v40, 1.0
	v_rcp_f32_e32 v73, v41
	s_nop 0
	v_fma_f32 v76, -v41, v73, 1.0
	v_fmac_f32_e32 v73, v76, v73
	v_div_scale_f32 v76, vcc, 1.0, v40, 1.0
	v_mul_f32_e32 v77, v76, v73
	v_fma_f32 v80, -v41, v77, v76
	v_fmac_f32_e32 v77, v80, v73
	v_fma_f32 v41, -v41, v77, v76
	v_div_fmas_f32 v41, v41, v73, v77
	v_div_fixup_f32 v76, v41, v40, 1.0
	v_mov_b32_e32 v40, v42
	v_mov_b32_e32 v41, v44
	v_mov_b32_e32 v44, v43
	v_pk_mul_f32 v[40:41], v[76:77], v[40:41] op_sel_hi:[0,1]
	v_pk_mul_f32 v[42:43], v[76:77], v[44:45] op_sel_hi:[0,1]
	s_mov_b64 s[14:15], 0x0
	v_lshl_add_u64 v[80:81], s[14:15], 2, v[60:61]
	v_pk_mul_f32 v[42:43], v[22:23], v[42:43]
	v_pk_mul_f32 v[40:41], v[20:21], v[40:41]
	global_store_dwordx4 v[80:81], v[40:43], off
	v_mov_b32_e32 v73, v59
	s_nop 0
	v_mov_b32_e32 v40, v78
	v_mov_b32_e32 v41, v46
	v_mov_b32_e32 v46, v79
	v_pk_mul_f32 v[40:41], v[76:77], v[40:41] op_sel_hi:[0,1]
	v_pk_mul_f32 v[42:43], v[76:77], v[46:47] op_sel_hi:[0,1]
	v_pk_mul_f32 v[42:43], v[18:19], v[42:43]
	v_pk_mul_f32 v[40:41], v[16:17], v[40:41]
	global_store_dwordx4 v[80:81], v[40:43], off offset:16
	s_nop 0
	s_nop 0
	v_pk_mul_f32 v[40:41], v[70:71], v[76:77] op_sel_hi:[1,0]
	v_pk_mul_f32 v[42:43], v[84:85], v[76:77] op_sel_hi:[1,0]
	v_pk_mul_f32 v[40:41], v[28:29], v[40:41]
	v_pk_mul_f32 v[42:43], v[30:31], v[42:43]
	global_store_dwordx4 v[80:81], v[40:43], off offset:2048
	s_nop 0
	s_nop 0
	v_pk_mul_f32 v[40:41], v[72:73], v[76:77] op_sel_hi:[1,0]
	v_pk_mul_f32 v[42:43], v[74:75], v[76:77] op_sel_hi:[1,0]
	v_pk_mul_f32 v[40:41], v[24:25], v[40:41]
	v_pk_mul_f32 v[42:43], v[26:27], v[42:43]
	global_store_dwordx4 v[80:81], v[40:43], off offset:2064
	s_nop 1
	s_nop 0
	s_nop 0
	s_nop 0
	s_nop 0
	s_waitcnt vmcnt(16)
	v_lshlrev_b32_e32 v72, 16, v38
	v_and_b32_e32 v59, 0xffff0000, v38
	v_lshlrev_b32_e32 v74, 16, v39
	v_and_b32_e32 v75, 0xffff0000, v39
	v_lshlrev_b32_e32 v39, 16, v33
	v_lshlrev_b32_e32 v38, 16, v32
	v_and_b32_e32 v33, 0xffff0000, v33
	v_and_b32_e32 v32, 0xffff0000, v32
	v_lshlrev_b32_e32 v79, 16, v35
	v_lshlrev_b32_e32 v78, 16, v34
	v_and_b32_e32 v35, 0xffff0000, v35
	v_and_b32_e32 v34, 0xffff0000, v34
	v_lshlrev_b32_e32 v70, 16, v36
	v_and_b32_e32 v71, 0xffff0000, v36
	v_pk_mul_f32 v[76:77], v[32:33], v[32:33]
	v_pk_mul_f32 v[80:81], v[34:35], v[34:35]
	v_lshlrev_b32_e32 v84, 16, v37
	v_pk_fma_f32 v[76:77], v[38:39], v[38:39], v[76:77]
	v_pk_fma_f32 v[80:81], v[78:79], v[78:79], v[80:81]
	v_mul_f32_e32 v73, v70, v70
	v_mul_f32_e32 v83, v71, v71
	v_and_b32_e32 v85, 0xffff0000, v37
	v_mul_f32_e32 v36, v84, v84
	v_mov_b32_e32 v82, v72
	v_pk_add_f32 v[76:77], v[76:77], v[76:77] op_sel_hi:[0,1]
	v_pk_add_f32 v[80:81], v[80:81], v[80:81] op_sel_hi:[0,1]
	v_pk_fma_f32 v[36:37], v[84:85], v[84:85], v[36:37] op_sel_hi:[1,1,0]
	v_pk_add_f32 v[82:83], v[72:73], v[82:83]
	v_mul_f32_e32 v36, v59, v59
	v_mul_f32_e32 v76, v74, v74
	v_mul_f32_e32 v80, v75, v75
	v_mul_f32_e32 v86, v72, v72
	v_mov_b32_e32 v87, v83
	v_pk_add_f32 v[36:37], v[86:87], v[36:37]
	v_pk_add_f32 v[76:77], v[76:77], v[80:81]
	v_pk_add_f32 v[36:37], v[36:37], v[76:77]
	v_add_f32_e32 v36, v36, v37
	ds_bpermute_b32 v37, v62, v36
	s_waitcnt lgkmcnt(0)
	v_add_f32_e32 v36, v36, v37
	ds_bpermute_b32 v37, v63, v36
	s_waitcnt lgkmcnt(0)
	v_add_f32_e32 v36, v36, v37
	ds_bpermute_b32 v37, v64, v36
	s_waitcnt lgkmcnt(0)
	v_add_f32_e32 v36, v36, v37
	ds_bpermute_b32 v37, v65, v36
	s_waitcnt lgkmcnt(0)
	v_add_f32_e32 v36, v36, v37
	ds_bpermute_b32 v37, v66, v36
	s_waitcnt lgkmcnt(0)
	v_add_f32_e32 v36, v36, v37
	ds_bpermute_b32 v37, v67, v36
	s_waitcnt lgkmcnt(0)
	v_add_f32_e32 v36, v36, v37
	v_fmamk_f32 v36, v36, 0x3a800000, v68
	v_mul_f32_e32 v37, 0x4f800000, v36
	v_cmp_gt_f32_e32 vcc, s3, v36
	s_nop 1
	v_cndmask_b32_e32 v36, v36, v37, vcc
	v_sqrt_f32_e32 v37, v36
	s_nop 0
	v_add_u32_e32 v73, -1, v37
	v_fma_f32 v76, -v73, v37, v36
	v_cmp_ge_f32_e64 s[0:1], 0, v76
	v_add_u32_e32 v76, 1, v37
	s_nop 0
	v_cndmask_b32_e64 v73, v37, v73, s[0:1]
	v_fma_f32 v37, -v76, v37, v36
	v_cmp_lt_f32_e64 s[0:1], 0, v37
	s_nop 1
	v_cndmask_b32_e64 v37, v73, v76, s[0:1]
	v_mul_f32_e32 v73, 0x37800000, v37
	v_cndmask_b32_e32 v37, v37, v73, vcc
	v_cmp_class_f32_e32 vcc, v36, v69
	s_nop 1
	v_cndmask_b32_e32 v36, v37, v36, vcc
	v_div_scale_f32 v37, s[0:1], v36, v36, 1.0
	v_rcp_f32_e32 v73, v37
	s_nop 0
	v_fma_f32 v76, -v37, v73, 1.0
	v_fmac_f32_e32 v73, v76, v73
	v_div_scale_f32 v76, vcc, 1.0, v36, 1.0
	v_mul_f32_e32 v77, v76, v73
	v_fma_f32 v80, -v37, v77, v76
	v_fmac_f32_e32 v77, v80, v73
	v_fma_f32 v37, -v37, v77, v76
	v_div_fmas_f32 v37, v37, v73, v77
	v_div_fixup_f32 v76, v37, v36, 1.0
	v_mov_b32_e32 v36, v38
	v_mov_b32_e32 v37, v32
	v_mov_b32_e32 v32, v39
	v_pk_mul_f32 v[36:37], v[76:77], v[36:37] op_sel_hi:[0,1]
	v_pk_mul_f32 v[38:39], v[76:77], v[32:33] op_sel_hi:[0,1]
	s_mov_b64 s[14:15], 0x400
	v_lshl_add_u64 v[80:81], s[14:15], 2, v[60:61]
	v_pk_mul_f32 v[38:39], v[22:23], v[38:39]
	v_pk_mul_f32 v[36:37], v[20:21], v[36:37]
	global_store_dwordx4 v[80:81], v[36:39], off
	v_mov_b32_e32 v73, v59
	s_nop 0
	v_mov_b32_e32 v36, v78
	v_mov_b32_e32 v37, v34
	v_mov_b32_e32 v34, v79
	v_pk_mul_f32 v[36:37], v[76:77], v[36:37] op_sel_hi:[0,1]
	v_pk_mul_f32 v[38:39], v[76:77], v[34:35] op_sel_hi:[0,1]
	v_pk_mul_f32 v[38:39], v[18:19], v[38:39]
	v_pk_mul_f32 v[36:37], v[16:17], v[36:37]
	global_store_dwordx4 v[80:81], v[36:39], off offset:16
	s_nop 0
	s_nop 0
	v_pk_mul_f32 v[36:37], v[70:71], v[76:77] op_sel_hi:[1,0]
	v_pk_mul_f32 v[38:39], v[84:85], v[76:77] op_sel_hi:[1,0]
	v_pk_mul_f32 v[36:37], v[28:29], v[36:37]
	v_pk_mul_f32 v[38:39], v[30:31], v[38:39]
	global_store_dwordx4 v[80:81], v[36:39], off offset:2048
	s_nop 0
	s_nop 0
	v_pk_mul_f32 v[36:37], v[72:73], v[76:77] op_sel_hi:[1,0]
	v_pk_mul_f32 v[38:39], v[74:75], v[76:77] op_sel_hi:[1,0]
	v_pk_mul_f32 v[36:37], v[24:25], v[36:37]
	v_pk_mul_f32 v[38:39], v[26:27], v[38:39]
	global_store_dwordx4 v[80:81], v[36:39], off offset:2064
	s_nop 1
	s_nop 0
	s_nop 0
	s_nop 0
	s_nop 0
	s_waitcnt vmcnt(18)
	v_lshlrev_b32_e32 v72, 16, v182
	v_and_b32_e32 v59, 0xffff0000, v182
	v_lshlrev_b32_e32 v74, 16, v183
	v_and_b32_e32 v75, 0xffff0000, v183
	v_lshlrev_b32_e32 v183, 16, v177
	v_lshlrev_b32_e32 v182, 16, v176
	v_and_b32_e32 v177, 0xffff0000, v177
	v_and_b32_e32 v176, 0xffff0000, v176
	v_lshlrev_b32_e32 v79, 16, v179
	v_lshlrev_b32_e32 v78, 16, v178
	v_and_b32_e32 v179, 0xffff0000, v179
	v_and_b32_e32 v178, 0xffff0000, v178
	v_lshlrev_b32_e32 v70, 16, v180
	v_and_b32_e32 v71, 0xffff0000, v180
	v_pk_mul_f32 v[76:77], v[176:177], v[176:177]
	v_pk_mul_f32 v[80:81], v[178:179], v[178:179]
	v_lshlrev_b32_e32 v84, 16, v181
	v_pk_fma_f32 v[76:77], v[182:183], v[182:183], v[76:77]
	v_pk_fma_f32 v[80:81], v[78:79], v[78:79], v[80:81]
	v_mul_f32_e32 v73, v70, v70
	v_mul_f32_e32 v83, v71, v71
	v_and_b32_e32 v85, 0xffff0000, v181
	v_mul_f32_e32 v180, v84, v84
	v_mov_b32_e32 v82, v72
	v_pk_add_f32 v[76:77], v[76:77], v[76:77] op_sel_hi:[0,1]
	v_pk_add_f32 v[80:81], v[80:81], v[80:81] op_sel_hi:[0,1]
	v_pk_fma_f32 v[180:181], v[84:85], v[84:85], v[180:181] op_sel_hi:[1,1,0]
	v_pk_add_f32 v[82:83], v[72:73], v[82:83]
	v_mul_f32_e32 v180, v59, v59
	v_mul_f32_e32 v76, v74, v74
	v_mul_f32_e32 v80, v75, v75
	v_mul_f32_e32 v86, v72, v72
	v_mov_b32_e32 v87, v83
	v_pk_add_f32 v[180:181], v[86:87], v[180:181]
	v_pk_add_f32 v[76:77], v[76:77], v[80:81]
	v_pk_add_f32 v[180:181], v[180:181], v[76:77]
	v_add_f32_e32 v180, v180, v181
	ds_bpermute_b32 v181, v62, v180
	s_waitcnt lgkmcnt(0)
	v_add_f32_e32 v180, v180, v181
	ds_bpermute_b32 v181, v63, v180
	s_waitcnt lgkmcnt(0)
	v_add_f32_e32 v180, v180, v181
	ds_bpermute_b32 v181, v64, v180
	s_waitcnt lgkmcnt(0)
	v_add_f32_e32 v180, v180, v181
	ds_bpermute_b32 v181, v65, v180
	s_waitcnt lgkmcnt(0)
	v_add_f32_e32 v180, v180, v181
	ds_bpermute_b32 v181, v66, v180
	s_waitcnt lgkmcnt(0)
	v_add_f32_e32 v180, v180, v181
	ds_bpermute_b32 v181, v67, v180
	s_waitcnt lgkmcnt(0)
	v_add_f32_e32 v180, v180, v181
	v_fmamk_f32 v180, v180, 0x3a800000, v68
	v_mul_f32_e32 v181, 0x4f800000, v180
	v_cmp_gt_f32_e32 vcc, s3, v180
	s_nop 1
	v_cndmask_b32_e32 v180, v180, v181, vcc
	v_sqrt_f32_e32 v181, v180
	s_nop 0
	v_add_u32_e32 v73, -1, v181
	v_fma_f32 v76, -v73, v181, v180
	v_cmp_ge_f32_e64 s[0:1], 0, v76
	v_add_u32_e32 v76, 1, v181
	s_nop 0
	v_cndmask_b32_e64 v73, v181, v73, s[0:1]
	v_fma_f32 v181, -v76, v181, v180
	v_cmp_lt_f32_e64 s[0:1], 0, v181
	s_nop 1
	v_cndmask_b32_e64 v181, v73, v76, s[0:1]
	v_mul_f32_e32 v73, 0x37800000, v181
	v_cndmask_b32_e32 v181, v181, v73, vcc
	v_cmp_class_f32_e32 vcc, v180, v69
	s_nop 1
	v_cndmask_b32_e32 v180, v181, v180, vcc
	v_div_scale_f32 v181, s[0:1], v180, v180, 1.0
	v_rcp_f32_e32 v73, v181
	s_nop 0
	v_fma_f32 v76, -v181, v73, 1.0
	v_fmac_f32_e32 v73, v76, v73
	v_div_scale_f32 v76, vcc, 1.0, v180, 1.0
	v_mul_f32_e32 v77, v76, v73
	v_fma_f32 v80, -v181, v77, v76
	v_fmac_f32_e32 v77, v80, v73
	v_fma_f32 v181, -v181, v77, v76
	v_div_fmas_f32 v181, v181, v73, v77
	v_div_fixup_f32 v76, v181, v180, 1.0
	v_mov_b32_e32 v180, v182
	v_mov_b32_e32 v181, v176
	v_mov_b32_e32 v176, v183
	v_pk_mul_f32 v[180:181], v[76:77], v[180:181] op_sel_hi:[0,1]
	v_pk_mul_f32 v[182:183], v[76:77], v[176:177] op_sel_hi:[0,1]
	s_mov_b64 s[14:15], 0x800
	v_lshl_add_u64 v[80:81], s[14:15], 2, v[60:61]
	v_pk_mul_f32 v[182:183], v[22:23], v[182:183]
	v_pk_mul_f32 v[180:181], v[20:21], v[180:181]
	global_store_dwordx4 v[80:81], v[180:183], off
	v_mov_b32_e32 v73, v59
	s_nop 0
	v_mov_b32_e32 v180, v78
	v_mov_b32_e32 v181, v178
	v_mov_b32_e32 v178, v79
	v_pk_mul_f32 v[180:181], v[76:77], v[180:181] op_sel_hi:[0,1]
	v_pk_mul_f32 v[182:183], v[76:77], v[178:179] op_sel_hi:[0,1]
	v_pk_mul_f32 v[182:183], v[18:19], v[182:183]
	v_pk_mul_f32 v[180:181], v[16:17], v[180:181]
	global_store_dwordx4 v[80:81], v[180:183], off offset:16
	s_nop 0
	s_nop 0
	v_pk_mul_f32 v[180:181], v[70:71], v[76:77] op_sel_hi:[1,0]
	v_pk_mul_f32 v[182:183], v[84:85], v[76:77] op_sel_hi:[1,0]
	v_pk_mul_f32 v[180:181], v[28:29], v[180:181]
	v_pk_mul_f32 v[182:183], v[30:31], v[182:183]
	global_store_dwordx4 v[80:81], v[180:183], off offset:2048
	s_nop 0
	s_nop 0
	v_pk_mul_f32 v[180:181], v[72:73], v[76:77] op_sel_hi:[1,0]
	v_pk_mul_f32 v[182:183], v[74:75], v[76:77] op_sel_hi:[1,0]
	v_pk_mul_f32 v[180:181], v[24:25], v[180:181]
	v_pk_mul_f32 v[182:183], v[26:27], v[182:183]
	global_store_dwordx4 v[80:81], v[180:183], off offset:2064
	s_nop 1
	s_nop 0
	s_nop 0
	s_nop 0
	s_nop 0
	s_waitcnt vmcnt(20)
	v_lshlrev_b32_e32 v72, 16, v190
	v_and_b32_e32 v59, 0xffff0000, v190
	v_lshlrev_b32_e32 v74, 16, v191
	v_and_b32_e32 v75, 0xffff0000, v191
	v_lshlrev_b32_e32 v191, 16, v185
	v_lshlrev_b32_e32 v190, 16, v184
	v_and_b32_e32 v185, 0xffff0000, v185
	v_and_b32_e32 v184, 0xffff0000, v184
	v_lshlrev_b32_e32 v79, 16, v187
	v_lshlrev_b32_e32 v78, 16, v186
	v_and_b32_e32 v187, 0xffff0000, v187
	v_and_b32_e32 v186, 0xffff0000, v186
	v_lshlrev_b32_e32 v70, 16, v188
	v_and_b32_e32 v71, 0xffff0000, v188
	v_pk_mul_f32 v[76:77], v[184:185], v[184:185]
	v_pk_mul_f32 v[80:81], v[186:187], v[186:187]
	v_lshlrev_b32_e32 v84, 16, v189
	v_pk_fma_f32 v[76:77], v[190:191], v[190:191], v[76:77]
	v_pk_fma_f32 v[80:81], v[78:79], v[78:79], v[80:81]
	v_mul_f32_e32 v73, v70, v70
	v_mul_f32_e32 v83, v71, v71
	v_and_b32_e32 v85, 0xffff0000, v189
	v_mul_f32_e32 v188, v84, v84
	v_mov_b32_e32 v82, v72
	v_pk_add_f32 v[76:77], v[76:77], v[76:77] op_sel_hi:[0,1]
	v_pk_add_f32 v[80:81], v[80:81], v[80:81] op_sel_hi:[0,1]
	v_pk_fma_f32 v[188:189], v[84:85], v[84:85], v[188:189] op_sel_hi:[1,1,0]
	v_pk_add_f32 v[82:83], v[72:73], v[82:83]
	v_mul_f32_e32 v188, v59, v59
	v_mul_f32_e32 v76, v74, v74
	v_mul_f32_e32 v80, v75, v75
	v_mul_f32_e32 v86, v72, v72
	v_mov_b32_e32 v87, v83
	v_pk_add_f32 v[188:189], v[86:87], v[188:189]
	v_pk_add_f32 v[76:77], v[76:77], v[80:81]
	v_pk_add_f32 v[188:189], v[188:189], v[76:77]
	v_add_f32_e32 v188, v188, v189
	ds_bpermute_b32 v189, v62, v188
	s_waitcnt lgkmcnt(0)
	v_add_f32_e32 v188, v188, v189
	ds_bpermute_b32 v189, v63, v188
	s_waitcnt lgkmcnt(0)
	v_add_f32_e32 v188, v188, v189
	ds_bpermute_b32 v189, v64, v188
	s_waitcnt lgkmcnt(0)
	v_add_f32_e32 v188, v188, v189
	ds_bpermute_b32 v189, v65, v188
	s_waitcnt lgkmcnt(0)
	v_add_f32_e32 v188, v188, v189
	ds_bpermute_b32 v189, v66, v188
	s_waitcnt lgkmcnt(0)
	v_add_f32_e32 v188, v188, v189
	ds_bpermute_b32 v189, v67, v188
	s_waitcnt lgkmcnt(0)
	v_add_f32_e32 v188, v188, v189
	v_fmamk_f32 v188, v188, 0x3a800000, v68
	v_mul_f32_e32 v189, 0x4f800000, v188
	v_cmp_gt_f32_e32 vcc, s3, v188
	s_nop 1
	v_cndmask_b32_e32 v188, v188, v189, vcc
	v_sqrt_f32_e32 v189, v188
	s_nop 0
	v_add_u32_e32 v73, -1, v189
	v_fma_f32 v76, -v73, v189, v188
	v_cmp_ge_f32_e64 s[0:1], 0, v76
	v_add_u32_e32 v76, 1, v189
	s_nop 0
	v_cndmask_b32_e64 v73, v189, v73, s[0:1]
	v_fma_f32 v189, -v76, v189, v188
	v_cmp_lt_f32_e64 s[0:1], 0, v189
	s_nop 1
	v_cndmask_b32_e64 v189, v73, v76, s[0:1]
	v_mul_f32_e32 v73, 0x37800000, v189
	v_cndmask_b32_e32 v189, v189, v73, vcc
	v_cmp_class_f32_e32 vcc, v188, v69
	s_nop 1
	v_cndmask_b32_e32 v188, v189, v188, vcc
	v_div_scale_f32 v189, s[0:1], v188, v188, 1.0
	v_rcp_f32_e32 v73, v189
	s_nop 0
	v_fma_f32 v76, -v189, v73, 1.0
	v_fmac_f32_e32 v73, v76, v73
	v_div_scale_f32 v76, vcc, 1.0, v188, 1.0
	v_mul_f32_e32 v77, v76, v73
	v_fma_f32 v80, -v189, v77, v76
	v_fmac_f32_e32 v77, v80, v73
	v_fma_f32 v189, -v189, v77, v76
	v_div_fmas_f32 v189, v189, v73, v77
	v_div_fixup_f32 v76, v189, v188, 1.0
	v_mov_b32_e32 v188, v190
	v_mov_b32_e32 v189, v184
	v_mov_b32_e32 v184, v191
	v_pk_mul_f32 v[188:189], v[76:77], v[188:189] op_sel_hi:[0,1]
	v_pk_mul_f32 v[190:191], v[76:77], v[184:185] op_sel_hi:[0,1]
	s_mov_b64 s[14:15], 0xc00
	v_lshl_add_u64 v[80:81], s[14:15], 2, v[60:61]
	v_pk_mul_f32 v[190:191], v[22:23], v[190:191]
	v_pk_mul_f32 v[188:189], v[20:21], v[188:189]
	global_store_dwordx4 v[80:81], v[188:191], off
	v_mov_b32_e32 v73, v59
	s_nop 0
	v_mov_b32_e32 v188, v78
	v_mov_b32_e32 v189, v186
	v_mov_b32_e32 v186, v79
	v_pk_mul_f32 v[188:189], v[76:77], v[188:189] op_sel_hi:[0,1]
	v_pk_mul_f32 v[190:191], v[76:77], v[186:187] op_sel_hi:[0,1]
	v_pk_mul_f32 v[190:191], v[18:19], v[190:191]
	v_pk_mul_f32 v[188:189], v[16:17], v[188:189]
	global_store_dwordx4 v[80:81], v[188:191], off offset:16
	s_nop 0
	s_nop 0
	v_pk_mul_f32 v[188:189], v[70:71], v[76:77] op_sel_hi:[1,0]
	v_pk_mul_f32 v[190:191], v[84:85], v[76:77] op_sel_hi:[1,0]
	v_pk_mul_f32 v[188:189], v[28:29], v[188:189]
	v_pk_mul_f32 v[190:191], v[30:31], v[190:191]
	global_store_dwordx4 v[80:81], v[188:191], off offset:2048
	s_nop 0
	s_nop 0
	v_pk_mul_f32 v[188:189], v[72:73], v[76:77] op_sel_hi:[1,0]
	v_pk_mul_f32 v[190:191], v[74:75], v[76:77] op_sel_hi:[1,0]
	v_pk_mul_f32 v[188:189], v[24:25], v[188:189]
	v_pk_mul_f32 v[190:191], v[26:27], v[190:191]
	global_store_dwordx4 v[80:81], v[188:191], off offset:2064
	s_nop 1
	s_nop 0
	s_nop 0
	s_nop 0
	s_nop 0
	s_waitcnt vmcnt(22)
	v_lshlrev_b32_e32 v72, 16, v198
	v_and_b32_e32 v59, 0xffff0000, v198
	v_lshlrev_b32_e32 v74, 16, v199
	v_and_b32_e32 v75, 0xffff0000, v199
	v_lshlrev_b32_e32 v199, 16, v193
	v_lshlrev_b32_e32 v198, 16, v192
	v_and_b32_e32 v193, 0xffff0000, v193
	v_and_b32_e32 v192, 0xffff0000, v192
	v_lshlrev_b32_e32 v79, 16, v195
	v_lshlrev_b32_e32 v78, 16, v194
	v_and_b32_e32 v195, 0xffff0000, v195
	v_and_b32_e32 v194, 0xffff0000, v194
	v_lshlrev_b32_e32 v70, 16, v196
	v_and_b32_e32 v71, 0xffff0000, v196
	v_pk_mul_f32 v[76:77], v[192:193], v[192:193]
	v_pk_mul_f32 v[80:81], v[194:195], v[194:195]
	v_lshlrev_b32_e32 v84, 16, v197
	v_pk_fma_f32 v[76:77], v[198:199], v[198:199], v[76:77]
	v_pk_fma_f32 v[80:81], v[78:79], v[78:79], v[80:81]
	v_mul_f32_e32 v73, v70, v70
	v_mul_f32_e32 v83, v71, v71
	v_and_b32_e32 v85, 0xffff0000, v197
	v_mul_f32_e32 v196, v84, v84
	v_mov_b32_e32 v82, v72
	v_pk_add_f32 v[76:77], v[76:77], v[76:77] op_sel_hi:[0,1]
	v_pk_add_f32 v[80:81], v[80:81], v[80:81] op_sel_hi:[0,1]
	v_pk_fma_f32 v[196:197], v[84:85], v[84:85], v[196:197] op_sel_hi:[1,1,0]
	v_pk_add_f32 v[82:83], v[72:73], v[82:83]
	v_mul_f32_e32 v196, v59, v59
	v_mul_f32_e32 v76, v74, v74
	v_mul_f32_e32 v80, v75, v75
	v_mul_f32_e32 v86, v72, v72
	v_mov_b32_e32 v87, v83
	v_pk_add_f32 v[196:197], v[86:87], v[196:197]
	v_pk_add_f32 v[76:77], v[76:77], v[80:81]
	v_pk_add_f32 v[196:197], v[196:197], v[76:77]
	v_add_f32_e32 v196, v196, v197
	ds_bpermute_b32 v197, v62, v196
	s_waitcnt lgkmcnt(0)
	v_add_f32_e32 v196, v196, v197
	ds_bpermute_b32 v197, v63, v196
	s_waitcnt lgkmcnt(0)
	v_add_f32_e32 v196, v196, v197
	ds_bpermute_b32 v197, v64, v196
	s_waitcnt lgkmcnt(0)
	v_add_f32_e32 v196, v196, v197
	ds_bpermute_b32 v197, v65, v196
	s_waitcnt lgkmcnt(0)
	v_add_f32_e32 v196, v196, v197
	ds_bpermute_b32 v197, v66, v196
	s_waitcnt lgkmcnt(0)
	v_add_f32_e32 v196, v196, v197
	ds_bpermute_b32 v197, v67, v196
	s_waitcnt lgkmcnt(0)
	v_add_f32_e32 v196, v196, v197
	v_fmamk_f32 v196, v196, 0x3a800000, v68
	v_mul_f32_e32 v197, 0x4f800000, v196
	v_cmp_gt_f32_e32 vcc, s3, v196
	s_nop 1
	v_cndmask_b32_e32 v196, v196, v197, vcc
	v_sqrt_f32_e32 v197, v196
	s_nop 0
	v_add_u32_e32 v73, -1, v197
	v_fma_f32 v76, -v73, v197, v196
	v_cmp_ge_f32_e64 s[0:1], 0, v76
	v_add_u32_e32 v76, 1, v197
	s_nop 0
	v_cndmask_b32_e64 v73, v197, v73, s[0:1]
	v_fma_f32 v197, -v76, v197, v196
	v_cmp_lt_f32_e64 s[0:1], 0, v197
	s_nop 1
	v_cndmask_b32_e64 v197, v73, v76, s[0:1]
	v_mul_f32_e32 v73, 0x37800000, v197
	v_cndmask_b32_e32 v197, v197, v73, vcc
	v_cmp_class_f32_e32 vcc, v196, v69
	s_nop 1
	v_cndmask_b32_e32 v196, v197, v196, vcc
	v_div_scale_f32 v197, s[0:1], v196, v196, 1.0
	v_rcp_f32_e32 v73, v197
	s_nop 0
	v_fma_f32 v76, -v197, v73, 1.0
	v_fmac_f32_e32 v73, v76, v73
	v_div_scale_f32 v76, vcc, 1.0, v196, 1.0
	v_mul_f32_e32 v77, v76, v73
	v_fma_f32 v80, -v197, v77, v76
	v_fmac_f32_e32 v77, v80, v73
	v_fma_f32 v197, -v197, v77, v76
	v_div_fmas_f32 v197, v197, v73, v77
	v_div_fixup_f32 v76, v197, v196, 1.0
	v_mov_b32_e32 v196, v198
	v_mov_b32_e32 v197, v192
	v_mov_b32_e32 v192, v199
	v_pk_mul_f32 v[196:197], v[76:77], v[196:197] op_sel_hi:[0,1]
	v_pk_mul_f32 v[198:199], v[76:77], v[192:193] op_sel_hi:[0,1]
	s_mov_b64 s[14:15], 0x1000
	v_lshl_add_u64 v[80:81], s[14:15], 2, v[60:61]
	v_pk_mul_f32 v[198:199], v[22:23], v[198:199]
	v_pk_mul_f32 v[196:197], v[20:21], v[196:197]
	global_store_dwordx4 v[80:81], v[196:199], off
	v_mov_b32_e32 v73, v59
	s_nop 0
	v_mov_b32_e32 v196, v78
	v_mov_b32_e32 v197, v194
	v_mov_b32_e32 v194, v79
	v_pk_mul_f32 v[196:197], v[76:77], v[196:197] op_sel_hi:[0,1]
	v_pk_mul_f32 v[198:199], v[76:77], v[194:195] op_sel_hi:[0,1]
	v_pk_mul_f32 v[198:199], v[18:19], v[198:199]
	v_pk_mul_f32 v[196:197], v[16:17], v[196:197]
	global_store_dwordx4 v[80:81], v[196:199], off offset:16
	s_nop 0
	s_nop 0
	v_pk_mul_f32 v[196:197], v[70:71], v[76:77] op_sel_hi:[1,0]
	v_pk_mul_f32 v[198:199], v[84:85], v[76:77] op_sel_hi:[1,0]
	v_pk_mul_f32 v[196:197], v[28:29], v[196:197]
	v_pk_mul_f32 v[198:199], v[30:31], v[198:199]
	global_store_dwordx4 v[80:81], v[196:199], off offset:2048
	s_nop 0
	s_nop 0
	v_pk_mul_f32 v[196:197], v[72:73], v[76:77] op_sel_hi:[1,0]
	v_pk_mul_f32 v[198:199], v[74:75], v[76:77] op_sel_hi:[1,0]
	v_pk_mul_f32 v[196:197], v[24:25], v[196:197]
	v_pk_mul_f32 v[198:199], v[26:27], v[198:199]
	global_store_dwordx4 v[80:81], v[196:199], off offset:2064
	s_nop 1
	s_nop 0
	s_nop 0
	s_nop 0
	s_nop 0
	s_waitcnt vmcnt(24)
	v_lshlrev_b32_e32 v72, 16, v206
	v_and_b32_e32 v59, 0xffff0000, v206
	v_lshlrev_b32_e32 v74, 16, v207
	v_and_b32_e32 v75, 0xffff0000, v207
	v_lshlrev_b32_e32 v207, 16, v201
	v_lshlrev_b32_e32 v206, 16, v200
	v_and_b32_e32 v201, 0xffff0000, v201
	v_and_b32_e32 v200, 0xffff0000, v200
	v_lshlrev_b32_e32 v79, 16, v203
	v_lshlrev_b32_e32 v78, 16, v202
	v_and_b32_e32 v203, 0xffff0000, v203
	v_and_b32_e32 v202, 0xffff0000, v202
	v_lshlrev_b32_e32 v70, 16, v204
	v_and_b32_e32 v71, 0xffff0000, v204
	v_pk_mul_f32 v[76:77], v[200:201], v[200:201]
	v_pk_mul_f32 v[80:81], v[202:203], v[202:203]
	v_lshlrev_b32_e32 v84, 16, v205
	v_pk_fma_f32 v[76:77], v[206:207], v[206:207], v[76:77]
	v_pk_fma_f32 v[80:81], v[78:79], v[78:79], v[80:81]
	v_mul_f32_e32 v73, v70, v70
	v_mul_f32_e32 v83, v71, v71
	v_and_b32_e32 v85, 0xffff0000, v205
	v_mul_f32_e32 v204, v84, v84
	v_mov_b32_e32 v82, v72
	v_pk_add_f32 v[76:77], v[76:77], v[76:77] op_sel_hi:[0,1]
	v_pk_add_f32 v[80:81], v[80:81], v[80:81] op_sel_hi:[0,1]
	v_pk_fma_f32 v[204:205], v[84:85], v[84:85], v[204:205] op_sel_hi:[1,1,0]
	v_pk_add_f32 v[82:83], v[72:73], v[82:83]
	v_mul_f32_e32 v204, v59, v59
	v_mul_f32_e32 v76, v74, v74
	v_mul_f32_e32 v80, v75, v75
	v_mul_f32_e32 v86, v72, v72
	v_mov_b32_e32 v87, v83
	v_pk_add_f32 v[204:205], v[86:87], v[204:205]
	v_pk_add_f32 v[76:77], v[76:77], v[80:81]
	v_pk_add_f32 v[204:205], v[204:205], v[76:77]
	v_add_f32_e32 v204, v204, v205
	ds_bpermute_b32 v205, v62, v204
	s_waitcnt lgkmcnt(0)
	v_add_f32_e32 v204, v204, v205
	ds_bpermute_b32 v205, v63, v204
	s_waitcnt lgkmcnt(0)
	v_add_f32_e32 v204, v204, v205
	ds_bpermute_b32 v205, v64, v204
	s_waitcnt lgkmcnt(0)
	v_add_f32_e32 v204, v204, v205
	ds_bpermute_b32 v205, v65, v204
	s_waitcnt lgkmcnt(0)
	v_add_f32_e32 v204, v204, v205
	ds_bpermute_b32 v205, v66, v204
	s_waitcnt lgkmcnt(0)
	v_add_f32_e32 v204, v204, v205
	ds_bpermute_b32 v205, v67, v204
	s_waitcnt lgkmcnt(0)
	v_add_f32_e32 v204, v204, v205
	v_fmamk_f32 v204, v204, 0x3a800000, v68
	v_mul_f32_e32 v205, 0x4f800000, v204
	v_cmp_gt_f32_e32 vcc, s3, v204
	s_nop 1
	v_cndmask_b32_e32 v204, v204, v205, vcc
	v_sqrt_f32_e32 v205, v204
	s_nop 0
	v_add_u32_e32 v73, -1, v205
	v_fma_f32 v76, -v73, v205, v204
	v_cmp_ge_f32_e64 s[0:1], 0, v76
	v_add_u32_e32 v76, 1, v205
	s_nop 0
	v_cndmask_b32_e64 v73, v205, v73, s[0:1]
	v_fma_f32 v205, -v76, v205, v204
	v_cmp_lt_f32_e64 s[0:1], 0, v205
	s_nop 1
	v_cndmask_b32_e64 v205, v73, v76, s[0:1]
	v_mul_f32_e32 v73, 0x37800000, v205
	v_cndmask_b32_e32 v205, v205, v73, vcc
	v_cmp_class_f32_e32 vcc, v204, v69
	s_nop 1
	v_cndmask_b32_e32 v204, v205, v204, vcc
	v_div_scale_f32 v205, s[0:1], v204, v204, 1.0
	v_rcp_f32_e32 v73, v205
	s_nop 0
	v_fma_f32 v76, -v205, v73, 1.0
	v_fmac_f32_e32 v73, v76, v73
	v_div_scale_f32 v76, vcc, 1.0, v204, 1.0
	v_mul_f32_e32 v77, v76, v73
	v_fma_f32 v80, -v205, v77, v76
	v_fmac_f32_e32 v77, v80, v73
	v_fma_f32 v205, -v205, v77, v76
	v_div_fmas_f32 v205, v205, v73, v77
	v_div_fixup_f32 v76, v205, v204, 1.0
	v_mov_b32_e32 v204, v206
	v_mov_b32_e32 v205, v200
	v_mov_b32_e32 v200, v207
	v_pk_mul_f32 v[204:205], v[76:77], v[204:205] op_sel_hi:[0,1]
	v_pk_mul_f32 v[206:207], v[76:77], v[200:201] op_sel_hi:[0,1]
	s_mov_b64 s[14:15], 0x1400
	v_lshl_add_u64 v[80:81], s[14:15], 2, v[60:61]
	v_pk_mul_f32 v[206:207], v[22:23], v[206:207]
	v_pk_mul_f32 v[204:205], v[20:21], v[204:205]
	global_store_dwordx4 v[80:81], v[204:207], off
	v_mov_b32_e32 v73, v59
	s_nop 0
	v_mov_b32_e32 v204, v78
	v_mov_b32_e32 v205, v202
	v_mov_b32_e32 v202, v79
	v_pk_mul_f32 v[204:205], v[76:77], v[204:205] op_sel_hi:[0,1]
	v_pk_mul_f32 v[206:207], v[76:77], v[202:203] op_sel_hi:[0,1]
	v_pk_mul_f32 v[206:207], v[18:19], v[206:207]
	v_pk_mul_f32 v[204:205], v[16:17], v[204:205]
	global_store_dwordx4 v[80:81], v[204:207], off offset:16
	s_nop 0
	s_nop 0
	v_pk_mul_f32 v[204:205], v[70:71], v[76:77] op_sel_hi:[1,0]
	v_pk_mul_f32 v[206:207], v[84:85], v[76:77] op_sel_hi:[1,0]
	v_pk_mul_f32 v[204:205], v[28:29], v[204:205]
	v_pk_mul_f32 v[206:207], v[30:31], v[206:207]
	global_store_dwordx4 v[80:81], v[204:207], off offset:2048
	s_nop 0
	s_nop 0
	v_pk_mul_f32 v[204:205], v[72:73], v[76:77] op_sel_hi:[1,0]
	v_pk_mul_f32 v[206:207], v[74:75], v[76:77] op_sel_hi:[1,0]
	v_pk_mul_f32 v[204:205], v[24:25], v[204:205]
	v_pk_mul_f32 v[206:207], v[26:27], v[206:207]
	global_store_dwordx4 v[80:81], v[204:207], off offset:2064
	s_nop 1
	s_nop 0
	s_nop 0
	s_nop 0
	s_nop 0
	s_waitcnt vmcnt(26)
	v_lshlrev_b32_e32 v72, 16, v214
	v_and_b32_e32 v59, 0xffff0000, v214
	v_lshlrev_b32_e32 v74, 16, v215
	v_and_b32_e32 v75, 0xffff0000, v215
	v_lshlrev_b32_e32 v215, 16, v209
	v_lshlrev_b32_e32 v214, 16, v208
	v_and_b32_e32 v209, 0xffff0000, v209
	v_and_b32_e32 v208, 0xffff0000, v208
	v_lshlrev_b32_e32 v79, 16, v211
	v_lshlrev_b32_e32 v78, 16, v210
	v_and_b32_e32 v211, 0xffff0000, v211
	v_and_b32_e32 v210, 0xffff0000, v210
	v_lshlrev_b32_e32 v70, 16, v212
	v_and_b32_e32 v71, 0xffff0000, v212
	v_pk_mul_f32 v[76:77], v[208:209], v[208:209]
	v_pk_mul_f32 v[80:81], v[210:211], v[210:211]
	v_lshlrev_b32_e32 v84, 16, v213
	v_pk_fma_f32 v[76:77], v[214:215], v[214:215], v[76:77]
	v_pk_fma_f32 v[80:81], v[78:79], v[78:79], v[80:81]
	v_mul_f32_e32 v73, v70, v70
	v_mul_f32_e32 v83, v71, v71
	v_and_b32_e32 v85, 0xffff0000, v213
	v_mul_f32_e32 v212, v84, v84
	v_mov_b32_e32 v82, v72
	v_pk_add_f32 v[76:77], v[76:77], v[76:77] op_sel_hi:[0,1]
	v_pk_add_f32 v[80:81], v[80:81], v[80:81] op_sel_hi:[0,1]
	v_pk_fma_f32 v[212:213], v[84:85], v[84:85], v[212:213] op_sel_hi:[1,1,0]
	v_pk_add_f32 v[82:83], v[72:73], v[82:83]
	v_mul_f32_e32 v212, v59, v59
	v_mul_f32_e32 v76, v74, v74
	v_mul_f32_e32 v80, v75, v75
	v_mul_f32_e32 v86, v72, v72
	v_mov_b32_e32 v87, v83
	v_pk_add_f32 v[212:213], v[86:87], v[212:213]
	v_pk_add_f32 v[76:77], v[76:77], v[80:81]
	v_pk_add_f32 v[212:213], v[212:213], v[76:77]
	v_add_f32_e32 v212, v212, v213
	ds_bpermute_b32 v213, v62, v212
	s_waitcnt lgkmcnt(0)
	v_add_f32_e32 v212, v212, v213
	ds_bpermute_b32 v213, v63, v212
	s_waitcnt lgkmcnt(0)
	v_add_f32_e32 v212, v212, v213
	ds_bpermute_b32 v213, v64, v212
	s_waitcnt lgkmcnt(0)
	v_add_f32_e32 v212, v212, v213
	ds_bpermute_b32 v213, v65, v212
	s_waitcnt lgkmcnt(0)
	v_add_f32_e32 v212, v212, v213
	ds_bpermute_b32 v213, v66, v212
	s_waitcnt lgkmcnt(0)
	v_add_f32_e32 v212, v212, v213
	ds_bpermute_b32 v213, v67, v212
	s_waitcnt lgkmcnt(0)
	v_add_f32_e32 v212, v212, v213
	v_fmamk_f32 v212, v212, 0x3a800000, v68
	v_mul_f32_e32 v213, 0x4f800000, v212
	v_cmp_gt_f32_e32 vcc, s3, v212
	s_nop 1
	v_cndmask_b32_e32 v212, v212, v213, vcc
	v_sqrt_f32_e32 v213, v212
	s_nop 0
	v_add_u32_e32 v73, -1, v213
	v_fma_f32 v76, -v73, v213, v212
	v_cmp_ge_f32_e64 s[0:1], 0, v76
	v_add_u32_e32 v76, 1, v213
	s_nop 0
	v_cndmask_b32_e64 v73, v213, v73, s[0:1]
	v_fma_f32 v213, -v76, v213, v212
	v_cmp_lt_f32_e64 s[0:1], 0, v213
	s_nop 1
	v_cndmask_b32_e64 v213, v73, v76, s[0:1]
	v_mul_f32_e32 v73, 0x37800000, v213
	v_cndmask_b32_e32 v213, v213, v73, vcc
	v_cmp_class_f32_e32 vcc, v212, v69
	s_nop 1
	v_cndmask_b32_e32 v212, v213, v212, vcc
	v_div_scale_f32 v213, s[0:1], v212, v212, 1.0
	v_rcp_f32_e32 v73, v213
	s_nop 0
	v_fma_f32 v76, -v213, v73, 1.0
	v_fmac_f32_e32 v73, v76, v73
	v_div_scale_f32 v76, vcc, 1.0, v212, 1.0
	v_mul_f32_e32 v77, v76, v73
	v_fma_f32 v80, -v213, v77, v76
	v_fmac_f32_e32 v77, v80, v73
	v_fma_f32 v213, -v213, v77, v76
	v_div_fmas_f32 v213, v213, v73, v77
	v_div_fixup_f32 v76, v213, v212, 1.0
	v_mov_b32_e32 v212, v214
	v_mov_b32_e32 v213, v208
	v_mov_b32_e32 v208, v215
	v_pk_mul_f32 v[212:213], v[76:77], v[212:213] op_sel_hi:[0,1]
	v_pk_mul_f32 v[214:215], v[76:77], v[208:209] op_sel_hi:[0,1]
	s_mov_b64 s[14:15], 0x1800
	v_lshl_add_u64 v[80:81], s[14:15], 2, v[60:61]
	v_pk_mul_f32 v[214:215], v[22:23], v[214:215]
	v_pk_mul_f32 v[212:213], v[20:21], v[212:213]
	global_store_dwordx4 v[80:81], v[212:215], off
	v_mov_b32_e32 v73, v59
	s_nop 0
	v_mov_b32_e32 v212, v78
	v_mov_b32_e32 v213, v210
	v_mov_b32_e32 v210, v79
	v_pk_mul_f32 v[212:213], v[76:77], v[212:213] op_sel_hi:[0,1]
	v_pk_mul_f32 v[214:215], v[76:77], v[210:211] op_sel_hi:[0,1]
	v_pk_mul_f32 v[214:215], v[18:19], v[214:215]
	v_pk_mul_f32 v[212:213], v[16:17], v[212:213]
	global_store_dwordx4 v[80:81], v[212:215], off offset:16
	s_nop 0
	s_nop 0
	v_pk_mul_f32 v[212:213], v[70:71], v[76:77] op_sel_hi:[1,0]
	v_pk_mul_f32 v[214:215], v[84:85], v[76:77] op_sel_hi:[1,0]
	v_pk_mul_f32 v[212:213], v[28:29], v[212:213]
	v_pk_mul_f32 v[214:215], v[30:31], v[214:215]
	global_store_dwordx4 v[80:81], v[212:215], off offset:2048
	s_nop 0
	s_nop 0
	v_pk_mul_f32 v[212:213], v[72:73], v[76:77] op_sel_hi:[1,0]
	v_pk_mul_f32 v[214:215], v[74:75], v[76:77] op_sel_hi:[1,0]
	v_pk_mul_f32 v[212:213], v[24:25], v[212:213]
	v_pk_mul_f32 v[214:215], v[26:27], v[214:215]
	global_store_dwordx4 v[80:81], v[212:215], off offset:2064
	s_nop 1
	s_nop 0
	s_nop 0
	s_nop 0
	s_nop 0
	s_waitcnt vmcnt(28)
	v_lshlrev_b32_e32 v72, 16, v222
	v_and_b32_e32 v59, 0xffff0000, v222
	v_lshlrev_b32_e32 v74, 16, v223
	v_and_b32_e32 v75, 0xffff0000, v223
	v_lshlrev_b32_e32 v223, 16, v217
	v_lshlrev_b32_e32 v222, 16, v216
	v_and_b32_e32 v217, 0xffff0000, v217
	v_and_b32_e32 v216, 0xffff0000, v216
	v_lshlrev_b32_e32 v79, 16, v219
	v_lshlrev_b32_e32 v78, 16, v218
	v_and_b32_e32 v219, 0xffff0000, v219
	v_and_b32_e32 v218, 0xffff0000, v218
	v_lshlrev_b32_e32 v70, 16, v220
	v_and_b32_e32 v71, 0xffff0000, v220
	v_pk_mul_f32 v[76:77], v[216:217], v[216:217]
	v_pk_mul_f32 v[80:81], v[218:219], v[218:219]
	v_lshlrev_b32_e32 v84, 16, v221
	v_pk_fma_f32 v[76:77], v[222:223], v[222:223], v[76:77]
	v_pk_fma_f32 v[80:81], v[78:79], v[78:79], v[80:81]
	v_mul_f32_e32 v73, v70, v70
	v_mul_f32_e32 v83, v71, v71
	v_and_b32_e32 v85, 0xffff0000, v221
	v_mul_f32_e32 v220, v84, v84
	v_mov_b32_e32 v82, v72
	v_pk_add_f32 v[76:77], v[76:77], v[76:77] op_sel_hi:[0,1]
	v_pk_add_f32 v[80:81], v[80:81], v[80:81] op_sel_hi:[0,1]
	v_pk_fma_f32 v[220:221], v[84:85], v[84:85], v[220:221] op_sel_hi:[1,1,0]
	v_pk_add_f32 v[82:83], v[72:73], v[82:83]
	v_mul_f32_e32 v220, v59, v59
	v_mul_f32_e32 v76, v74, v74
	v_mul_f32_e32 v80, v75, v75
	v_mul_f32_e32 v86, v72, v72
	v_mov_b32_e32 v87, v83
	v_pk_add_f32 v[220:221], v[86:87], v[220:221]
	v_pk_add_f32 v[76:77], v[76:77], v[80:81]
	v_pk_add_f32 v[220:221], v[220:221], v[76:77]
	v_add_f32_e32 v220, v220, v221
	ds_bpermute_b32 v221, v62, v220
	s_waitcnt lgkmcnt(0)
	v_add_f32_e32 v220, v220, v221
	ds_bpermute_b32 v221, v63, v220
	s_waitcnt lgkmcnt(0)
	v_add_f32_e32 v220, v220, v221
	ds_bpermute_b32 v221, v64, v220
	s_waitcnt lgkmcnt(0)
	v_add_f32_e32 v220, v220, v221
	ds_bpermute_b32 v221, v65, v220
	s_waitcnt lgkmcnt(0)
	v_add_f32_e32 v220, v220, v221
	ds_bpermute_b32 v221, v66, v220
	s_waitcnt lgkmcnt(0)
	v_add_f32_e32 v220, v220, v221
	ds_bpermute_b32 v221, v67, v220
	s_waitcnt lgkmcnt(0)
	v_add_f32_e32 v220, v220, v221
	v_fmamk_f32 v220, v220, 0x3a800000, v68
	v_mul_f32_e32 v221, 0x4f800000, v220
	v_cmp_gt_f32_e32 vcc, s3, v220
	s_nop 1
	v_cndmask_b32_e32 v220, v220, v221, vcc
	v_sqrt_f32_e32 v221, v220
	s_nop 0
	v_add_u32_e32 v73, -1, v221
	v_fma_f32 v76, -v73, v221, v220
	v_cmp_ge_f32_e64 s[0:1], 0, v76
	v_add_u32_e32 v76, 1, v221
	s_nop 0
	v_cndmask_b32_e64 v73, v221, v73, s[0:1]
	v_fma_f32 v221, -v76, v221, v220
	v_cmp_lt_f32_e64 s[0:1], 0, v221
	s_nop 1
	v_cndmask_b32_e64 v221, v73, v76, s[0:1]
	v_mul_f32_e32 v73, 0x37800000, v221
	v_cndmask_b32_e32 v221, v221, v73, vcc
	v_cmp_class_f32_e32 vcc, v220, v69
	s_nop 1
	v_cndmask_b32_e32 v220, v221, v220, vcc
	v_div_scale_f32 v221, s[0:1], v220, v220, 1.0
	v_rcp_f32_e32 v73, v221
	s_nop 0
	v_fma_f32 v76, -v221, v73, 1.0
	v_fmac_f32_e32 v73, v76, v73
	v_div_scale_f32 v76, vcc, 1.0, v220, 1.0
	v_mul_f32_e32 v77, v76, v73
	v_fma_f32 v80, -v221, v77, v76
	v_fmac_f32_e32 v77, v80, v73
	v_fma_f32 v221, -v221, v77, v76
	v_div_fmas_f32 v221, v221, v73, v77
	v_div_fixup_f32 v76, v221, v220, 1.0
	v_mov_b32_e32 v220, v222
	v_mov_b32_e32 v221, v216
	v_mov_b32_e32 v216, v223
	v_pk_mul_f32 v[220:221], v[76:77], v[220:221] op_sel_hi:[0,1]
	v_pk_mul_f32 v[222:223], v[76:77], v[216:217] op_sel_hi:[0,1]
	s_mov_b64 s[14:15], 0x1c00
	v_lshl_add_u64 v[80:81], s[14:15], 2, v[60:61]
	v_pk_mul_f32 v[222:223], v[22:23], v[222:223]
	v_pk_mul_f32 v[220:221], v[20:21], v[220:221]
	global_store_dwordx4 v[80:81], v[220:223], off
	v_mov_b32_e32 v73, v59
	s_nop 0
	v_mov_b32_e32 v220, v78
	v_mov_b32_e32 v221, v218
	v_mov_b32_e32 v218, v79
	v_pk_mul_f32 v[220:221], v[76:77], v[220:221] op_sel_hi:[0,1]
	v_pk_mul_f32 v[222:223], v[76:77], v[218:219] op_sel_hi:[0,1]
	v_pk_mul_f32 v[222:223], v[18:19], v[222:223]
	v_pk_mul_f32 v[220:221], v[16:17], v[220:221]
	global_store_dwordx4 v[80:81], v[220:223], off offset:16
	s_nop 0
	s_nop 0
	v_pk_mul_f32 v[220:221], v[70:71], v[76:77] op_sel_hi:[1,0]
	v_pk_mul_f32 v[222:223], v[84:85], v[76:77] op_sel_hi:[1,0]
	v_pk_mul_f32 v[220:221], v[28:29], v[220:221]
	v_pk_mul_f32 v[222:223], v[30:31], v[222:223]
	global_store_dwordx4 v[80:81], v[220:223], off offset:2048
	s_nop 0
	s_nop 0
	v_pk_mul_f32 v[220:221], v[72:73], v[76:77] op_sel_hi:[1,0]
	v_pk_mul_f32 v[222:223], v[74:75], v[76:77] op_sel_hi:[1,0]
	v_pk_mul_f32 v[220:221], v[24:25], v[220:221]
	v_pk_mul_f32 v[222:223], v[26:27], v[222:223]
	global_store_dwordx4 v[80:81], v[220:223], off offset:2064
	s_nop 1
	s_nop 0
	s_nop 0
	s_nop 0
	s_nop 0
	s_branch .LBB0_1389
